# GEMM compute segments: snake order so adjacent MFMAs share the accumulator or one operand register
# speedup vs baseline: 1.0774x; 1.0019x over previous
; #define PG8_STAGE(bufoff, gbase, voff) do { _Pragma("unroll") for (int _i = 0; _i < 2; ++_i) \
;         __builtin_amdgcn_global_load_lds((const unsigned*)((const char*)(gbase) + (voff)[_i]), (LAS unsigned*)(lds + (bufoff) + ldsw + _i * 8192), 16, 0, 0); } while (0)
; #define PG8_LDA(dst, b, h) do { _Pragma("unroll") for (int m = 0; m < 4; ++m) _Pragma("unroll") for (int k = 0; k < 2; ++k) dst[m][k] = *(const LAS bf16x8*)(lds + PG8_SA(b, h) + aoff + m * 2048 + k * 1024); } while (0)
; #define PG8_LDB(dst, b, h) do { _Pragma("unroll") for (int n = 0; n < 2; ++n) _Pragma("unroll") for (int k = 0; k < 2; ++k) dst[n][k] = *(const LAS bf16x8*)(lds + PG8_SB(b, h) + boff + n * 2048 + k * 1024); } while (0)
; #define PG8_MMA(ai, bj, At, Bt) do { __builtin_amdgcn_s_setprio(1); _Pragma("unroll") for (int m = 0; m < 4; ++m) _Pragma("unroll") for (int n = 0; n < 2; ++n) _Pragma("unroll") for (int k = 0; k < 2; ++k) \
;         acc[ai][bj][m][n] = __builtin_amdgcn_mfma_f32_16x16x32_bf16(Bt[n][k], At[m][k], acc[ai][bj][m][n], 0, 0, 0); __builtin_amdgcn_s_setprio(0); } while (0)
; #define PG8_WAIT_V(n) asm volatile("s_waitcnt vmcnt(" #n ")" ::: "memory")
; #define PG8_WAIT_L(n) asm volatile("s_waitcnt lgkmcnt(" #n ")" ::: "memory")
; #define PG8_BAR __builtin_amdgcn_s_barrier()
; #define PG8_SCHED __builtin_amdgcn_sched_barrier(0)
; template <class Epi, bool ALIGN_EPI>
; __device__ __forceinline__ void gemm_phase(LAS unsigned char* lds, const Gemm g, const StaticOrder& S, const Epi& E) {
;     ...
;         for (int t = 0; t < nt; t += 2) {
;             const bool last = (t == nt - 2);
;             const char* a1 = cA + (size_t)(t + 1) * kstep;
;             const char* a2 = last ? nA : cA + (size_t)(t + 2) * kstep; const char* b2 = last ? nB : cB + (size_t)(t + 2) * kstep;
;             const char* a3 = a2 + kstep; const char* b3 = b2 + kstep;
;             PG8_LDB(B0, 0, 0); PG8_LDB(B1, 0, 1); PG8_SCHED; PG8_LDA(At, 0, 0); PG8_STAGE(PG8_SA(1, 1), a1 + hA, voffA);
;             PG8_WAIT_V(8); PG8_WAIT_L(0); PG8_BAR; PG8_MMA(0, 0, At, B0); PG8_MMA(0, 1, At, B1); PG8_BAR; PG8_SCHED;
;             PG8_LDA(At, 0, 1); PG8_STAGE(PG8_SB(0, 0), b2, voffB); PG8_STAGE(PG8_SB(0, 1), b2 + hB, voffB); PG8_STAGE(PG8_SA(0, 0), a2, voffA);
;             PG8_WAIT_V(8); PG8_WAIT_L(0); PG8_BAR; PG8_MMA(1, 0, At, B0); PG8_MMA(1, 1, At, B1); PG8_BAR; PG8_SCHED;
.LBB0_252:
	ds_read_b128 v[168:171], v153
	ds_read_b128 v[172:175], v153 offset:1024
	ds_read_b128 v[176:179], v153 offset:2048
	ds_read_b128 v[180:183], v153 offset:3072
	ds_read_b128 v[184:187], v154
	ds_read_b128 v[188:191], v154 offset:1024
	ds_read_b128 v[194:197], v154 offset:2048
	ds_read_b128 v[198:201], v154 offset:3072
	s_add_u32 s8, s6, 0xfff80080
	s_addc_u32 s9, s7, -1
	s_cmp_eq_u32 s71, 28
	s_cselect_b32 s55, s47, s9
	s_cselect_b32 s54, s67, s8
	s_cselect_b32 s9, s45, s70
	s_cselect_b32 s8, s68, s69
	v_lshl_add_u64 v[234:235], s[6:7], 0, v[136:137]
	s_add_i32 m0, s39, 0xc000
	ds_read_b128 v[202:205], v155
	ds_read_b128 v[206:209], v155 offset:1024
	ds_read_b128 v[210:213], v155 offset:2048
	ds_read_b128 v[214:217], v155 offset:3072
	ds_read_b128 v[218:221], v155 offset:4096
	ds_read_b128 v[222:225], v155 offset:5120
	ds_read_b128 v[226:229], v155 offset:6144
	ds_read_b128 v[230:233], v155 offset:7168
	global_load_lds_dwordx4 v[234:235], off
	v_lshl_add_u64 v[234:235], s[6:7], 0, v[138:139]
	s_add_i32 m0, s39, 0xe000
	s_nop 0
	global_load_lds_dwordx4 v[234:235], off
	s_waitcnt vmcnt(8)
	s_waitcnt lgkmcnt(0)
	s_barrier
	s_setprio 1
	s_waitcnt lgkmcnt(0)
	v_mfma_f32_16x16x32_bf16 v[124:127], v[168:171], v[202:205], v[124:127]
	v_mfma_f32_16x16x32_bf16 v[124:127], v[172:175], v[206:209], v[124:127]
	v_mfma_f32_16x16x32_bf16 v[120:123], v[180:183], v[206:209], v[120:123]
	v_mfma_f32_16x16x32_bf16 v[120:123], v[176:179], v[202:205], v[120:123]
	v_mfma_f32_16x16x32_bf16 v[104:107], v[176:179], v[210:213], v[104:107]
	v_mfma_f32_16x16x32_bf16 v[104:107], v[180:183], v[214:217], v[104:107]
	v_mfma_f32_16x16x32_bf16 v[108:111], v[172:175], v[214:217], v[108:111]
	v_mfma_f32_16x16x32_bf16 v[108:111], v[168:171], v[210:213], v[108:111]
	v_mfma_f32_16x16x32_bf16 v[92:95], v[168:171], v[218:221], v[92:95]
	v_mfma_f32_16x16x32_bf16 v[92:95], v[172:175], v[222:225], v[92:95]
	v_mfma_f32_16x16x32_bf16 v[88:91], v[180:183], v[222:225], v[88:91]
	v_mfma_f32_16x16x32_bf16 v[88:91], v[176:179], v[218:221], v[88:91]
	v_mfma_f32_16x16x32_bf16 v[72:75], v[176:179], v[226:229], v[72:75]
	v_mfma_f32_16x16x32_bf16 v[72:75], v[180:183], v[230:233], v[72:75]
	v_mfma_f32_16x16x32_bf16 v[76:79], v[172:175], v[230:233], v[76:79]
	v_mfma_f32_16x16x32_bf16 v[76:79], v[168:171], v[226:229], v[76:79]
	s_setprio 0
	s_setprio 1
	v_mfma_f32_16x16x32_bf16 v[116:119], v[184:187], v[202:205], v[116:119]
	v_mfma_f32_16x16x32_bf16 v[116:119], v[188:191], v[206:209], v[116:119]
	v_mfma_f32_16x16x32_bf16 v[112:115], v[198:201], v[206:209], v[112:115]
	v_mfma_f32_16x16x32_bf16 v[112:115], v[194:197], v[202:205], v[112:115]
	v_mfma_f32_16x16x32_bf16 v[96:99], v[194:197], v[210:213], v[96:99]
	v_mfma_f32_16x16x32_bf16 v[96:99], v[198:201], v[214:217], v[96:99]
	v_mfma_f32_16x16x32_bf16 v[100:103], v[188:191], v[214:217], v[100:103]
	v_mfma_f32_16x16x32_bf16 v[100:103], v[184:187], v[210:213], v[100:103]
	v_mfma_f32_16x16x32_bf16 v[84:87], v[184:187], v[218:221], v[84:87]
	v_mfma_f32_16x16x32_bf16 v[84:87], v[188:191], v[222:225], v[84:87]
	v_mfma_f32_16x16x32_bf16 v[80:83], v[198:201], v[222:225], v[80:83]
	v_mfma_f32_16x16x32_bf16 v[80:83], v[194:197], v[218:221], v[80:83]
	v_mfma_f32_16x16x32_bf16 v[64:67], v[194:197], v[226:229], v[64:67]
	v_mfma_f32_16x16x32_bf16 v[64:67], v[198:201], v[230:233], v[64:67]
	v_mfma_f32_16x16x32_bf16 v[68:71], v[188:191], v[230:233], v[68:71]
	v_mfma_f32_16x16x32_bf16 v[68:71], v[184:187], v[226:229], v[68:71]
	s_setprio 0
	s_barrier
	s_add_i32 s72, s63, s33
	v_lshl_add_u64 v[234:235], s[8:9], 0, v[132:133]
	s_mov_b32 m0, s72
	ds_read_b128 v[202:205], v155 offset:16384
	ds_read_b128 v[206:209], v155 offset:17408
	ds_read_b128 v[210:213], v155 offset:18432
	ds_read_b128 v[214:217], v155 offset:19456
	ds_read_b128 v[218:221], v155 offset:20480
	ds_read_b128 v[222:225], v155 offset:21504
	ds_read_b128 v[226:229], v155 offset:22528
	ds_read_b128 v[230:233], v155 offset:23552
	global_load_lds_dwordx4 v[234:235], off
	s_add_i32 m0, s72, 0x2000
	s_add_u32 s72, s8, 0x80000
	v_lshl_add_u64 v[236:237], s[8:9], 0, v[128:129]
	s_addc_u32 s73, s9, 0
	s_add_i32 s74, s64, s33
	global_load_lds_dwordx4 v[236:237], off
	v_lshl_add_u64 v[238:239], s[72:73], 0, v[132:133]
	s_mov_b32 m0, s74
	v_lshl_add_u64 v[240:241], s[54:55], 0, v[130:131]
	global_load_lds_dwordx4 v[238:239], off
	v_lshl_add_u64 v[238:239], s[72:73], 0, v[128:129]
	s_add_i32 m0, s74, 0x2000
	s_nop 0
	global_load_lds_dwordx4 v[238:239], off
	v_lshl_add_u64 v[238:239], s[54:55], 0, v[134:135]
	s_mov_b32 m0, s39
	s_nop 0
	global_load_lds_dwordx4 v[238:239], off
	s_mov_b32 m0, s53
	s_nop 0
	global_load_lds_dwordx4 v[240:241], off
	s_waitcnt vmcnt(8)
	s_waitcnt lgkmcnt(0)
	s_barrier
; #define PG8_STAGE(bufoff, gbase, voff) do { _Pragma("unroll") for (int _i = 0; _i < 2; ++_i) \
;         __builtin_amdgcn_global_load_lds((const unsigned*)((const char*)(gbase) + (voff)[_i]), (LAS unsigned*)(lds + (bufoff) + ldsw + _i * 8192), 16, 0, 0); } while (0)
; #define PG8_LDA(dst, b, h) do { _Pragma("unroll") for (int m = 0; m < 4; ++m) _Pragma("unroll") for (int k = 0; k < 2; ++k) dst[m][k] = *(const LAS bf16x8*)(lds + PG8_SA(b, h) + aoff + m * 2048 + k * 1024); } while (0)
; #define PG8_LDB(dst, b, h) do { _Pragma("unroll") for (int n = 0; n < 2; ++n) _Pragma("unroll") for (int k = 0; k < 2; ++k) dst[n][k] = *(const LAS bf16x8*)(lds + PG8_SB(b, h) + boff + n * 2048 + k * 1024); } while (0)
; #define PG8_MMA(ai, bj, At, Bt) do { __builtin_amdgcn_s_setprio(1); _Pragma("unroll") for (int m = 0; m < 4; ++m) _Pragma("unroll") for (int n = 0; n < 2; ++n) _Pragma("unroll") for (int k = 0; k < 2; ++k) \
;         acc[ai][bj][m][n] = __builtin_amdgcn_mfma_f32_16x16x32_bf16(Bt[n][k], At[m][k], acc[ai][bj][m][n], 0, 0, 0); __builtin_amdgcn_s_setprio(0); } while (0)
; #define PG8_WAIT_V(n) asm volatile("s_waitcnt vmcnt(" #n ")" ::: "memory")
; #define PG8_WAIT_L(n) asm volatile("s_waitcnt lgkmcnt(" #n ")" ::: "memory")
; #define PG8_BAR __builtin_amdgcn_s_barrier()
; #define PG8_SCHED __builtin_amdgcn_sched_barrier(0)
; template <class Epi, bool ALIGN_EPI>
; __device__ __forceinline__ void gemm_phase(LAS unsigned char* lds, const Gemm g, const StaticOrder& S, const Epi& E) {
;     ...
;             PG8_WAIT_V(8); PG8_WAIT_L(0); PG8_BAR; PG8_MMA(1, 0, At, B0); PG8_MMA(1, 1, At, B1); PG8_BAR; PG8_SCHED;
;             PG8_LDB(B0, 1, 0); PG8_LDB(B1, 1, 1); PG8_SCHED; PG8_LDA(At, 1, 0); PG8_STAGE(PG8_SA(0, 1), a2 + hA, voffA);
;             PG8_WAIT_V(8); PG8_WAIT_L(0); PG8_BAR; PG8_MMA(0, 0, At, B0); PG8_MMA(0, 1, At, B1); PG8_BAR; PG8_SCHED;
	s_setprio 1
	s_waitcnt lgkmcnt(0)
	v_mfma_f32_16x16x32_bf16 v[60:63], v[168:171], v[202:205], v[60:63]
	v_mfma_f32_16x16x32_bf16 v[60:63], v[172:175], v[206:209], v[60:63]
	v_mfma_f32_16x16x32_bf16 v[56:59], v[180:183], v[206:209], v[56:59]
	v_mfma_f32_16x16x32_bf16 v[56:59], v[176:179], v[202:205], v[56:59]
	v_mfma_f32_16x16x32_bf16 v[40:43], v[176:179], v[210:213], v[40:43]
	v_mfma_f32_16x16x32_bf16 v[40:43], v[180:183], v[214:217], v[40:43]
	v_mfma_f32_16x16x32_bf16 v[48:51], v[172:175], v[214:217], v[48:51]
	v_mfma_f32_16x16x32_bf16 v[48:51], v[168:171], v[210:213], v[48:51]
	v_mfma_f32_16x16x32_bf16 v[32:35], v[168:171], v[218:221], v[32:35]
	v_mfma_f32_16x16x32_bf16 v[32:35], v[172:175], v[222:225], v[32:35]
	v_mfma_f32_16x16x32_bf16 v[24:27], v[180:183], v[222:225], v[24:27]
	v_mfma_f32_16x16x32_bf16 v[24:27], v[176:179], v[218:221], v[24:27]
	v_mfma_f32_16x16x32_bf16 v[8:11], v[176:179], v[226:229], v[8:11]
	v_mfma_f32_16x16x32_bf16 v[8:11], v[180:183], v[230:233], v[8:11]
	v_mfma_f32_16x16x32_bf16 v[16:19], v[172:175], v[230:233], v[16:19]
	v_mfma_f32_16x16x32_bf16 v[16:19], v[168:171], v[226:229], v[16:19]
	s_setprio 0
	s_setprio 1
	v_mfma_f32_16x16x32_bf16 v[52:55], v[184:187], v[202:205], v[52:55]
	v_mfma_f32_16x16x32_bf16 v[52:55], v[188:191], v[206:209], v[52:55]
	v_mfma_f32_16x16x32_bf16 v[44:47], v[198:201], v[206:209], v[44:47]
	v_mfma_f32_16x16x32_bf16 v[44:47], v[194:197], v[202:205], v[44:47]
	v_mfma_f32_16x16x32_bf16 v[28:31], v[194:197], v[210:213], v[28:31]
	v_mfma_f32_16x16x32_bf16 v[28:31], v[198:201], v[214:217], v[28:31]
	v_mfma_f32_16x16x32_bf16 v[36:39], v[188:191], v[214:217], v[36:39]
	v_mfma_f32_16x16x32_bf16 v[36:39], v[184:187], v[210:213], v[36:39]
	v_mfma_f32_16x16x32_bf16 v[20:23], v[184:187], v[218:221], v[20:23]
	v_mfma_f32_16x16x32_bf16 v[20:23], v[188:191], v[222:225], v[20:23]
	v_mfma_f32_16x16x32_bf16 v[12:15], v[198:201], v[222:225], v[12:15]
	v_mfma_f32_16x16x32_bf16 v[12:15], v[194:197], v[218:221], v[12:15]
	v_mfma_f32_16x16x32_bf16 v[0:3], v[194:197], v[226:229], v[0:3]
	v_mfma_f32_16x16x32_bf16 v[0:3], v[198:201], v[230:233], v[0:3]
	v_mfma_f32_16x16x32_bf16 v[4:7], v[188:191], v[230:233], v[4:7]
	v_mfma_f32_16x16x32_bf16 v[4:7], v[184:187], v[226:229], v[4:7]
	s_setprio 0
	s_barrier
	s_add_i32 s72, 0, 0x18000
	v_add_u32_e32 v167, s72, v149
	s_add_i32 s73, 0, 0x1c000
	ds_read_b128 v[168:171], v167
	ds_read_b128 v[172:175], v167 offset:1024
	ds_read_b128 v[176:179], v167 offset:2048
	ds_read_b128 v[180:183], v167 offset:3072
	v_add_u32_e32 v167, s73, v149
	ds_read_b128 v[184:187], v167
	ds_read_b128 v[188:191], v167 offset:1024
	ds_read_b128 v[194:197], v167 offset:2048
	ds_read_b128 v[198:201], v167 offset:3072
	s_add_u32 s54, s54, 0x80000
	s_addc_u32 s55, s55, 0
	s_mov_b32 m0, s56
	v_lshl_add_u64 v[242:243], s[54:55], 0, v[134:135]
	ds_read_b128 v[202:205], v155 offset:32768
	ds_read_b128 v[206:209], v155 offset:33792
	ds_read_b128 v[210:213], v155 offset:34816
	ds_read_b128 v[214:217], v155 offset:35840
	ds_read_b128 v[218:221], v155 offset:36864
	ds_read_b128 v[222:225], v155 offset:37888
	ds_read_b128 v[226:229], v155 offset:38912
	ds_read_b128 v[230:233], v155 offset:39936
	global_load_lds_dwordx4 v[242:243], off
	v_lshl_add_u64 v[242:243], s[54:55], 0, v[130:131]
	s_mov_b32 m0, s57
	s_nop 0
	global_load_lds_dwordx4 v[242:243], off
	s_waitcnt vmcnt(8)
	s_waitcnt lgkmcnt(0)
	s_barrier
	s_setprio 1
	s_waitcnt lgkmcnt(0)
	v_mfma_f32_16x16x32_bf16 v[124:127], v[168:171], v[202:205], v[124:127]
	v_mfma_f32_16x16x32_bf16 v[124:127], v[172:175], v[206:209], v[124:127]
	v_mfma_f32_16x16x32_bf16 v[120:123], v[180:183], v[206:209], v[120:123]
	v_mfma_f32_16x16x32_bf16 v[120:123], v[176:179], v[202:205], v[120:123]
	v_mfma_f32_16x16x32_bf16 v[104:107], v[176:179], v[210:213], v[104:107]
	v_mfma_f32_16x16x32_bf16 v[104:107], v[180:183], v[214:217], v[104:107]
	v_mfma_f32_16x16x32_bf16 v[108:111], v[172:175], v[214:217], v[108:111]
	v_mfma_f32_16x16x32_bf16 v[108:111], v[168:171], v[210:213], v[108:111]
	v_mfma_f32_16x16x32_bf16 v[92:95], v[168:171], v[218:221], v[92:95]
	v_mfma_f32_16x16x32_bf16 v[92:95], v[172:175], v[222:225], v[92:95]
	v_mfma_f32_16x16x32_bf16 v[88:91], v[180:183], v[222:225], v[88:91]
	v_mfma_f32_16x16x32_bf16 v[88:91], v[176:179], v[218:221], v[88:91]
	v_mfma_f32_16x16x32_bf16 v[72:75], v[176:179], v[226:229], v[72:75]
	v_mfma_f32_16x16x32_bf16 v[72:75], v[180:183], v[230:233], v[72:75]
	v_mfma_f32_16x16x32_bf16 v[76:79], v[172:175], v[230:233], v[76:79]
	v_mfma_f32_16x16x32_bf16 v[76:79], v[168:171], v[226:229], v[76:79]
	s_setprio 0
	s_setprio 1
	v_mfma_f32_16x16x32_bf16 v[116:119], v[184:187], v[202:205], v[116:119]
	v_mfma_f32_16x16x32_bf16 v[116:119], v[188:191], v[206:209], v[116:119]
	v_mfma_f32_16x16x32_bf16 v[112:115], v[198:201], v[206:209], v[112:115]
	v_mfma_f32_16x16x32_bf16 v[112:115], v[194:197], v[202:205], v[112:115]
	v_mfma_f32_16x16x32_bf16 v[96:99], v[194:197], v[210:213], v[96:99]
	v_mfma_f32_16x16x32_bf16 v[96:99], v[198:201], v[214:217], v[96:99]
	v_mfma_f32_16x16x32_bf16 v[100:103], v[188:191], v[214:217], v[100:103]
	v_mfma_f32_16x16x32_bf16 v[100:103], v[184:187], v[210:213], v[100:103]
	v_mfma_f32_16x16x32_bf16 v[84:87], v[184:187], v[218:221], v[84:87]
	v_mfma_f32_16x16x32_bf16 v[84:87], v[188:191], v[222:225], v[84:87]
	v_mfma_f32_16x16x32_bf16 v[80:83], v[198:201], v[222:225], v[80:83]
	v_mfma_f32_16x16x32_bf16 v[80:83], v[194:197], v[218:221], v[80:83]
	v_mfma_f32_16x16x32_bf16 v[64:67], v[194:197], v[226:229], v[64:67]
	v_mfma_f32_16x16x32_bf16 v[64:67], v[198:201], v[230:233], v[64:67]
	v_mfma_f32_16x16x32_bf16 v[68:71], v[188:191], v[230:233], v[68:71]
	v_mfma_f32_16x16x32_bf16 v[68:71], v[184:187], v[226:229], v[68:71]
	s_setprio 0
	s_barrier
; #define PG8_STAGE(bufoff, gbase, voff) do { _Pragma("unroll") for (int _i = 0; _i < 2; ++_i) \
;         __builtin_amdgcn_global_load_lds((const unsigned*)((const char*)(gbase) + (voff)[_i]), (LAS unsigned*)(lds + (bufoff) + ldsw + _i * 8192), 16, 0, 0); } while (0)
; #define PG8_LDA(dst, b, h) do { _Pragma("unroll") for (int m = 0; m < 4; ++m) _Pragma("unroll") for (int k = 0; k < 2; ++k) dst[m][k] = *(const LAS bf16x8*)(lds + PG8_SA(b, h) + aoff + m * 2048 + k * 1024); } while (0)
; #define PG8_MMA(ai, bj, At, Bt) do { __builtin_amdgcn_s_setprio(1); _Pragma("unroll") for (int m = 0; m < 4; ++m) _Pragma("unroll") for (int n = 0; n < 2; ++n) _Pragma("unroll") for (int k = 0; k < 2; ++k) \
;         acc[ai][bj][m][n] = __builtin_amdgcn_mfma_f32_16x16x32_bf16(Bt[n][k], At[m][k], acc[ai][bj][m][n], 0, 0, 0); __builtin_amdgcn_s_setprio(0); } while (0)
; #define PG8_WAIT_V(n) asm volatile("s_waitcnt vmcnt(" #n ")" ::: "memory")
; #define PG8_WAIT_L(n) asm volatile("s_waitcnt lgkmcnt(" #n ")" ::: "memory")
; #define PG8_BAR __builtin_amdgcn_s_barrier()
; #define PG8_SCHED __builtin_amdgcn_sched_barrier(0)
; template <class Epi, bool ALIGN_EPI>
; __device__ __forceinline__ void gemm_phase(LAS unsigned char* lds, const Gemm g, const StaticOrder& S, const Epi& E) {
;     ...
;             PG8_LDA(At, 1, 1); PG8_STAGE(PG8_SB(1, 0), b3, voffB); PG8_STAGE(PG8_SB(1, 1), b3 + hB, voffB); PG8_STAGE(PG8_SA(1, 0), a3, voffA);
;             PG8_WAIT_V(8); PG8_WAIT_L(0); PG8_BAR; PG8_MMA(1, 0, At, B0); PG8_MMA(1, 1, At, B1); PG8_BAR; PG8_SCHED;
;         }
	s_add_i32 s54, s72, s33
	v_lshl_add_u64 v[234:235], v[234:235], 0, s[20:21]
	s_mov_b32 m0, s54
	ds_read_b128 v[202:205], v155 offset:49152
	ds_read_b128 v[206:209], v155 offset:50176
	ds_read_b128 v[210:213], v155 offset:51200
	ds_read_b128 v[214:217], v155 offset:52224
	ds_read_b128 v[218:221], v155 offset:53248
	ds_read_b128 v[222:225], v155 offset:54272
	ds_read_b128 v[226:229], v155 offset:55296
	ds_read_b128 v[230:233], v155 offset:56320
	global_load_lds_dwordx4 v[234:235], off
	s_add_i32 m0, s54, 0x2000
	s_add_u32 s8, s8, 0x80080
	v_lshl_add_u64 v[234:235], v[236:237], 0, s[20:21]
	s_addc_u32 s9, s9, 0
	s_add_i32 s54, s73, s33
	global_load_lds_dwordx4 v[234:235], off
	v_lshl_add_u64 v[234:235], s[8:9], 0, v[132:133]
	s_mov_b32 m0, s54
	s_nop 0
	global_load_lds_dwordx4 v[234:235], off
	v_lshl_add_u64 v[234:235], s[8:9], 0, v[128:129]
	s_add_i32 m0, s54, 0x2000
	s_nop 0
	global_load_lds_dwordx4 v[234:235], off
	v_lshl_add_u64 v[234:235], v[238:239], 0, s[20:21]
	s_mov_b32 m0, s60
	s_nop 0
	global_load_lds_dwordx4 v[234:235], off
	v_lshl_add_u64 v[234:235], v[240:241], 0, s[20:21]
	s_mov_b32 m0, s61
	s_nop 0
	global_load_lds_dwordx4 v[234:235], off
	s_waitcnt vmcnt(8)
	s_waitcnt lgkmcnt(0)
	s_barrier
	s_setprio 1
	s_waitcnt lgkmcnt(0)
	v_mfma_f32_16x16x32_bf16 v[60:63], v[168:171], v[202:205], v[60:63]
	v_mfma_f32_16x16x32_bf16 v[60:63], v[172:175], v[206:209], v[60:63]
	v_mfma_f32_16x16x32_bf16 v[56:59], v[180:183], v[206:209], v[56:59]
	v_mfma_f32_16x16x32_bf16 v[56:59], v[176:179], v[202:205], v[56:59]
	v_mfma_f32_16x16x32_bf16 v[40:43], v[176:179], v[210:213], v[40:43]
	v_mfma_f32_16x16x32_bf16 v[40:43], v[180:183], v[214:217], v[40:43]
	v_mfma_f32_16x16x32_bf16 v[48:51], v[172:175], v[214:217], v[48:51]
	v_mfma_f32_16x16x32_bf16 v[48:51], v[168:171], v[210:213], v[48:51]
	v_mfma_f32_16x16x32_bf16 v[32:35], v[168:171], v[218:221], v[32:35]
	v_mfma_f32_16x16x32_bf16 v[32:35], v[172:175], v[222:225], v[32:35]
	v_mfma_f32_16x16x32_bf16 v[24:27], v[180:183], v[222:225], v[24:27]
	v_mfma_f32_16x16x32_bf16 v[24:27], v[176:179], v[218:221], v[24:27]
	v_mfma_f32_16x16x32_bf16 v[8:11], v[176:179], v[226:229], v[8:11]
	v_mfma_f32_16x16x32_bf16 v[8:11], v[180:183], v[230:233], v[8:11]
	v_mfma_f32_16x16x32_bf16 v[16:19], v[172:175], v[230:233], v[16:19]
	v_mfma_f32_16x16x32_bf16 v[16:19], v[168:171], v[226:229], v[16:19]
	s_setprio 0
	s_setprio 1
	v_mfma_f32_16x16x32_bf16 v[52:55], v[184:187], v[202:205], v[52:55]
	v_mfma_f32_16x16x32_bf16 v[52:55], v[188:191], v[206:209], v[52:55]
	v_mfma_f32_16x16x32_bf16 v[44:47], v[198:201], v[206:209], v[44:47]
	v_mfma_f32_16x16x32_bf16 v[44:47], v[194:197], v[202:205], v[44:47]
	v_mfma_f32_16x16x32_bf16 v[28:31], v[194:197], v[210:213], v[28:31]
	v_mfma_f32_16x16x32_bf16 v[28:31], v[198:201], v[214:217], v[28:31]
	v_mfma_f32_16x16x32_bf16 v[36:39], v[188:191], v[214:217], v[36:39]
	v_mfma_f32_16x16x32_bf16 v[36:39], v[184:187], v[210:213], v[36:39]
	v_mfma_f32_16x16x32_bf16 v[20:23], v[184:187], v[218:221], v[20:23]
	v_mfma_f32_16x16x32_bf16 v[20:23], v[188:191], v[222:225], v[20:23]
	v_mfma_f32_16x16x32_bf16 v[12:15], v[198:201], v[222:225], v[12:15]
	v_mfma_f32_16x16x32_bf16 v[12:15], v[194:197], v[218:221], v[12:15]
	v_mfma_f32_16x16x32_bf16 v[0:3], v[194:197], v[226:229], v[0:3]
	v_mfma_f32_16x16x32_bf16 v[0:3], v[198:201], v[230:233], v[0:3]
	v_mfma_f32_16x16x32_bf16 v[4:7], v[188:191], v[230:233], v[4:7]
	v_mfma_f32_16x16x32_bf16 v[4:7], v[184:187], v[226:229], v[4:7]
	s_setprio 0
	s_barrier
	s_add_i32 s71, s71, 2
	s_add_u32 s6, s6, 0x100
	s_addc_u32 s7, s7, 0
	s_add_u32 s69, s69, 0x100
	s_addc_u32 s70, s70, 0
	s_cmp_gt_u32 s71, 29
	s_cbranch_scc0 .LBB0_252
	s_and_b64 vcc, exec, s[22:23]
	s_cbranch_vccz .LBB0_255
	s_barrier

; #define PG8_STAGE(bufoff, gbase, voff) do { _Pragma("unroll") for (int _i = 0; _i < 2; ++_i) \
;         __builtin_amdgcn_global_load_lds((const unsigned*)((const char*)(gbase) + (voff)[_i]), (LAS unsigned*)(lds + (bufoff) + ldsw + _i * 8192), 16, 0, 0); } while (0)
; #define PG8_LDA(dst, b, h) do { _Pragma("unroll") for (int m = 0; m < 4; ++m) _Pragma("unroll") for (int k = 0; k < 2; ++k) dst[m][k] = *(const LAS bf16x8*)(lds + PG8_SA(b, h) + aoff + m * 2048 + k * 1024); } while (0)
; #define PG8_LDB(dst, b, h) do { _Pragma("unroll") for (int n = 0; n < 2; ++n) _Pragma("unroll") for (int k = 0; k < 2; ++k) dst[n][k] = *(const LAS bf16x8*)(lds + PG8_SB(b, h) + boff + n * 2048 + k * 1024); } while (0)
; #define PG8_MMA(ai, bj, At, Bt) do { __builtin_amdgcn_s_setprio(1); _Pragma("unroll") for (int m = 0; m < 4; ++m) _Pragma("unroll") for (int n = 0; n < 2; ++n) _Pragma("unroll") for (int k = 0; k < 2; ++k) \
;         acc[ai][bj][m][n] = __builtin_amdgcn_mfma_f32_16x16x32_bf16(Bt[n][k], At[m][k], acc[ai][bj][m][n], 0, 0, 0); __builtin_amdgcn_s_setprio(0); } while (0)
; #define PG8_WAIT_V(n) asm volatile("s_waitcnt vmcnt(" #n ")" ::: "memory")
; #define PG8_WAIT_L(n) asm volatile("s_waitcnt lgkmcnt(" #n ")" ::: "memory")
; #define PG8_BAR __builtin_amdgcn_s_barrier()
; #define PG8_SCHED __builtin_amdgcn_sched_barrier(0)
; template <class Epi, bool ALIGN_EPI>
; __device__ __forceinline__ void gemm_phase(LAS unsigned char* lds, const Gemm g, const StaticOrder& S, const Epi& E) {
;     ...
;         for (int t = 0; t < nt; t += 2) {
;             const bool last = (t == nt - 2);
;             const char* a1 = cA + (size_t)(t + 1) * kstep;
;             const char* a2 = last ? nA : cA + (size_t)(t + 2) * kstep; const char* b2 = last ? nB : cB + (size_t)(t + 2) * kstep;
;             const char* a3 = a2 + kstep; const char* b3 = b2 + kstep;
;             PG8_LDB(B0, 0, 0); PG8_LDB(B1, 0, 1); PG8_SCHED; PG8_LDA(At, 0, 0); PG8_STAGE(PG8_SA(1, 1), a1 + hA, voffA);
;             PG8_WAIT_V(8); PG8_WAIT_L(0); PG8_BAR; PG8_MMA(0, 0, At, B0); PG8_MMA(0, 1, At, B1); PG8_BAR; PG8_SCHED;
;             PG8_LDA(At, 0, 1); PG8_STAGE(PG8_SB(0, 0), b2, voffB); PG8_STAGE(PG8_SB(0, 1), b2 + hB, voffB); PG8_STAGE(PG8_SA(0, 0), a2, voffA);
;             PG8_WAIT_V(8); PG8_WAIT_L(0); PG8_BAR; PG8_MMA(1, 0, At, B0); PG8_MMA(1, 1, At, B1); PG8_BAR; PG8_SCHED;
.LBB0_385:
	ds_read_b128 v[152:155], v149
	ds_read_b128 v[156:159], v149 offset:1024
	ds_read_b128 v[160:163], v149 offset:2048
	ds_read_b128 v[164:167], v149 offset:3072
	ds_read_b128 v[168:171], v150
	ds_read_b128 v[172:175], v150 offset:1024
	ds_read_b128 v[176:179], v150 offset:2048
	ds_read_b128 v[180:183], v150 offset:3072
	s_add_u32 s40, s36, 0xfff80080
	s_addc_u32 s41, s37, -1
	s_cmp_eq_u32 s61, 4
	s_cselect_b32 s43, s27, s41
	s_cselect_b32 s42, s57, s40
	s_cselect_b32 s41, s25, s60
	s_cselect_b32 s40, s58, s59
	v_lshl_add_u64 v[144:145], s[36:37], 0, v[136:137]
	s_add_i32 m0, s35, 0xc000
	ds_read_b128 v[184:187], v151
	ds_read_b128 v[188:191], v151 offset:1024
	ds_read_b128 v[194:197], v151 offset:2048
	ds_read_b128 v[198:201], v151 offset:3072
	ds_read_b128 v[202:205], v151 offset:4096
	ds_read_b128 v[206:209], v151 offset:5120
	ds_read_b128 v[210:213], v151 offset:6144
	ds_read_b128 v[214:217], v151 offset:7168
	global_load_lds_dwordx4 v[144:145], off
	v_lshl_add_u64 v[144:145], s[36:37], 0, v[138:139]
	s_add_i32 m0, s35, 0xe000
	s_nop 0
	global_load_lds_dwordx4 v[144:145], off
	s_waitcnt vmcnt(8)
	s_waitcnt lgkmcnt(0)
	s_barrier
	s_setprio 1
	s_waitcnt lgkmcnt(0)
	v_mfma_f32_16x16x32_bf16 v[124:127], v[152:155], v[184:187], v[124:127]
	v_mfma_f32_16x16x32_bf16 v[124:127], v[156:159], v[188:191], v[124:127]
	v_mfma_f32_16x16x32_bf16 v[120:123], v[164:167], v[188:191], v[120:123]
	v_mfma_f32_16x16x32_bf16 v[120:123], v[160:163], v[184:187], v[120:123]
	v_mfma_f32_16x16x32_bf16 v[108:111], v[160:163], v[194:197], v[108:111]
	v_mfma_f32_16x16x32_bf16 v[108:111], v[164:167], v[198:201], v[108:111]
	v_mfma_f32_16x16x32_bf16 v[116:119], v[156:159], v[198:201], v[116:119]
	v_mfma_f32_16x16x32_bf16 v[116:119], v[152:155], v[194:197], v[116:119]
	v_mfma_f32_16x16x32_bf16 v[100:103], v[152:155], v[202:205], v[100:103]
	v_mfma_f32_16x16x32_bf16 v[100:103], v[156:159], v[206:209], v[100:103]
	v_mfma_f32_16x16x32_bf16 v[92:95], v[164:167], v[206:209], v[92:95]
	v_mfma_f32_16x16x32_bf16 v[92:95], v[160:163], v[202:205], v[92:95]
	v_mfma_f32_16x16x32_bf16 v[76:79], v[160:163], v[210:213], v[76:79]
	v_mfma_f32_16x16x32_bf16 v[76:79], v[164:167], v[214:217], v[76:79]
	v_mfma_f32_16x16x32_bf16 v[84:87], v[156:159], v[214:217], v[84:87]
	v_mfma_f32_16x16x32_bf16 v[84:87], v[152:155], v[210:213], v[84:87]
	s_setprio 0
	s_setprio 1
	v_mfma_f32_16x16x32_bf16 v[112:115], v[168:171], v[184:187], v[112:115]
	v_mfma_f32_16x16x32_bf16 v[112:115], v[172:175], v[188:191], v[112:115]
	v_mfma_f32_16x16x32_bf16 v[104:107], v[180:183], v[188:191], v[104:107]
	v_mfma_f32_16x16x32_bf16 v[104:107], v[176:179], v[184:187], v[104:107]
	v_mfma_f32_16x16x32_bf16 v[88:91], v[176:179], v[194:197], v[88:91]
	v_mfma_f32_16x16x32_bf16 v[88:91], v[180:183], v[198:201], v[88:91]
	v_mfma_f32_16x16x32_bf16 v[96:99], v[172:175], v[198:201], v[96:99]
	v_mfma_f32_16x16x32_bf16 v[96:99], v[168:171], v[194:197], v[96:99]
	v_mfma_f32_16x16x32_bf16 v[80:83], v[168:171], v[202:205], v[80:83]
	v_mfma_f32_16x16x32_bf16 v[80:83], v[172:175], v[206:209], v[80:83]
	v_mfma_f32_16x16x32_bf16 v[72:75], v[180:183], v[206:209], v[72:75]
	v_mfma_f32_16x16x32_bf16 v[72:75], v[176:179], v[202:205], v[72:75]
	v_mfma_f32_16x16x32_bf16 v[64:67], v[176:179], v[210:213], v[64:67]
	v_mfma_f32_16x16x32_bf16 v[64:67], v[180:183], v[214:217], v[64:67]
	v_mfma_f32_16x16x32_bf16 v[68:71], v[172:175], v[214:217], v[68:71]
	v_mfma_f32_16x16x32_bf16 v[68:71], v[168:171], v[210:213], v[68:71]
	s_setprio 0
	s_barrier
	s_add_i32 s62, s53, s45
	v_lshl_add_u64 v[144:145], s[40:41], 0, v[132:133]
	s_mov_b32 m0, s62
	ds_read_b128 v[184:187], v151 offset:16384
	ds_read_b128 v[188:191], v151 offset:17408
	ds_read_b128 v[194:197], v151 offset:18432
	ds_read_b128 v[198:201], v151 offset:19456
	ds_read_b128 v[202:205], v151 offset:20480
	ds_read_b128 v[206:209], v151 offset:21504
	ds_read_b128 v[210:213], v151 offset:22528
	ds_read_b128 v[214:217], v151 offset:23552
	global_load_lds_dwordx4 v[144:145], off
	s_add_i32 m0, s62, 0x2000
	s_add_u32 s62, s40, 0x20000
	v_lshl_add_u64 v[218:219], s[40:41], 0, v[128:129]
	s_addc_u32 s63, s41, 0
	s_add_i32 s64, s54, s45
	global_load_lds_dwordx4 v[218:219], off
	v_lshl_add_u64 v[220:221], s[62:63], 0, v[132:133]
	s_mov_b32 m0, s64
	v_lshl_add_u64 v[222:223], s[42:43], 0, v[130:131]
	global_load_lds_dwordx4 v[220:221], off
	v_lshl_add_u64 v[220:221], s[62:63], 0, v[128:129]
	s_add_i32 m0, s64, 0x2000
	s_nop 0
	global_load_lds_dwordx4 v[220:221], off
	v_lshl_add_u64 v[220:221], s[42:43], 0, v[134:135]
	s_mov_b32 m0, s35
	s_nop 0
	global_load_lds_dwordx4 v[220:221], off
	s_mov_b32 m0, s47
	s_nop 0
	global_load_lds_dwordx4 v[222:223], off
	s_waitcnt vmcnt(8)
	s_waitcnt lgkmcnt(0)
	s_barrier
; #define PG8_STAGE(bufoff, gbase, voff) do { _Pragma("unroll") for (int _i = 0; _i < 2; ++_i) \
;         __builtin_amdgcn_global_load_lds((const unsigned*)((const char*)(gbase) + (voff)[_i]), (LAS unsigned*)(lds + (bufoff) + ldsw + _i * 8192), 16, 0, 0); } while (0)
; #define PG8_LDA(dst, b, h) do { _Pragma("unroll") for (int m = 0; m < 4; ++m) _Pragma("unroll") for (int k = 0; k < 2; ++k) dst[m][k] = *(const LAS bf16x8*)(lds + PG8_SA(b, h) + aoff + m * 2048 + k * 1024); } while (0)
; #define PG8_LDB(dst, b, h) do { _Pragma("unroll") for (int n = 0; n < 2; ++n) _Pragma("unroll") for (int k = 0; k < 2; ++k) dst[n][k] = *(const LAS bf16x8*)(lds + PG8_SB(b, h) + boff + n * 2048 + k * 1024); } while (0)
; #define PG8_MMA(ai, bj, At, Bt) do { __builtin_amdgcn_s_setprio(1); _Pragma("unroll") for (int m = 0; m < 4; ++m) _Pragma("unroll") for (int n = 0; n < 2; ++n) _Pragma("unroll") for (int k = 0; k < 2; ++k) \
;         acc[ai][bj][m][n] = __builtin_amdgcn_mfma_f32_16x16x32_bf16(Bt[n][k], At[m][k], acc[ai][bj][m][n], 0, 0, 0); __builtin_amdgcn_s_setprio(0); } while (0)
; #define PG8_WAIT_V(n) asm volatile("s_waitcnt vmcnt(" #n ")" ::: "memory")
; #define PG8_WAIT_L(n) asm volatile("s_waitcnt lgkmcnt(" #n ")" ::: "memory")
; #define PG8_BAR __builtin_amdgcn_s_barrier()
; #define PG8_SCHED __builtin_amdgcn_sched_barrier(0)
; template <class Epi, bool ALIGN_EPI>
; __device__ __forceinline__ void gemm_phase(LAS unsigned char* lds, const Gemm g, const StaticOrder& S, const Epi& E) {
;     ...
;             PG8_WAIT_V(8); PG8_WAIT_L(0); PG8_BAR; PG8_MMA(1, 0, At, B0); PG8_MMA(1, 1, At, B1); PG8_BAR; PG8_SCHED;
;             PG8_LDB(B0, 1, 0); PG8_LDB(B1, 1, 1); PG8_SCHED; PG8_LDA(At, 1, 0); PG8_STAGE(PG8_SA(0, 1), a2 + hA, voffA);
;             PG8_WAIT_V(8); PG8_WAIT_L(0); PG8_BAR; PG8_MMA(0, 0, At, B0); PG8_MMA(0, 1, At, B1); PG8_BAR; PG8_SCHED;
	s_setprio 1
	s_waitcnt lgkmcnt(0)
	v_mfma_f32_16x16x32_bf16 v[60:63], v[152:155], v[184:187], v[60:63]
	v_mfma_f32_16x16x32_bf16 v[60:63], v[156:159], v[188:191], v[60:63]
	v_mfma_f32_16x16x32_bf16 v[56:59], v[164:167], v[188:191], v[56:59]
	v_mfma_f32_16x16x32_bf16 v[56:59], v[160:163], v[184:187], v[56:59]
	v_mfma_f32_16x16x32_bf16 v[44:47], v[160:163], v[194:197], v[44:47]
	v_mfma_f32_16x16x32_bf16 v[44:47], v[164:167], v[198:201], v[44:47]
	v_mfma_f32_16x16x32_bf16 v[52:55], v[156:159], v[198:201], v[52:55]
	v_mfma_f32_16x16x32_bf16 v[52:55], v[152:155], v[194:197], v[52:55]
	v_mfma_f32_16x16x32_bf16 v[36:39], v[152:155], v[202:205], v[36:39]
	v_mfma_f32_16x16x32_bf16 v[36:39], v[156:159], v[206:209], v[36:39]
	v_mfma_f32_16x16x32_bf16 v[28:31], v[164:167], v[206:209], v[28:31]
	v_mfma_f32_16x16x32_bf16 v[28:31], v[160:163], v[202:205], v[28:31]
	v_mfma_f32_16x16x32_bf16 v[12:15], v[160:163], v[210:213], v[12:15]
	v_mfma_f32_16x16x32_bf16 v[12:15], v[164:167], v[214:217], v[12:15]
	v_mfma_f32_16x16x32_bf16 v[20:23], v[156:159], v[214:217], v[20:23]
	v_mfma_f32_16x16x32_bf16 v[20:23], v[152:155], v[210:213], v[20:23]
	s_setprio 0
	s_setprio 1
	v_mfma_f32_16x16x32_bf16 v[48:51], v[168:171], v[184:187], v[48:51]
	v_mfma_f32_16x16x32_bf16 v[48:51], v[172:175], v[188:191], v[48:51]
	v_mfma_f32_16x16x32_bf16 v[40:43], v[180:183], v[188:191], v[40:43]
	v_mfma_f32_16x16x32_bf16 v[40:43], v[176:179], v[184:187], v[40:43]
	v_mfma_f32_16x16x32_bf16 v[24:27], v[176:179], v[194:197], v[24:27]
	v_mfma_f32_16x16x32_bf16 v[24:27], v[180:183], v[198:201], v[24:27]
	v_mfma_f32_16x16x32_bf16 v[32:35], v[172:175], v[198:201], v[32:35]
	v_mfma_f32_16x16x32_bf16 v[32:35], v[168:171], v[194:197], v[32:35]
	v_mfma_f32_16x16x32_bf16 v[16:19], v[168:171], v[202:205], v[16:19]
	v_mfma_f32_16x16x32_bf16 v[16:19], v[172:175], v[206:209], v[16:19]
	v_mfma_f32_16x16x32_bf16 v[8:11], v[180:183], v[206:209], v[8:11]
	v_mfma_f32_16x16x32_bf16 v[8:11], v[176:179], v[202:205], v[8:11]
	v_mfma_f32_16x16x32_bf16 v[0:3], v[176:179], v[210:213], v[0:3]
	v_mfma_f32_16x16x32_bf16 v[0:3], v[180:183], v[214:217], v[0:3]
	v_mfma_f32_16x16x32_bf16 v[4:7], v[172:175], v[214:217], v[4:7]
	v_mfma_f32_16x16x32_bf16 v[4:7], v[168:171], v[210:213], v[4:7]
	s_setprio 0
	s_barrier
	s_add_i32 s62, 0, 0x18000
	s_add_i32 s63, 0, 0x1c000
	v_add_u32_e32 v164, s62, v147
	v_add_u32_e32 v180, s63, v147
	ds_read_b128 v[152:155], v164
	ds_read_b128 v[156:159], v164 offset:1024
	ds_read_b128 v[160:163], v164 offset:2048
	ds_read_b128 v[164:167], v164 offset:3072
	ds_read_b128 v[168:171], v180
	ds_read_b128 v[172:175], v180 offset:1024
	ds_read_b128 v[176:179], v180 offset:2048
	ds_read_b128 v[180:183], v180 offset:3072
	s_add_u32 s42, s42, 0x80000
	s_addc_u32 s43, s43, 0
	s_mov_b32 m0, s48
	v_lshl_add_u64 v[224:225], s[42:43], 0, v[134:135]
	ds_read_b128 v[184:187], v151 offset:32768
	ds_read_b128 v[188:191], v151 offset:33792
	ds_read_b128 v[194:197], v151 offset:34816
	ds_read_b128 v[198:201], v151 offset:35840
	ds_read_b128 v[202:205], v151 offset:36864
	ds_read_b128 v[206:209], v151 offset:37888
	ds_read_b128 v[210:213], v151 offset:38912
	ds_read_b128 v[214:217], v151 offset:39936
	global_load_lds_dwordx4 v[224:225], off
	v_lshl_add_u64 v[224:225], s[42:43], 0, v[130:131]
	s_mov_b32 m0, s49
	s_nop 0
	global_load_lds_dwordx4 v[224:225], off
	s_waitcnt vmcnt(8)
	s_waitcnt lgkmcnt(0)
	s_barrier
	s_setprio 1
	s_waitcnt lgkmcnt(0)
	v_mfma_f32_16x16x32_bf16 v[124:127], v[152:155], v[184:187], v[124:127]
	v_mfma_f32_16x16x32_bf16 v[124:127], v[156:159], v[188:191], v[124:127]
	v_mfma_f32_16x16x32_bf16 v[120:123], v[164:167], v[188:191], v[120:123]
	v_mfma_f32_16x16x32_bf16 v[120:123], v[160:163], v[184:187], v[120:123]
	v_mfma_f32_16x16x32_bf16 v[108:111], v[160:163], v[194:197], v[108:111]
	v_mfma_f32_16x16x32_bf16 v[108:111], v[164:167], v[198:201], v[108:111]
	v_mfma_f32_16x16x32_bf16 v[116:119], v[156:159], v[198:201], v[116:119]
	v_mfma_f32_16x16x32_bf16 v[116:119], v[152:155], v[194:197], v[116:119]
	v_mfma_f32_16x16x32_bf16 v[100:103], v[152:155], v[202:205], v[100:103]
	v_mfma_f32_16x16x32_bf16 v[100:103], v[156:159], v[206:209], v[100:103]
	v_mfma_f32_16x16x32_bf16 v[92:95], v[164:167], v[206:209], v[92:95]
	v_mfma_f32_16x16x32_bf16 v[92:95], v[160:163], v[202:205], v[92:95]
	v_mfma_f32_16x16x32_bf16 v[76:79], v[160:163], v[210:213], v[76:79]
	v_mfma_f32_16x16x32_bf16 v[76:79], v[164:167], v[214:217], v[76:79]
	v_mfma_f32_16x16x32_bf16 v[84:87], v[156:159], v[214:217], v[84:87]
	v_mfma_f32_16x16x32_bf16 v[84:87], v[152:155], v[210:213], v[84:87]
	s_setprio 0
	s_setprio 1
	v_mfma_f32_16x16x32_bf16 v[112:115], v[168:171], v[184:187], v[112:115]
	v_mfma_f32_16x16x32_bf16 v[112:115], v[172:175], v[188:191], v[112:115]
	v_mfma_f32_16x16x32_bf16 v[104:107], v[180:183], v[188:191], v[104:107]
	v_mfma_f32_16x16x32_bf16 v[104:107], v[176:179], v[184:187], v[104:107]
	v_mfma_f32_16x16x32_bf16 v[88:91], v[176:179], v[194:197], v[88:91]
	v_mfma_f32_16x16x32_bf16 v[88:91], v[180:183], v[198:201], v[88:91]
	v_mfma_f32_16x16x32_bf16 v[96:99], v[172:175], v[198:201], v[96:99]
	v_mfma_f32_16x16x32_bf16 v[96:99], v[168:171], v[194:197], v[96:99]
	v_mfma_f32_16x16x32_bf16 v[80:83], v[168:171], v[202:205], v[80:83]
	v_mfma_f32_16x16x32_bf16 v[80:83], v[172:175], v[206:209], v[80:83]
	v_mfma_f32_16x16x32_bf16 v[72:75], v[180:183], v[206:209], v[72:75]
	v_mfma_f32_16x16x32_bf16 v[72:75], v[176:179], v[202:205], v[72:75]
	v_mfma_f32_16x16x32_bf16 v[64:67], v[176:179], v[210:213], v[64:67]
	v_mfma_f32_16x16x32_bf16 v[64:67], v[180:183], v[214:217], v[64:67]
	v_mfma_f32_16x16x32_bf16 v[68:71], v[172:175], v[214:217], v[68:71]
	v_mfma_f32_16x16x32_bf16 v[68:71], v[168:171], v[210:213], v[68:71]
	s_setprio 0
	s_barrier
; #define PG8_STAGE(bufoff, gbase, voff) do { _Pragma("unroll") for (int _i = 0; _i < 2; ++_i) \
;         __builtin_amdgcn_global_load_lds((const unsigned*)((const char*)(gbase) + (voff)[_i]), (LAS unsigned*)(lds + (bufoff) + ldsw + _i * 8192), 16, 0, 0); } while (0)
; #define PG8_LDA(dst, b, h) do { _Pragma("unroll") for (int m = 0; m < 4; ++m) _Pragma("unroll") for (int k = 0; k < 2; ++k) dst[m][k] = *(const LAS bf16x8*)(lds + PG8_SA(b, h) + aoff + m * 2048 + k * 1024); } while (0)
; #define PG8_MMA(ai, bj, At, Bt) do { __builtin_amdgcn_s_setprio(1); _Pragma("unroll") for (int m = 0; m < 4; ++m) _Pragma("unroll") for (int n = 0; n < 2; ++n) _Pragma("unroll") for (int k = 0; k < 2; ++k) \
;         acc[ai][bj][m][n] = __builtin_amdgcn_mfma_f32_16x16x32_bf16(Bt[n][k], At[m][k], acc[ai][bj][m][n], 0, 0, 0); __builtin_amdgcn_s_setprio(0); } while (0)
; #define PG8_WAIT_V(n) asm volatile("s_waitcnt vmcnt(" #n ")" ::: "memory")
; #define PG8_WAIT_L(n) asm volatile("s_waitcnt lgkmcnt(" #n ")" ::: "memory")
; #define PG8_BAR __builtin_amdgcn_s_barrier()
; #define PG8_SCHED __builtin_amdgcn_sched_barrier(0)
; template <class Epi, bool ALIGN_EPI>
; __device__ __forceinline__ void gemm_phase(LAS unsigned char* lds, const Gemm g, const StaticOrder& S, const Epi& E) {
;     ...
;             PG8_LDA(At, 1, 1); PG8_STAGE(PG8_SB(1, 0), b3, voffB); PG8_STAGE(PG8_SB(1, 1), b3 + hB, voffB); PG8_STAGE(PG8_SA(1, 0), a3, voffA);
;             PG8_WAIT_V(8); PG8_WAIT_L(0); PG8_BAR; PG8_MMA(1, 0, At, B0); PG8_MMA(1, 1, At, B1); PG8_BAR; PG8_SCHED;
;         }
	s_add_i32 s42, s62, s45
	v_lshl_add_u64 v[144:145], v[144:145], 0, s[18:19]
	s_mov_b32 m0, s42
	ds_read_b128 v[184:187], v151 offset:49152
	ds_read_b128 v[188:191], v151 offset:50176
	ds_read_b128 v[194:197], v151 offset:51200
	ds_read_b128 v[198:201], v151 offset:52224
	ds_read_b128 v[202:205], v151 offset:53248
	ds_read_b128 v[206:209], v151 offset:54272
	ds_read_b128 v[210:213], v151 offset:55296
	ds_read_b128 v[214:217], v151 offset:56320
	global_load_lds_dwordx4 v[144:145], off
	s_add_i32 m0, s42, 0x2000
	s_add_u32 s40, s40, 0x20080
	v_lshl_add_u64 v[144:145], v[218:219], 0, s[18:19]
	s_addc_u32 s41, s41, 0
	s_add_i32 s42, s63, s45
	global_load_lds_dwordx4 v[144:145], off
	v_lshl_add_u64 v[144:145], s[40:41], 0, v[132:133]
	s_mov_b32 m0, s42
	s_nop 0
	global_load_lds_dwordx4 v[144:145], off
	v_lshl_add_u64 v[144:145], s[40:41], 0, v[128:129]
	s_add_i32 m0, s42, 0x2000
	s_nop 0
	global_load_lds_dwordx4 v[144:145], off
	v_lshl_add_u64 v[144:145], v[220:221], 0, s[18:19]
	s_mov_b32 m0, s50
	s_nop 0
	global_load_lds_dwordx4 v[144:145], off
	v_lshl_add_u64 v[144:145], v[222:223], 0, s[18:19]
	s_mov_b32 m0, s51
	s_nop 0
	global_load_lds_dwordx4 v[144:145], off
	s_waitcnt vmcnt(8)
	s_waitcnt lgkmcnt(0)
	s_barrier
	s_setprio 1
	s_waitcnt lgkmcnt(0)
	v_mfma_f32_16x16x32_bf16 v[60:63], v[152:155], v[184:187], v[60:63]
	v_mfma_f32_16x16x32_bf16 v[60:63], v[156:159], v[188:191], v[60:63]
	v_mfma_f32_16x16x32_bf16 v[56:59], v[164:167], v[188:191], v[56:59]
	v_mfma_f32_16x16x32_bf16 v[56:59], v[160:163], v[184:187], v[56:59]
	v_mfma_f32_16x16x32_bf16 v[44:47], v[160:163], v[194:197], v[44:47]
	v_mfma_f32_16x16x32_bf16 v[44:47], v[164:167], v[198:201], v[44:47]
	v_mfma_f32_16x16x32_bf16 v[52:55], v[156:159], v[198:201], v[52:55]
	v_mfma_f32_16x16x32_bf16 v[52:55], v[152:155], v[194:197], v[52:55]
	v_mfma_f32_16x16x32_bf16 v[36:39], v[152:155], v[202:205], v[36:39]
	v_mfma_f32_16x16x32_bf16 v[36:39], v[156:159], v[206:209], v[36:39]
	v_mfma_f32_16x16x32_bf16 v[28:31], v[164:167], v[206:209], v[28:31]
	v_mfma_f32_16x16x32_bf16 v[28:31], v[160:163], v[202:205], v[28:31]
	v_mfma_f32_16x16x32_bf16 v[12:15], v[160:163], v[210:213], v[12:15]
	v_mfma_f32_16x16x32_bf16 v[12:15], v[164:167], v[214:217], v[12:15]
	v_mfma_f32_16x16x32_bf16 v[20:23], v[156:159], v[214:217], v[20:23]
	v_mfma_f32_16x16x32_bf16 v[20:23], v[152:155], v[210:213], v[20:23]
	s_setprio 0
	s_setprio 1
	v_mfma_f32_16x16x32_bf16 v[48:51], v[168:171], v[184:187], v[48:51]
	v_mfma_f32_16x16x32_bf16 v[48:51], v[172:175], v[188:191], v[48:51]
	v_mfma_f32_16x16x32_bf16 v[40:43], v[180:183], v[188:191], v[40:43]
	v_mfma_f32_16x16x32_bf16 v[40:43], v[176:179], v[184:187], v[40:43]
	v_mfma_f32_16x16x32_bf16 v[24:27], v[176:179], v[194:197], v[24:27]
	v_mfma_f32_16x16x32_bf16 v[24:27], v[180:183], v[198:201], v[24:27]
	v_mfma_f32_16x16x32_bf16 v[32:35], v[172:175], v[198:201], v[32:35]
	v_mfma_f32_16x16x32_bf16 v[32:35], v[168:171], v[194:197], v[32:35]
	v_mfma_f32_16x16x32_bf16 v[16:19], v[168:171], v[202:205], v[16:19]
	v_mfma_f32_16x16x32_bf16 v[16:19], v[172:175], v[206:209], v[16:19]
	v_mfma_f32_16x16x32_bf16 v[8:11], v[180:183], v[206:209], v[8:11]
	v_mfma_f32_16x16x32_bf16 v[8:11], v[176:179], v[202:205], v[8:11]
	v_mfma_f32_16x16x32_bf16 v[0:3], v[176:179], v[210:213], v[0:3]
	v_mfma_f32_16x16x32_bf16 v[0:3], v[180:183], v[214:217], v[0:3]
	v_mfma_f32_16x16x32_bf16 v[4:7], v[172:175], v[214:217], v[4:7]
	v_mfma_f32_16x16x32_bf16 v[4:7], v[168:171], v[210:213], v[4:7]
	s_setprio 0
	s_barrier
	s_add_i32 s61, s61, 2
	s_add_u32 s36, s36, 0x100
	s_addc_u32 s37, s37, 0
	s_add_u32 s59, s59, 0x100
	s_addc_u32 s60, s60, 0
	s_cmp_gt_u32 s61, 5
	s_cbranch_scc0 .LBB0_385
	s_and_b64 vcc, exec, s[20:21]
	s_cbranch_vccz .LBB0_388
	s_barrier

; #define PG8_STAGE(bufoff, gbase, voff) do { _Pragma("unroll") for (int _i = 0; _i < 2; ++_i) \
;         __builtin_amdgcn_global_load_lds((const unsigned*)((const char*)(gbase) + (voff)[_i]), (LAS unsigned*)(lds + (bufoff) + ldsw + _i * 8192), 16, 0, 0); } while (0)
; #define PG8_LDA(dst, b, h) do { _Pragma("unroll") for (int m = 0; m < 4; ++m) _Pragma("unroll") for (int k = 0; k < 2; ++k) dst[m][k] = *(const LAS bf16x8*)(lds + PG8_SA(b, h) + aoff + m * 2048 + k * 1024); } while (0)
; #define PG8_LDB(dst, b, h) do { _Pragma("unroll") for (int n = 0; n < 2; ++n) _Pragma("unroll") for (int k = 0; k < 2; ++k) dst[n][k] = *(const LAS bf16x8*)(lds + PG8_SB(b, h) + boff + n * 2048 + k * 1024); } while (0)
; #define PG8_MMA(ai, bj, At, Bt) do { __builtin_amdgcn_s_setprio(1); _Pragma("unroll") for (int m = 0; m < 4; ++m) _Pragma("unroll") for (int n = 0; n < 2; ++n) _Pragma("unroll") for (int k = 0; k < 2; ++k) \
;         acc[ai][bj][m][n] = __builtin_amdgcn_mfma_f32_16x16x32_bf16(Bt[n][k], At[m][k], acc[ai][bj][m][n], 0, 0, 0); __builtin_amdgcn_s_setprio(0); } while (0)
; #define PG8_WAIT_V(n) asm volatile("s_waitcnt vmcnt(" #n ")" ::: "memory")
; #define PG8_WAIT_L(n) asm volatile("s_waitcnt lgkmcnt(" #n ")" ::: "memory")
; #define PG8_BAR __builtin_amdgcn_s_barrier()
; #define PG8_SCHED __builtin_amdgcn_sched_barrier(0)
; template <class Epi, bool ALIGN_EPI>
; __device__ __forceinline__ void gemm_phase(LAS unsigned char* lds, const Gemm g, const StaticOrder& S, const Epi& E) {
;     ...
;         for (int t = 0; t < nt; t += 2) {
;             const bool last = (t == nt - 2);
;             const char* a1 = cA + (size_t)(t + 1) * kstep;
;             const char* a2 = last ? nA : cA + (size_t)(t + 2) * kstep; const char* b2 = last ? nB : cB + (size_t)(t + 2) * kstep;
;             const char* a3 = a2 + kstep; const char* b3 = b2 + kstep;
;             PG8_LDB(B0, 0, 0); PG8_LDB(B1, 0, 1); PG8_SCHED; PG8_LDA(At, 0, 0); PG8_STAGE(PG8_SA(1, 1), a1 + hA, voffA);
;             PG8_WAIT_V(8); PG8_WAIT_L(0); PG8_BAR; PG8_MMA(0, 0, At, B0); PG8_MMA(0, 1, At, B1); PG8_BAR; PG8_SCHED;
;             PG8_LDA(At, 0, 1); PG8_STAGE(PG8_SB(0, 0), b2, voffB); PG8_STAGE(PG8_SB(0, 1), b2 + hB, voffB); PG8_STAGE(PG8_SA(0, 0), a2, voffA);
;             PG8_WAIT_V(8); PG8_WAIT_L(0); PG8_BAR; PG8_MMA(1, 0, At, B0); PG8_MMA(1, 1, At, B1); PG8_BAR; PG8_SCHED;
.LBB0_403:
	ds_read_b128 v[152:155], v149
	ds_read_b128 v[156:159], v149 offset:1024
	ds_read_b128 v[160:163], v149 offset:2048
	ds_read_b128 v[164:167], v149 offset:3072
	ds_read_b128 v[168:171], v150
	ds_read_b128 v[172:175], v150 offset:1024
	ds_read_b128 v[176:179], v150 offset:2048
	ds_read_b128 v[180:183], v150 offset:3072
	s_add_u32 s30, s6, 0xfff80080
	s_addc_u32 s31, s7, -1
	s_cmp_eq_u32 s53, 8
	s_cselect_b32 s35, s23, s31
	s_cselect_b32 s34, s50, s30
	s_cselect_b32 s31, s25, s52
	s_cselect_b32 s30, s24, s51
	v_lshl_add_u64 v[144:145], s[6:7], 0, v[136:137]
	s_add_i32 m0, s0, 0xc000
	ds_read_b128 v[184:187], v151
	ds_read_b128 v[188:191], v151 offset:1024
	ds_read_b128 v[194:197], v151 offset:2048
	ds_read_b128 v[198:201], v151 offset:3072
	ds_read_b128 v[202:205], v151 offset:4096
	ds_read_b128 v[206:209], v151 offset:5120
	ds_read_b128 v[210:213], v151 offset:6144
	ds_read_b128 v[214:217], v151 offset:7168
	global_load_lds_dwordx4 v[144:145], off
	v_lshl_add_u64 v[144:145], s[6:7], 0, v[138:139]
	s_add_i32 m0, s0, 0xe000
	s_nop 0
	global_load_lds_dwordx4 v[144:145], off
	s_waitcnt vmcnt(8)
	s_waitcnt lgkmcnt(0)
	s_barrier
	s_setprio 1
	s_waitcnt lgkmcnt(0)
	v_mfma_f32_16x16x32_bf16 v[124:127], v[152:155], v[184:187], v[124:127]
	v_mfma_f32_16x16x32_bf16 v[124:127], v[156:159], v[188:191], v[124:127]
	v_mfma_f32_16x16x32_bf16 v[120:123], v[164:167], v[188:191], v[120:123]
	v_mfma_f32_16x16x32_bf16 v[120:123], v[160:163], v[184:187], v[120:123]
	v_mfma_f32_16x16x32_bf16 v[108:111], v[160:163], v[194:197], v[108:111]
	v_mfma_f32_16x16x32_bf16 v[108:111], v[164:167], v[198:201], v[108:111]
	v_mfma_f32_16x16x32_bf16 v[116:119], v[156:159], v[198:201], v[116:119]
	v_mfma_f32_16x16x32_bf16 v[116:119], v[152:155], v[194:197], v[116:119]
	v_mfma_f32_16x16x32_bf16 v[100:103], v[152:155], v[202:205], v[100:103]
	v_mfma_f32_16x16x32_bf16 v[100:103], v[156:159], v[206:209], v[100:103]
	v_mfma_f32_16x16x32_bf16 v[92:95], v[164:167], v[206:209], v[92:95]
	v_mfma_f32_16x16x32_bf16 v[92:95], v[160:163], v[202:205], v[92:95]
	v_mfma_f32_16x16x32_bf16 v[76:79], v[160:163], v[210:213], v[76:79]
	v_mfma_f32_16x16x32_bf16 v[76:79], v[164:167], v[214:217], v[76:79]
	v_mfma_f32_16x16x32_bf16 v[84:87], v[156:159], v[214:217], v[84:87]
	v_mfma_f32_16x16x32_bf16 v[84:87], v[152:155], v[210:213], v[84:87]
	s_setprio 0
	s_setprio 1
	v_mfma_f32_16x16x32_bf16 v[112:115], v[168:171], v[184:187], v[112:115]
	v_mfma_f32_16x16x32_bf16 v[112:115], v[172:175], v[188:191], v[112:115]
	v_mfma_f32_16x16x32_bf16 v[104:107], v[180:183], v[188:191], v[104:107]
	v_mfma_f32_16x16x32_bf16 v[104:107], v[176:179], v[184:187], v[104:107]
	v_mfma_f32_16x16x32_bf16 v[88:91], v[176:179], v[194:197], v[88:91]
	v_mfma_f32_16x16x32_bf16 v[88:91], v[180:183], v[198:201], v[88:91]
	v_mfma_f32_16x16x32_bf16 v[96:99], v[172:175], v[198:201], v[96:99]
	v_mfma_f32_16x16x32_bf16 v[96:99], v[168:171], v[194:197], v[96:99]
	v_mfma_f32_16x16x32_bf16 v[80:83], v[168:171], v[202:205], v[80:83]
	v_mfma_f32_16x16x32_bf16 v[80:83], v[172:175], v[206:209], v[80:83]
	v_mfma_f32_16x16x32_bf16 v[72:75], v[180:183], v[206:209], v[72:75]
	v_mfma_f32_16x16x32_bf16 v[72:75], v[176:179], v[202:205], v[72:75]
	v_mfma_f32_16x16x32_bf16 v[64:67], v[176:179], v[210:213], v[64:67]
	v_mfma_f32_16x16x32_bf16 v[64:67], v[180:183], v[214:217], v[64:67]
	v_mfma_f32_16x16x32_bf16 v[68:71], v[172:175], v[214:217], v[68:71]
	v_mfma_f32_16x16x32_bf16 v[68:71], v[168:171], v[210:213], v[68:71]
	s_setprio 0
	s_barrier
	s_add_i32 s54, s45, s2
	v_lshl_add_u64 v[144:145], s[30:31], 0, v[132:133]
	s_mov_b32 m0, s54
	ds_read_b128 v[184:187], v151 offset:16384
	ds_read_b128 v[188:191], v151 offset:17408
	ds_read_b128 v[194:197], v151 offset:18432
	ds_read_b128 v[198:201], v151 offset:19456
	ds_read_b128 v[202:205], v151 offset:20480
	ds_read_b128 v[206:209], v151 offset:21504
	ds_read_b128 v[210:213], v151 offset:22528
	ds_read_b128 v[214:217], v151 offset:23552
	global_load_lds_dwordx4 v[144:145], off
	s_add_i32 m0, s54, 0x2000
	s_add_u32 s54, s30, 0x30000
	v_lshl_add_u64 v[218:219], s[30:31], 0, v[128:129]
	s_addc_u32 s55, s31, 0
	s_add_i32 s56, s46, s2
	global_load_lds_dwordx4 v[218:219], off
	v_lshl_add_u64 v[220:221], s[54:55], 0, v[132:133]
	s_mov_b32 m0, s56
	v_lshl_add_u64 v[222:223], s[34:35], 0, v[130:131]
	global_load_lds_dwordx4 v[220:221], off
	v_lshl_add_u64 v[220:221], s[54:55], 0, v[128:129]
	s_add_i32 m0, s56, 0x2000
	s_nop 0
	global_load_lds_dwordx4 v[220:221], off
	v_lshl_add_u64 v[220:221], s[34:35], 0, v[134:135]
	s_mov_b32 m0, s0
	s_nop 0
	global_load_lds_dwordx4 v[220:221], off
	s_mov_b32 m0, s1
	s_nop 0
	global_load_lds_dwordx4 v[222:223], off
	s_waitcnt vmcnt(8)
	s_waitcnt lgkmcnt(0)
	s_barrier
; #define PG8_STAGE(bufoff, gbase, voff) do { _Pragma("unroll") for (int _i = 0; _i < 2; ++_i) \
;         __builtin_amdgcn_global_load_lds((const unsigned*)((const char*)(gbase) + (voff)[_i]), (LAS unsigned*)(lds + (bufoff) + ldsw + _i * 8192), 16, 0, 0); } while (0)
; #define PG8_LDA(dst, b, h) do { _Pragma("unroll") for (int m = 0; m < 4; ++m) _Pragma("unroll") for (int k = 0; k < 2; ++k) dst[m][k] = *(const LAS bf16x8*)(lds + PG8_SA(b, h) + aoff + m * 2048 + k * 1024); } while (0)
; #define PG8_LDB(dst, b, h) do { _Pragma("unroll") for (int n = 0; n < 2; ++n) _Pragma("unroll") for (int k = 0; k < 2; ++k) dst[n][k] = *(const LAS bf16x8*)(lds + PG8_SB(b, h) + boff + n * 2048 + k * 1024); } while (0)
; #define PG8_MMA(ai, bj, At, Bt) do { __builtin_amdgcn_s_setprio(1); _Pragma("unroll") for (int m = 0; m < 4; ++m) _Pragma("unroll") for (int n = 0; n < 2; ++n) _Pragma("unroll") for (int k = 0; k < 2; ++k) \
;         acc[ai][bj][m][n] = __builtin_amdgcn_mfma_f32_16x16x32_bf16(Bt[n][k], At[m][k], acc[ai][bj][m][n], 0, 0, 0); __builtin_amdgcn_s_setprio(0); } while (0)
; #define PG8_WAIT_V(n) asm volatile("s_waitcnt vmcnt(" #n ")" ::: "memory")
; #define PG8_WAIT_L(n) asm volatile("s_waitcnt lgkmcnt(" #n ")" ::: "memory")
; #define PG8_BAR __builtin_amdgcn_s_barrier()
; #define PG8_SCHED __builtin_amdgcn_sched_barrier(0)
; template <class Epi, bool ALIGN_EPI>
; __device__ __forceinline__ void gemm_phase(LAS unsigned char* lds, const Gemm g, const StaticOrder& S, const Epi& E) {
;     ...
;             PG8_WAIT_V(8); PG8_WAIT_L(0); PG8_BAR; PG8_MMA(1, 0, At, B0); PG8_MMA(1, 1, At, B1); PG8_BAR; PG8_SCHED;
;             PG8_LDB(B0, 1, 0); PG8_LDB(B1, 1, 1); PG8_SCHED; PG8_LDA(At, 1, 0); PG8_STAGE(PG8_SA(0, 1), a2 + hA, voffA);
;             PG8_WAIT_V(8); PG8_WAIT_L(0); PG8_BAR; PG8_MMA(0, 0, At, B0); PG8_MMA(0, 1, At, B1); PG8_BAR; PG8_SCHED;
	s_setprio 1
	s_waitcnt lgkmcnt(0)
	v_mfma_f32_16x16x32_bf16 v[60:63], v[152:155], v[184:187], v[60:63]
	v_mfma_f32_16x16x32_bf16 v[60:63], v[156:159], v[188:191], v[60:63]
	v_mfma_f32_16x16x32_bf16 v[56:59], v[164:167], v[188:191], v[56:59]
	v_mfma_f32_16x16x32_bf16 v[56:59], v[160:163], v[184:187], v[56:59]
	v_mfma_f32_16x16x32_bf16 v[44:47], v[160:163], v[194:197], v[44:47]
	v_mfma_f32_16x16x32_bf16 v[44:47], v[164:167], v[198:201], v[44:47]
	v_mfma_f32_16x16x32_bf16 v[52:55], v[156:159], v[198:201], v[52:55]
	v_mfma_f32_16x16x32_bf16 v[52:55], v[152:155], v[194:197], v[52:55]
	v_mfma_f32_16x16x32_bf16 v[36:39], v[152:155], v[202:205], v[36:39]
	v_mfma_f32_16x16x32_bf16 v[36:39], v[156:159], v[206:209], v[36:39]
	v_mfma_f32_16x16x32_bf16 v[28:31], v[164:167], v[206:209], v[28:31]
	v_mfma_f32_16x16x32_bf16 v[28:31], v[160:163], v[202:205], v[28:31]
	v_mfma_f32_16x16x32_bf16 v[12:15], v[160:163], v[210:213], v[12:15]
	v_mfma_f32_16x16x32_bf16 v[12:15], v[164:167], v[214:217], v[12:15]
	v_mfma_f32_16x16x32_bf16 v[20:23], v[156:159], v[214:217], v[20:23]
	v_mfma_f32_16x16x32_bf16 v[20:23], v[152:155], v[210:213], v[20:23]
	s_setprio 0
	s_setprio 1
	v_mfma_f32_16x16x32_bf16 v[48:51], v[168:171], v[184:187], v[48:51]
	v_mfma_f32_16x16x32_bf16 v[48:51], v[172:175], v[188:191], v[48:51]
	v_mfma_f32_16x16x32_bf16 v[40:43], v[180:183], v[188:191], v[40:43]
	v_mfma_f32_16x16x32_bf16 v[40:43], v[176:179], v[184:187], v[40:43]
	v_mfma_f32_16x16x32_bf16 v[24:27], v[176:179], v[194:197], v[24:27]
	v_mfma_f32_16x16x32_bf16 v[24:27], v[180:183], v[198:201], v[24:27]
	v_mfma_f32_16x16x32_bf16 v[32:35], v[172:175], v[198:201], v[32:35]
	v_mfma_f32_16x16x32_bf16 v[32:35], v[168:171], v[194:197], v[32:35]
	v_mfma_f32_16x16x32_bf16 v[16:19], v[168:171], v[202:205], v[16:19]
	v_mfma_f32_16x16x32_bf16 v[16:19], v[172:175], v[206:209], v[16:19]
	v_mfma_f32_16x16x32_bf16 v[8:11], v[180:183], v[206:209], v[8:11]
	v_mfma_f32_16x16x32_bf16 v[8:11], v[176:179], v[202:205], v[8:11]
	v_mfma_f32_16x16x32_bf16 v[0:3], v[176:179], v[210:213], v[0:3]
	v_mfma_f32_16x16x32_bf16 v[0:3], v[180:183], v[214:217], v[0:3]
	v_mfma_f32_16x16x32_bf16 v[4:7], v[172:175], v[214:217], v[4:7]
	v_mfma_f32_16x16x32_bf16 v[4:7], v[168:171], v[210:213], v[4:7]
	s_setprio 0
	s_barrier
	s_add_i32 s54, 0, 0x18000
	s_add_i32 s55, 0, 0x1c000
	v_add_u32_e32 v164, s54, v147
	v_add_u32_e32 v180, s55, v147
	ds_read_b128 v[152:155], v164
	ds_read_b128 v[156:159], v164 offset:1024
	ds_read_b128 v[160:163], v164 offset:2048
	ds_read_b128 v[164:167], v164 offset:3072
	ds_read_b128 v[168:171], v180
	ds_read_b128 v[172:175], v180 offset:1024
	ds_read_b128 v[176:179], v180 offset:2048
	ds_read_b128 v[180:183], v180 offset:3072
	s_add_u32 s34, s34, 0x80000
	s_addc_u32 s35, s35, 0
	s_mov_b32 m0, s29
	v_lshl_add_u64 v[224:225], s[34:35], 0, v[134:135]
	ds_read_b128 v[184:187], v151 offset:32768
	ds_read_b128 v[188:191], v151 offset:33792
	ds_read_b128 v[194:197], v151 offset:34816
	ds_read_b128 v[198:201], v151 offset:35840
	ds_read_b128 v[202:205], v151 offset:36864
	ds_read_b128 v[206:209], v151 offset:37888
	ds_read_b128 v[210:213], v151 offset:38912
	ds_read_b128 v[214:217], v151 offset:39936
	global_load_lds_dwordx4 v[224:225], off
	v_lshl_add_u64 v[224:225], s[34:35], 0, v[130:131]
	s_mov_b32 m0, s40
	s_nop 0
	global_load_lds_dwordx4 v[224:225], off
	s_waitcnt vmcnt(8)
	s_waitcnt lgkmcnt(0)
	s_barrier
	s_setprio 1
	s_waitcnt lgkmcnt(0)
	v_mfma_f32_16x16x32_bf16 v[124:127], v[152:155], v[184:187], v[124:127]
	v_mfma_f32_16x16x32_bf16 v[124:127], v[156:159], v[188:191], v[124:127]
	v_mfma_f32_16x16x32_bf16 v[120:123], v[164:167], v[188:191], v[120:123]
	v_mfma_f32_16x16x32_bf16 v[120:123], v[160:163], v[184:187], v[120:123]
	v_mfma_f32_16x16x32_bf16 v[108:111], v[160:163], v[194:197], v[108:111]
	v_mfma_f32_16x16x32_bf16 v[108:111], v[164:167], v[198:201], v[108:111]
	v_mfma_f32_16x16x32_bf16 v[116:119], v[156:159], v[198:201], v[116:119]
	v_mfma_f32_16x16x32_bf16 v[116:119], v[152:155], v[194:197], v[116:119]
	v_mfma_f32_16x16x32_bf16 v[100:103], v[152:155], v[202:205], v[100:103]
	v_mfma_f32_16x16x32_bf16 v[100:103], v[156:159], v[206:209], v[100:103]
	v_mfma_f32_16x16x32_bf16 v[92:95], v[164:167], v[206:209], v[92:95]
	v_mfma_f32_16x16x32_bf16 v[92:95], v[160:163], v[202:205], v[92:95]
	v_mfma_f32_16x16x32_bf16 v[76:79], v[160:163], v[210:213], v[76:79]
	v_mfma_f32_16x16x32_bf16 v[76:79], v[164:167], v[214:217], v[76:79]
	v_mfma_f32_16x16x32_bf16 v[84:87], v[156:159], v[214:217], v[84:87]
	v_mfma_f32_16x16x32_bf16 v[84:87], v[152:155], v[210:213], v[84:87]
	s_setprio 0
	s_setprio 1
	v_mfma_f32_16x16x32_bf16 v[112:115], v[168:171], v[184:187], v[112:115]
	v_mfma_f32_16x16x32_bf16 v[112:115], v[172:175], v[188:191], v[112:115]
	v_mfma_f32_16x16x32_bf16 v[104:107], v[180:183], v[188:191], v[104:107]
	v_mfma_f32_16x16x32_bf16 v[104:107], v[176:179], v[184:187], v[104:107]
	v_mfma_f32_16x16x32_bf16 v[88:91], v[176:179], v[194:197], v[88:91]
	v_mfma_f32_16x16x32_bf16 v[88:91], v[180:183], v[198:201], v[88:91]
	v_mfma_f32_16x16x32_bf16 v[96:99], v[172:175], v[198:201], v[96:99]
	v_mfma_f32_16x16x32_bf16 v[96:99], v[168:171], v[194:197], v[96:99]
	v_mfma_f32_16x16x32_bf16 v[80:83], v[168:171], v[202:205], v[80:83]
	v_mfma_f32_16x16x32_bf16 v[80:83], v[172:175], v[206:209], v[80:83]
	v_mfma_f32_16x16x32_bf16 v[72:75], v[180:183], v[206:209], v[72:75]
	v_mfma_f32_16x16x32_bf16 v[72:75], v[176:179], v[202:205], v[72:75]
	v_mfma_f32_16x16x32_bf16 v[64:67], v[176:179], v[210:213], v[64:67]
	v_mfma_f32_16x16x32_bf16 v[64:67], v[180:183], v[214:217], v[64:67]
	v_mfma_f32_16x16x32_bf16 v[68:71], v[172:175], v[214:217], v[68:71]
	v_mfma_f32_16x16x32_bf16 v[68:71], v[168:171], v[210:213], v[68:71]
	s_setprio 0
	s_barrier
; #define PG8_STAGE(bufoff, gbase, voff) do { _Pragma("unroll") for (int _i = 0; _i < 2; ++_i) \
;         __builtin_amdgcn_global_load_lds((const unsigned*)((const char*)(gbase) + (voff)[_i]), (LAS unsigned*)(lds + (bufoff) + ldsw + _i * 8192), 16, 0, 0); } while (0)
; #define PG8_LDA(dst, b, h) do { _Pragma("unroll") for (int m = 0; m < 4; ++m) _Pragma("unroll") for (int k = 0; k < 2; ++k) dst[m][k] = *(const LAS bf16x8*)(lds + PG8_SA(b, h) + aoff + m * 2048 + k * 1024); } while (0)
; #define PG8_MMA(ai, bj, At, Bt) do { __builtin_amdgcn_s_setprio(1); _Pragma("unroll") for (int m = 0; m < 4; ++m) _Pragma("unroll") for (int n = 0; n < 2; ++n) _Pragma("unroll") for (int k = 0; k < 2; ++k) \
;         acc[ai][bj][m][n] = __builtin_amdgcn_mfma_f32_16x16x32_bf16(Bt[n][k], At[m][k], acc[ai][bj][m][n], 0, 0, 0); __builtin_amdgcn_s_setprio(0); } while (0)
; #define PG8_WAIT_V(n) asm volatile("s_waitcnt vmcnt(" #n ")" ::: "memory")
; #define PG8_WAIT_L(n) asm volatile("s_waitcnt lgkmcnt(" #n ")" ::: "memory")
; #define PG8_BAR __builtin_amdgcn_s_barrier()
; #define PG8_SCHED __builtin_amdgcn_sched_barrier(0)
; template <class Epi, bool ALIGN_EPI>
; __device__ __forceinline__ void gemm_phase(LAS unsigned char* lds, const Gemm g, const StaticOrder& S, const Epi& E) {
;     ...
;             PG8_LDA(At, 1, 1); PG8_STAGE(PG8_SB(1, 0), b3, voffB); PG8_STAGE(PG8_SB(1, 1), b3 + hB, voffB); PG8_STAGE(PG8_SA(1, 0), a3, voffA);
;             PG8_WAIT_V(8); PG8_WAIT_L(0); PG8_BAR; PG8_MMA(1, 0, At, B0); PG8_MMA(1, 1, At, B1); PG8_BAR; PG8_SCHED;
;         }
;         if constexpr (ALIGN_EPI) { if (wr == 0) PG8_BAR; }
	s_add_i32 s34, s54, s2
	v_lshl_add_u64 v[144:145], v[144:145], 0, s[16:17]
	s_mov_b32 m0, s34
	ds_read_b128 v[184:187], v151 offset:49152
	ds_read_b128 v[188:191], v151 offset:50176
	ds_read_b128 v[194:197], v151 offset:51200
	ds_read_b128 v[198:201], v151 offset:52224
	ds_read_b128 v[202:205], v151 offset:53248
	ds_read_b128 v[206:209], v151 offset:54272
	ds_read_b128 v[210:213], v151 offset:55296
	ds_read_b128 v[214:217], v151 offset:56320
	global_load_lds_dwordx4 v[144:145], off
	s_add_i32 m0, s34, 0x2000
	s_add_u32 s30, s30, 0x30080
	v_lshl_add_u64 v[144:145], v[218:219], 0, s[16:17]
	s_addc_u32 s31, s31, 0
	s_add_i32 s34, s55, s2
	global_load_lds_dwordx4 v[144:145], off
	v_lshl_add_u64 v[144:145], s[30:31], 0, v[132:133]
	s_mov_b32 m0, s34
	s_nop 0
	global_load_lds_dwordx4 v[144:145], off
	v_lshl_add_u64 v[144:145], s[30:31], 0, v[128:129]
	s_add_i32 m0, s34, 0x2000
	s_nop 0
	global_load_lds_dwordx4 v[144:145], off
	v_lshl_add_u64 v[144:145], v[220:221], 0, s[16:17]
	s_mov_b32 m0, s42
	s_nop 0
	global_load_lds_dwordx4 v[144:145], off
	v_lshl_add_u64 v[144:145], v[222:223], 0, s[16:17]
	s_mov_b32 m0, s43
	s_nop 0
	global_load_lds_dwordx4 v[144:145], off
	s_waitcnt vmcnt(8)
	s_waitcnt lgkmcnt(0)
	s_barrier
	s_setprio 1
	s_waitcnt lgkmcnt(0)
	v_mfma_f32_16x16x32_bf16 v[60:63], v[152:155], v[184:187], v[60:63]
	v_mfma_f32_16x16x32_bf16 v[60:63], v[156:159], v[188:191], v[60:63]
	v_mfma_f32_16x16x32_bf16 v[56:59], v[164:167], v[188:191], v[56:59]
	v_mfma_f32_16x16x32_bf16 v[56:59], v[160:163], v[184:187], v[56:59]
	v_mfma_f32_16x16x32_bf16 v[44:47], v[160:163], v[194:197], v[44:47]
	v_mfma_f32_16x16x32_bf16 v[44:47], v[164:167], v[198:201], v[44:47]
	v_mfma_f32_16x16x32_bf16 v[52:55], v[156:159], v[198:201], v[52:55]
	v_mfma_f32_16x16x32_bf16 v[52:55], v[152:155], v[194:197], v[52:55]
	v_mfma_f32_16x16x32_bf16 v[36:39], v[152:155], v[202:205], v[36:39]
	v_mfma_f32_16x16x32_bf16 v[36:39], v[156:159], v[206:209], v[36:39]
	v_mfma_f32_16x16x32_bf16 v[28:31], v[164:167], v[206:209], v[28:31]
	v_mfma_f32_16x16x32_bf16 v[28:31], v[160:163], v[202:205], v[28:31]
	v_mfma_f32_16x16x32_bf16 v[12:15], v[160:163], v[210:213], v[12:15]
	v_mfma_f32_16x16x32_bf16 v[12:15], v[164:167], v[214:217], v[12:15]
	v_mfma_f32_16x16x32_bf16 v[20:23], v[156:159], v[214:217], v[20:23]
	v_mfma_f32_16x16x32_bf16 v[20:23], v[152:155], v[210:213], v[20:23]
	s_setprio 0
	s_setprio 1
	v_mfma_f32_16x16x32_bf16 v[48:51], v[168:171], v[184:187], v[48:51]
	v_mfma_f32_16x16x32_bf16 v[48:51], v[172:175], v[188:191], v[48:51]
	v_mfma_f32_16x16x32_bf16 v[40:43], v[180:183], v[188:191], v[40:43]
	v_mfma_f32_16x16x32_bf16 v[40:43], v[176:179], v[184:187], v[40:43]
	v_mfma_f32_16x16x32_bf16 v[24:27], v[176:179], v[194:197], v[24:27]
	v_mfma_f32_16x16x32_bf16 v[24:27], v[180:183], v[198:201], v[24:27]
	v_mfma_f32_16x16x32_bf16 v[32:35], v[172:175], v[198:201], v[32:35]
	v_mfma_f32_16x16x32_bf16 v[32:35], v[168:171], v[194:197], v[32:35]
	v_mfma_f32_16x16x32_bf16 v[16:19], v[168:171], v[202:205], v[16:19]
	v_mfma_f32_16x16x32_bf16 v[16:19], v[172:175], v[206:209], v[16:19]
	v_mfma_f32_16x16x32_bf16 v[8:11], v[180:183], v[206:209], v[8:11]
	v_mfma_f32_16x16x32_bf16 v[8:11], v[176:179], v[202:205], v[8:11]
	v_mfma_f32_16x16x32_bf16 v[0:3], v[176:179], v[210:213], v[0:3]
	v_mfma_f32_16x16x32_bf16 v[0:3], v[180:183], v[214:217], v[0:3]
	v_mfma_f32_16x16x32_bf16 v[4:7], v[172:175], v[214:217], v[4:7]
	v_mfma_f32_16x16x32_bf16 v[4:7], v[168:171], v[210:213], v[4:7]
	s_setprio 0
	s_barrier
	s_add_i32 s53, s53, 2
	s_add_u32 s6, s6, 0x100
	s_addc_u32 s7, s7, 0
	s_add_u32 s51, s51, 0x100
	s_addc_u32 s52, s52, 0
	s_cmp_gt_u32 s53, 9
	s_cbranch_scc0 .LBB0_403
	s_and_b64 vcc, exec, s[18:19]
	s_cbranch_vccz .LBB0_406
	s_barrier

; #define PG8_STAGE(bufoff, gbase, voff) do { _Pragma("unroll") for (int _i = 0; _i < 2; ++_i) \
;         __builtin_amdgcn_global_load_lds((const unsigned*)((const char*)(gbase) + (voff)[_i]), (LAS unsigned*)(lds + (bufoff) + ldsw + _i * 8192), 16, 0, 0); } while (0)
; #define PG8_LDA(dst, b, h) do { _Pragma("unroll") for (int m = 0; m < 4; ++m) _Pragma("unroll") for (int k = 0; k < 2; ++k) dst[m][k] = *(const LAS bf16x8*)(lds + PG8_SA(b, h) + aoff + m * 2048 + k * 1024); } while (0)
; #define PG8_LDB(dst, b, h) do { _Pragma("unroll") for (int n = 0; n < 2; ++n) _Pragma("unroll") for (int k = 0; k < 2; ++k) dst[n][k] = *(const LAS bf16x8*)(lds + PG8_SB(b, h) + boff + n * 2048 + k * 1024); } while (0)
; #define PG8_MMA(ai, bj, At, Bt) do { __builtin_amdgcn_s_setprio(1); _Pragma("unroll") for (int m = 0; m < 4; ++m) _Pragma("unroll") for (int n = 0; n < 2; ++n) _Pragma("unroll") for (int k = 0; k < 2; ++k) \
;         acc[ai][bj][m][n] = __builtin_amdgcn_mfma_f32_16x16x32_bf16(Bt[n][k], At[m][k], acc[ai][bj][m][n], 0, 0, 0); __builtin_amdgcn_s_setprio(0); } while (0)
; #define PG8_WAIT_V(n) asm volatile("s_waitcnt vmcnt(" #n ")" ::: "memory")
; #define PG8_WAIT_L(n) asm volatile("s_waitcnt lgkmcnt(" #n ")" ::: "memory")
; #define PG8_BAR __builtin_amdgcn_s_barrier()
; #define PG8_SCHED __builtin_amdgcn_sched_barrier(0)
; template <class Epi, bool ALIGN_EPI>
; __device__ __forceinline__ void gemm_phase(LAS unsigned char* lds, const Gemm g, const StaticOrder& S, const Epi& E) {
;     ...
;             const char* a1 = cA + (size_t)(t + 1) * kstep;
;             const char* a2 = last ? nA : cA + (size_t)(t + 2) * kstep; const char* b2 = last ? nB : cB + (size_t)(t + 2) * kstep;
;             const char* a3 = a2 + kstep; const char* b3 = b2 + kstep;
;             PG8_LDB(B0, 0, 0); PG8_LDB(B1, 0, 1); PG8_SCHED; PG8_LDA(At, 0, 0); PG8_STAGE(PG8_SA(1, 1), a1 + hA, voffA);
;             PG8_WAIT_V(8); PG8_WAIT_L(0); PG8_BAR; PG8_MMA(0, 0, At, B0); PG8_MMA(0, 1, At, B1); PG8_BAR; PG8_SCHED;
;             PG8_LDA(At, 0, 1); PG8_STAGE(PG8_SB(0, 0), b2, voffB); PG8_STAGE(PG8_SB(0, 1), b2 + hB, voffB); PG8_STAGE(PG8_SA(0, 0), a2, voffA);
;             PG8_WAIT_V(8); PG8_WAIT_L(0); PG8_BAR; PG8_MMA(1, 0, At, B0); PG8_MMA(1, 1, At, B1); PG8_BAR; PG8_SCHED;
.LBB0_419:
	ds_read_b128 v[148:151], v145
	ds_read_b128 v[152:155], v145 offset:1024
	ds_read_b128 v[156:159], v145 offset:2048
	ds_read_b128 v[160:163], v145 offset:3072
	ds_read_b128 v[164:167], v146
	ds_read_b128 v[168:171], v146 offset:1024
	ds_read_b128 v[172:175], v146 offset:2048
	ds_read_b128 v[176:179], v146 offset:3072
	s_add_u32 s30, s28, 0xfff80080
	s_addc_u32 s31, s29, -1
	s_cmp_eq_u32 s53, 28
	s_cselect_b32 s35, s19, s31
	s_cselect_b32 s34, s49, s30
	s_cselect_b32 s31, s17, s52
	s_cselect_b32 s30, s50, s51
	v_lshl_add_u64 v[140:141], s[28:29], 0, v[136:137]
	s_add_i32 m0, s27, 0xc000
	ds_read_b128 v[180:183], v147
	ds_read_b128 v[184:187], v147 offset:1024
	ds_read_b128 v[188:191], v147 offset:2048
	ds_read_b128 v[194:197], v147 offset:3072
	ds_read_b128 v[198:201], v147 offset:4096
	ds_read_b128 v[202:205], v147 offset:5120
	ds_read_b128 v[206:209], v147 offset:6144
	ds_read_b128 v[210:213], v147 offset:7168
	global_load_lds_dwordx4 v[140:141], off
	v_lshl_add_u64 v[140:141], s[28:29], 0, v[138:139]
	s_add_i32 m0, s27, 0xe000
	s_nop 0
	global_load_lds_dwordx4 v[140:141], off
	s_waitcnt vmcnt(8)
	s_waitcnt lgkmcnt(0)
	s_barrier
	s_setprio 1
	s_waitcnt lgkmcnt(0)
	v_mfma_f32_16x16x32_bf16 v[124:127], v[148:151], v[180:183], v[124:127]
	v_mfma_f32_16x16x32_bf16 v[124:127], v[152:155], v[184:187], v[124:127]
	v_mfma_f32_16x16x32_bf16 v[120:123], v[160:163], v[184:187], v[120:123]
	v_mfma_f32_16x16x32_bf16 v[120:123], v[156:159], v[180:183], v[120:123]
	v_mfma_f32_16x16x32_bf16 v[108:111], v[156:159], v[188:191], v[108:111]
	v_mfma_f32_16x16x32_bf16 v[108:111], v[160:163], v[194:197], v[108:111]
	v_mfma_f32_16x16x32_bf16 v[116:119], v[152:155], v[194:197], v[116:119]
	v_mfma_f32_16x16x32_bf16 v[116:119], v[148:151], v[188:191], v[116:119]
	v_mfma_f32_16x16x32_bf16 v[100:103], v[148:151], v[198:201], v[100:103]
	v_mfma_f32_16x16x32_bf16 v[100:103], v[152:155], v[202:205], v[100:103]
	v_mfma_f32_16x16x32_bf16 v[92:95], v[160:163], v[202:205], v[92:95]
	v_mfma_f32_16x16x32_bf16 v[92:95], v[156:159], v[198:201], v[92:95]
	v_mfma_f32_16x16x32_bf16 v[76:79], v[156:159], v[206:209], v[76:79]
	v_mfma_f32_16x16x32_bf16 v[76:79], v[160:163], v[210:213], v[76:79]
	v_mfma_f32_16x16x32_bf16 v[84:87], v[152:155], v[210:213], v[84:87]
	v_mfma_f32_16x16x32_bf16 v[84:87], v[148:151], v[206:209], v[84:87]
	s_setprio 0
	s_setprio 1
	v_mfma_f32_16x16x32_bf16 v[112:115], v[164:167], v[180:183], v[112:115]
	v_mfma_f32_16x16x32_bf16 v[112:115], v[168:171], v[184:187], v[112:115]
	v_mfma_f32_16x16x32_bf16 v[104:107], v[176:179], v[184:187], v[104:107]
	v_mfma_f32_16x16x32_bf16 v[104:107], v[172:175], v[180:183], v[104:107]
	v_mfma_f32_16x16x32_bf16 v[88:91], v[172:175], v[188:191], v[88:91]
	v_mfma_f32_16x16x32_bf16 v[88:91], v[176:179], v[194:197], v[88:91]
	v_mfma_f32_16x16x32_bf16 v[96:99], v[168:171], v[194:197], v[96:99]
	v_mfma_f32_16x16x32_bf16 v[96:99], v[164:167], v[188:191], v[96:99]
	v_mfma_f32_16x16x32_bf16 v[80:83], v[164:167], v[198:201], v[80:83]
	v_mfma_f32_16x16x32_bf16 v[80:83], v[168:171], v[202:205], v[80:83]
	v_mfma_f32_16x16x32_bf16 v[72:75], v[176:179], v[202:205], v[72:75]
	v_mfma_f32_16x16x32_bf16 v[72:75], v[172:175], v[198:201], v[72:75]
	v_mfma_f32_16x16x32_bf16 v[64:67], v[172:175], v[206:209], v[64:67]
	v_mfma_f32_16x16x32_bf16 v[64:67], v[176:179], v[210:213], v[64:67]
	v_mfma_f32_16x16x32_bf16 v[68:71], v[168:171], v[210:213], v[68:71]
	v_mfma_f32_16x16x32_bf16 v[68:71], v[164:167], v[206:209], v[68:71]
	s_setprio 0
	s_barrier
	s_add_i32 s54, s45, s1
	v_lshl_add_u64 v[140:141], s[30:31], 0, v[132:133]
	s_mov_b32 m0, s54
	ds_read_b128 v[180:183], v147 offset:16384
	ds_read_b128 v[184:187], v147 offset:17408
	ds_read_b128 v[188:191], v147 offset:18432
	ds_read_b128 v[194:197], v147 offset:19456
	ds_read_b128 v[198:201], v147 offset:20480
	ds_read_b128 v[202:205], v147 offset:21504
	ds_read_b128 v[206:209], v147 offset:22528
	ds_read_b128 v[210:213], v147 offset:23552
	global_load_lds_dwordx4 v[140:141], off
	s_add_i32 m0, s54, 0x2000
	s_add_u32 s54, s30, 0x80000
	v_lshl_add_u64 v[214:215], s[30:31], 0, v[128:129]
	s_addc_u32 s55, s31, 0
	s_add_i32 s56, s46, s1
	global_load_lds_dwordx4 v[214:215], off
	v_lshl_add_u64 v[216:217], s[54:55], 0, v[132:133]
	s_mov_b32 m0, s56
	v_lshl_add_u64 v[218:219], s[34:35], 0, v[130:131]
	global_load_lds_dwordx4 v[216:217], off
	v_lshl_add_u64 v[216:217], s[54:55], 0, v[128:129]
	s_add_i32 m0, s56, 0x2000
	s_nop 0
	global_load_lds_dwordx4 v[216:217], off
	v_lshl_add_u64 v[216:217], s[34:35], 0, v[134:135]
	s_mov_b32 m0, s27
	s_nop 0
	global_load_lds_dwordx4 v[216:217], off
	s_mov_b32 m0, s39
	s_nop 0
	global_load_lds_dwordx4 v[218:219], off
	s_waitcnt vmcnt(8)
	s_waitcnt lgkmcnt(0)
	s_barrier
; #define PG8_STAGE(bufoff, gbase, voff) do { _Pragma("unroll") for (int _i = 0; _i < 2; ++_i) \
;         __builtin_amdgcn_global_load_lds((const unsigned*)((const char*)(gbase) + (voff)[_i]), (LAS unsigned*)(lds + (bufoff) + ldsw + _i * 8192), 16, 0, 0); } while (0)
; #define PG8_LDA(dst, b, h) do { _Pragma("unroll") for (int m = 0; m < 4; ++m) _Pragma("unroll") for (int k = 0; k < 2; ++k) dst[m][k] = *(const LAS bf16x8*)(lds + PG8_SA(b, h) + aoff + m * 2048 + k * 1024); } while (0)
; #define PG8_LDB(dst, b, h) do { _Pragma("unroll") for (int n = 0; n < 2; ++n) _Pragma("unroll") for (int k = 0; k < 2; ++k) dst[n][k] = *(const LAS bf16x8*)(lds + PG8_SB(b, h) + boff + n * 2048 + k * 1024); } while (0)
; #define PG8_MMA(ai, bj, At, Bt) do { __builtin_amdgcn_s_setprio(1); _Pragma("unroll") for (int m = 0; m < 4; ++m) _Pragma("unroll") for (int n = 0; n < 2; ++n) _Pragma("unroll") for (int k = 0; k < 2; ++k) \
;         acc[ai][bj][m][n] = __builtin_amdgcn_mfma_f32_16x16x32_bf16(Bt[n][k], At[m][k], acc[ai][bj][m][n], 0, 0, 0); __builtin_amdgcn_s_setprio(0); } while (0)
; #define PG8_WAIT_V(n) asm volatile("s_waitcnt vmcnt(" #n ")" ::: "memory")
; #define PG8_WAIT_L(n) asm volatile("s_waitcnt lgkmcnt(" #n ")" ::: "memory")
; #define PG8_BAR __builtin_amdgcn_s_barrier()
; #define PG8_SCHED __builtin_amdgcn_sched_barrier(0)
; template <class Epi, bool ALIGN_EPI>
; __device__ __forceinline__ void gemm_phase(LAS unsigned char* lds, const Gemm g, const StaticOrder& S, const Epi& E) {
;     ...
;             PG8_WAIT_V(8); PG8_WAIT_L(0); PG8_BAR; PG8_MMA(1, 0, At, B0); PG8_MMA(1, 1, At, B1); PG8_BAR; PG8_SCHED;
;             PG8_LDB(B0, 1, 0); PG8_LDB(B1, 1, 1); PG8_SCHED; PG8_LDA(At, 1, 0); PG8_STAGE(PG8_SA(0, 1), a2 + hA, voffA);
;             PG8_WAIT_V(8); PG8_WAIT_L(0); PG8_BAR; PG8_MMA(0, 0, At, B0); PG8_MMA(0, 1, At, B1); PG8_BAR; PG8_SCHED;
	s_setprio 1
	s_waitcnt lgkmcnt(0)
	v_mfma_f32_16x16x32_bf16 v[60:63], v[148:151], v[180:183], v[60:63]
	v_mfma_f32_16x16x32_bf16 v[60:63], v[152:155], v[184:187], v[60:63]
	v_mfma_f32_16x16x32_bf16 v[56:59], v[160:163], v[184:187], v[56:59]
	v_mfma_f32_16x16x32_bf16 v[56:59], v[156:159], v[180:183], v[56:59]
	v_mfma_f32_16x16x32_bf16 v[44:47], v[156:159], v[188:191], v[44:47]
	v_mfma_f32_16x16x32_bf16 v[44:47], v[160:163], v[194:197], v[44:47]
	v_mfma_f32_16x16x32_bf16 v[52:55], v[152:155], v[194:197], v[52:55]
	v_mfma_f32_16x16x32_bf16 v[52:55], v[148:151], v[188:191], v[52:55]
	v_mfma_f32_16x16x32_bf16 v[36:39], v[148:151], v[198:201], v[36:39]
	v_mfma_f32_16x16x32_bf16 v[36:39], v[152:155], v[202:205], v[36:39]
	v_mfma_f32_16x16x32_bf16 v[28:31], v[160:163], v[202:205], v[28:31]
	v_mfma_f32_16x16x32_bf16 v[28:31], v[156:159], v[198:201], v[28:31]
	v_mfma_f32_16x16x32_bf16 v[12:15], v[156:159], v[206:209], v[12:15]
	v_mfma_f32_16x16x32_bf16 v[12:15], v[160:163], v[210:213], v[12:15]
	v_mfma_f32_16x16x32_bf16 v[20:23], v[152:155], v[210:213], v[20:23]
	v_mfma_f32_16x16x32_bf16 v[20:23], v[148:151], v[206:209], v[20:23]
	s_setprio 0
	s_setprio 1
	v_mfma_f32_16x16x32_bf16 v[48:51], v[164:167], v[180:183], v[48:51]
	v_mfma_f32_16x16x32_bf16 v[48:51], v[168:171], v[184:187], v[48:51]
	v_mfma_f32_16x16x32_bf16 v[40:43], v[176:179], v[184:187], v[40:43]
	v_mfma_f32_16x16x32_bf16 v[40:43], v[172:175], v[180:183], v[40:43]
	v_mfma_f32_16x16x32_bf16 v[24:27], v[172:175], v[188:191], v[24:27]
	v_mfma_f32_16x16x32_bf16 v[24:27], v[176:179], v[194:197], v[24:27]
	v_mfma_f32_16x16x32_bf16 v[32:35], v[168:171], v[194:197], v[32:35]
	v_mfma_f32_16x16x32_bf16 v[32:35], v[164:167], v[188:191], v[32:35]
	v_mfma_f32_16x16x32_bf16 v[16:19], v[164:167], v[198:201], v[16:19]
	v_mfma_f32_16x16x32_bf16 v[16:19], v[168:171], v[202:205], v[16:19]
	v_mfma_f32_16x16x32_bf16 v[8:11], v[176:179], v[202:205], v[8:11]
	v_mfma_f32_16x16x32_bf16 v[8:11], v[172:175], v[198:201], v[8:11]
	v_mfma_f32_16x16x32_bf16 v[0:3], v[172:175], v[206:209], v[0:3]
	v_mfma_f32_16x16x32_bf16 v[0:3], v[176:179], v[210:213], v[0:3]
	v_mfma_f32_16x16x32_bf16 v[4:7], v[168:171], v[210:213], v[4:7]
	v_mfma_f32_16x16x32_bf16 v[4:7], v[164:167], v[206:209], v[4:7]
	s_setprio 0
	s_barrier
	s_add_i32 s54, 0, 0x18000
	s_add_i32 s55, 0, 0x1c000
	v_add_u32_e32 v160, s54, v143
	v_add_u32_e32 v176, s55, v143
	ds_read_b128 v[148:151], v160
	ds_read_b128 v[152:155], v160 offset:1024
	ds_read_b128 v[156:159], v160 offset:2048
	ds_read_b128 v[160:163], v160 offset:3072
	ds_read_b128 v[164:167], v176
	ds_read_b128 v[168:171], v176 offset:1024
	ds_read_b128 v[172:175], v176 offset:2048
	ds_read_b128 v[176:179], v176 offset:3072
	s_add_u32 s34, s34, 0x80000
	s_addc_u32 s35, s35, 0
	s_mov_b32 m0, s40
	v_lshl_add_u64 v[220:221], s[34:35], 0, v[134:135]
	ds_read_b128 v[180:183], v147 offset:32768
	ds_read_b128 v[184:187], v147 offset:33792
	ds_read_b128 v[188:191], v147 offset:34816
	ds_read_b128 v[194:197], v147 offset:35840
	ds_read_b128 v[198:201], v147 offset:36864
	ds_read_b128 v[202:205], v147 offset:37888
	ds_read_b128 v[206:209], v147 offset:38912
	ds_read_b128 v[210:213], v147 offset:39936
	global_load_lds_dwordx4 v[220:221], off
	v_lshl_add_u64 v[220:221], s[34:35], 0, v[130:131]
	s_mov_b32 m0, s41
	s_nop 0
	global_load_lds_dwordx4 v[220:221], off
	s_waitcnt vmcnt(8)
	s_waitcnt lgkmcnt(0)
	s_barrier
	s_setprio 1
	s_waitcnt lgkmcnt(0)
	v_mfma_f32_16x16x32_bf16 v[124:127], v[148:151], v[180:183], v[124:127]
	v_mfma_f32_16x16x32_bf16 v[124:127], v[152:155], v[184:187], v[124:127]
	v_mfma_f32_16x16x32_bf16 v[120:123], v[160:163], v[184:187], v[120:123]
	v_mfma_f32_16x16x32_bf16 v[120:123], v[156:159], v[180:183], v[120:123]
	v_mfma_f32_16x16x32_bf16 v[108:111], v[156:159], v[188:191], v[108:111]
	v_mfma_f32_16x16x32_bf16 v[108:111], v[160:163], v[194:197], v[108:111]
	v_mfma_f32_16x16x32_bf16 v[116:119], v[152:155], v[194:197], v[116:119]
	v_mfma_f32_16x16x32_bf16 v[116:119], v[148:151], v[188:191], v[116:119]
	v_mfma_f32_16x16x32_bf16 v[100:103], v[148:151], v[198:201], v[100:103]
	v_mfma_f32_16x16x32_bf16 v[100:103], v[152:155], v[202:205], v[100:103]
	v_mfma_f32_16x16x32_bf16 v[92:95], v[160:163], v[202:205], v[92:95]
	v_mfma_f32_16x16x32_bf16 v[92:95], v[156:159], v[198:201], v[92:95]
	v_mfma_f32_16x16x32_bf16 v[76:79], v[156:159], v[206:209], v[76:79]
	v_mfma_f32_16x16x32_bf16 v[76:79], v[160:163], v[210:213], v[76:79]
	v_mfma_f32_16x16x32_bf16 v[84:87], v[152:155], v[210:213], v[84:87]
	v_mfma_f32_16x16x32_bf16 v[84:87], v[148:151], v[206:209], v[84:87]
	s_setprio 0
	s_setprio 1
	v_mfma_f32_16x16x32_bf16 v[112:115], v[164:167], v[180:183], v[112:115]
	v_mfma_f32_16x16x32_bf16 v[112:115], v[168:171], v[184:187], v[112:115]
	v_mfma_f32_16x16x32_bf16 v[104:107], v[176:179], v[184:187], v[104:107]
	v_mfma_f32_16x16x32_bf16 v[104:107], v[172:175], v[180:183], v[104:107]
	v_mfma_f32_16x16x32_bf16 v[88:91], v[172:175], v[188:191], v[88:91]
	v_mfma_f32_16x16x32_bf16 v[88:91], v[176:179], v[194:197], v[88:91]
	v_mfma_f32_16x16x32_bf16 v[96:99], v[168:171], v[194:197], v[96:99]
	v_mfma_f32_16x16x32_bf16 v[96:99], v[164:167], v[188:191], v[96:99]
	v_mfma_f32_16x16x32_bf16 v[80:83], v[164:167], v[198:201], v[80:83]
	v_mfma_f32_16x16x32_bf16 v[80:83], v[168:171], v[202:205], v[80:83]
	v_mfma_f32_16x16x32_bf16 v[72:75], v[176:179], v[202:205], v[72:75]
	v_mfma_f32_16x16x32_bf16 v[72:75], v[172:175], v[198:201], v[72:75]
	v_mfma_f32_16x16x32_bf16 v[64:67], v[172:175], v[206:209], v[64:67]
	v_mfma_f32_16x16x32_bf16 v[64:67], v[176:179], v[210:213], v[64:67]
	v_mfma_f32_16x16x32_bf16 v[68:71], v[168:171], v[210:213], v[68:71]
	v_mfma_f32_16x16x32_bf16 v[68:71], v[164:167], v[206:209], v[68:71]
	s_setprio 0
	s_barrier
; #define PG8_STAGE(bufoff, gbase, voff) do { _Pragma("unroll") for (int _i = 0; _i < 2; ++_i) \
;         __builtin_amdgcn_global_load_lds((const unsigned*)((const char*)(gbase) + (voff)[_i]), (LAS unsigned*)(lds + (bufoff) + ldsw + _i * 8192), 16, 0, 0); } while (0)
; #define PG8_LDA(dst, b, h) do { _Pragma("unroll") for (int m = 0; m < 4; ++m) _Pragma("unroll") for (int k = 0; k < 2; ++k) dst[m][k] = *(const LAS bf16x8*)(lds + PG8_SA(b, h) + aoff + m * 2048 + k * 1024); } while (0)
; #define PG8_MMA(ai, bj, At, Bt) do { __builtin_amdgcn_s_setprio(1); _Pragma("unroll") for (int m = 0; m < 4; ++m) _Pragma("unroll") for (int n = 0; n < 2; ++n) _Pragma("unroll") for (int k = 0; k < 2; ++k) \
;         acc[ai][bj][m][n] = __builtin_amdgcn_mfma_f32_16x16x32_bf16(Bt[n][k], At[m][k], acc[ai][bj][m][n], 0, 0, 0); __builtin_amdgcn_s_setprio(0); } while (0)
; #define PG8_WAIT_V(n) asm volatile("s_waitcnt vmcnt(" #n ")" ::: "memory")
; #define PG8_WAIT_L(n) asm volatile("s_waitcnt lgkmcnt(" #n ")" ::: "memory")
; #define PG8_BAR __builtin_amdgcn_s_barrier()
; #define PG8_SCHED __builtin_amdgcn_sched_barrier(0)
; template <class Epi, bool ALIGN_EPI>
; __device__ __forceinline__ void gemm_phase(LAS unsigned char* lds, const Gemm g, const StaticOrder& S, const Epi& E) {
;     ...
;             PG8_LDA(At, 1, 1); PG8_STAGE(PG8_SB(1, 0), b3, voffB); PG8_STAGE(PG8_SB(1, 1), b3 + hB, voffB); PG8_STAGE(PG8_SA(1, 0), a3, voffA);
;             PG8_WAIT_V(8); PG8_WAIT_L(0); PG8_BAR; PG8_MMA(1, 0, At, B0); PG8_MMA(1, 1, At, B1); PG8_BAR; PG8_SCHED;
;         }
;         if constexpr (ALIGN_EPI) { if (wr == 0) PG8_BAR; }
	s_add_i32 s34, s54, s1
	v_lshl_add_u64 v[140:141], v[140:141], 0, s[10:11]
	s_mov_b32 m0, s34
	ds_read_b128 v[180:183], v147 offset:49152
	ds_read_b128 v[184:187], v147 offset:50176
	ds_read_b128 v[188:191], v147 offset:51200
	ds_read_b128 v[194:197], v147 offset:52224
	ds_read_b128 v[198:201], v147 offset:53248
	ds_read_b128 v[202:205], v147 offset:54272
	ds_read_b128 v[206:209], v147 offset:55296
	ds_read_b128 v[210:213], v147 offset:56320
	global_load_lds_dwordx4 v[140:141], off
	s_add_i32 m0, s34, 0x2000
	s_add_u32 s30, s30, 0x80080
	v_lshl_add_u64 v[140:141], v[214:215], 0, s[10:11]
	s_addc_u32 s31, s31, 0
	s_add_i32 s34, s55, s1
	global_load_lds_dwordx4 v[140:141], off
	v_lshl_add_u64 v[140:141], s[30:31], 0, v[132:133]
	s_mov_b32 m0, s34
	s_nop 0
	global_load_lds_dwordx4 v[140:141], off
	v_lshl_add_u64 v[140:141], s[30:31], 0, v[128:129]
	s_add_i32 m0, s34, 0x2000
	s_nop 0
	global_load_lds_dwordx4 v[140:141], off
	v_lshl_add_u64 v[140:141], v[216:217], 0, s[10:11]
	s_mov_b32 m0, s42
	s_nop 0
	global_load_lds_dwordx4 v[140:141], off
	v_lshl_add_u64 v[140:141], v[218:219], 0, s[10:11]
	s_mov_b32 m0, s43
	s_nop 0
	global_load_lds_dwordx4 v[140:141], off
	s_waitcnt vmcnt(8)
	s_waitcnt lgkmcnt(0)
	s_barrier
	s_setprio 1
	s_waitcnt lgkmcnt(0)
	v_mfma_f32_16x16x32_bf16 v[60:63], v[148:151], v[180:183], v[60:63]
	v_mfma_f32_16x16x32_bf16 v[60:63], v[152:155], v[184:187], v[60:63]
	v_mfma_f32_16x16x32_bf16 v[56:59], v[160:163], v[184:187], v[56:59]
	v_mfma_f32_16x16x32_bf16 v[56:59], v[156:159], v[180:183], v[56:59]
	v_mfma_f32_16x16x32_bf16 v[44:47], v[156:159], v[188:191], v[44:47]
	v_mfma_f32_16x16x32_bf16 v[44:47], v[160:163], v[194:197], v[44:47]
	v_mfma_f32_16x16x32_bf16 v[52:55], v[152:155], v[194:197], v[52:55]
	v_mfma_f32_16x16x32_bf16 v[52:55], v[148:151], v[188:191], v[52:55]
	v_mfma_f32_16x16x32_bf16 v[36:39], v[148:151], v[198:201], v[36:39]
	v_mfma_f32_16x16x32_bf16 v[36:39], v[152:155], v[202:205], v[36:39]
	v_mfma_f32_16x16x32_bf16 v[28:31], v[160:163], v[202:205], v[28:31]
	v_mfma_f32_16x16x32_bf16 v[28:31], v[156:159], v[198:201], v[28:31]
	v_mfma_f32_16x16x32_bf16 v[12:15], v[156:159], v[206:209], v[12:15]
	v_mfma_f32_16x16x32_bf16 v[12:15], v[160:163], v[210:213], v[12:15]
	v_mfma_f32_16x16x32_bf16 v[20:23], v[152:155], v[210:213], v[20:23]
	v_mfma_f32_16x16x32_bf16 v[20:23], v[148:151], v[206:209], v[20:23]
	s_setprio 0
	s_setprio 1
	v_mfma_f32_16x16x32_bf16 v[48:51], v[164:167], v[180:183], v[48:51]
	v_mfma_f32_16x16x32_bf16 v[48:51], v[168:171], v[184:187], v[48:51]
	v_mfma_f32_16x16x32_bf16 v[40:43], v[176:179], v[184:187], v[40:43]
	v_mfma_f32_16x16x32_bf16 v[40:43], v[172:175], v[180:183], v[40:43]
	v_mfma_f32_16x16x32_bf16 v[24:27], v[172:175], v[188:191], v[24:27]
	v_mfma_f32_16x16x32_bf16 v[24:27], v[176:179], v[194:197], v[24:27]
	v_mfma_f32_16x16x32_bf16 v[32:35], v[168:171], v[194:197], v[32:35]
	v_mfma_f32_16x16x32_bf16 v[32:35], v[164:167], v[188:191], v[32:35]
	v_mfma_f32_16x16x32_bf16 v[16:19], v[164:167], v[198:201], v[16:19]
	v_mfma_f32_16x16x32_bf16 v[16:19], v[168:171], v[202:205], v[16:19]
	v_mfma_f32_16x16x32_bf16 v[8:11], v[176:179], v[202:205], v[8:11]
	v_mfma_f32_16x16x32_bf16 v[8:11], v[172:175], v[198:201], v[8:11]
	v_mfma_f32_16x16x32_bf16 v[0:3], v[172:175], v[206:209], v[0:3]
	v_mfma_f32_16x16x32_bf16 v[0:3], v[176:179], v[210:213], v[0:3]
	v_mfma_f32_16x16x32_bf16 v[4:7], v[168:171], v[210:213], v[4:7]
	v_mfma_f32_16x16x32_bf16 v[4:7], v[164:167], v[206:209], v[4:7]
	s_setprio 0
	s_barrier
	s_add_i32 s53, s53, 2
	s_add_u32 s28, s28, 0x100
	s_addc_u32 s29, s29, 0
	s_add_u32 s51, s51, 0x100
	s_addc_u32 s52, s52, 0
	s_cmp_gt_u32 s53, 29
	s_cbranch_scc0 .LBB0_419
	s_and_b64 vcc, exec, s[14:15]
	s_cbranch_vccz .LBB0_422
	s_barrier

; #define PG8_STAGE(bufoff, gbase, voff) do { _Pragma("unroll") for (int _i = 0; _i < 2; ++_i) \
;         __builtin_amdgcn_global_load_lds((const unsigned*)((const char*)(gbase) + (voff)[_i]), (LAS unsigned*)(lds + (bufoff) + ldsw + _i * 8192), 16, 0, 0); } while (0)
; #define PG8_LDA(dst, b, h) do { _Pragma("unroll") for (int m = 0; m < 4; ++m) _Pragma("unroll") for (int k = 0; k < 2; ++k) dst[m][k] = *(const LAS bf16x8*)(lds + PG8_SA(b, h) + aoff + m * 2048 + k * 1024); } while (0)
; #define PG8_LDB(dst, b, h) do { _Pragma("unroll") for (int n = 0; n < 2; ++n) _Pragma("unroll") for (int k = 0; k < 2; ++k) dst[n][k] = *(const LAS bf16x8*)(lds + PG8_SB(b, h) + boff + n * 2048 + k * 1024); } while (0)
; #define PG8_MMA(ai, bj, At, Bt) do { __builtin_amdgcn_s_setprio(1); _Pragma("unroll") for (int m = 0; m < 4; ++m) _Pragma("unroll") for (int n = 0; n < 2; ++n) _Pragma("unroll") for (int k = 0; k < 2; ++k) \
;         acc[ai][bj][m][n] = __builtin_amdgcn_mfma_f32_16x16x32_bf16(Bt[n][k], At[m][k], acc[ai][bj][m][n], 0, 0, 0); __builtin_amdgcn_s_setprio(0); } while (0)
; #define PG8_WAIT_V(n) asm volatile("s_waitcnt vmcnt(" #n ")" ::: "memory")
; #define PG8_WAIT_L(n) asm volatile("s_waitcnt lgkmcnt(" #n ")" ::: "memory")
; #define PG8_BAR __builtin_amdgcn_s_barrier()
; #define PG8_SCHED __builtin_amdgcn_sched_barrier(0)
; template <class Epi, bool ALIGN_EPI>
; __device__ __forceinline__ void gemm_phase(LAS unsigned char* lds, const Gemm g, const StaticOrder& S, const Epi& E) {
;     ...
;             const char* a1 = cA + (size_t)(t + 1) * kstep;
;             const char* a2 = last ? nA : cA + (size_t)(t + 2) * kstep; const char* b2 = last ? nB : cB + (size_t)(t + 2) * kstep;
;             const char* a3 = a2 + kstep; const char* b3 = b2 + kstep;
;             PG8_LDB(B0, 0, 0); PG8_LDB(B1, 0, 1); PG8_SCHED; PG8_LDA(At, 0, 0); PG8_STAGE(PG8_SA(1, 1), a1 + hA, voffA);
;             PG8_WAIT_V(8); PG8_WAIT_L(0); PG8_BAR; PG8_MMA(0, 0, At, B0); PG8_MMA(0, 1, At, B1); PG8_BAR; PG8_SCHED;
;             PG8_LDA(At, 0, 1); PG8_STAGE(PG8_SB(0, 0), b2, voffB); PG8_STAGE(PG8_SB(0, 1), b2 + hB, voffB); PG8_STAGE(PG8_SA(0, 0), a2, voffA);
;             PG8_WAIT_V(8); PG8_WAIT_L(0); PG8_BAR; PG8_MMA(1, 0, At, B0); PG8_MMA(1, 1, At, B1); PG8_BAR; PG8_SCHED;
.LBB0_775:
	ds_read_b128 v[128:131], v196
	ds_read_b128 v[132:135], v196 offset:1024
	ds_read_b128 v[136:139], v196 offset:2048
	ds_read_b128 v[140:143], v196 offset:3072
	ds_read_b128 v[144:147], v197
	ds_read_b128 v[148:151], v197 offset:1024
	ds_read_b128 v[152:155], v197 offset:2048
	ds_read_b128 v[156:159], v197 offset:3072
	s_add_u32 s37, s40, 0xfff80080
	s_addc_u32 s38, s41, -1
	s_cmp_eq_u32 s29, 28
	s_cselect_b32 s45, s0, s38
	s_cselect_b32 s44, s1, s37
	s_cselect_b32 s43, s2, s27
	s_cselect_b32 s42, s3, s9
	v_lshl_add_u64 v[216:217], s[40:41], 0, v[168:169]
	s_add_i32 m0, s50, 0xc000
	ds_read_b128 v[176:179], v198
	ds_read_b128 v[180:183], v198 offset:1024
	ds_read_b128 v[184:187], v198 offset:2048
	ds_read_b128 v[188:191], v198 offset:3072
	ds_read_b128 v[200:203], v198 offset:4096
	ds_read_b128 v[204:207], v198 offset:5120
	ds_read_b128 v[208:211], v198 offset:6144
	ds_read_b128 v[212:215], v198 offset:7168
	global_load_lds_dwordx4 v[216:217], off
	v_lshl_add_u64 v[216:217], s[40:41], 0, v[170:171]
	s_add_i32 m0, s50, 0xe000
	s_nop 0
	global_load_lds_dwordx4 v[216:217], off
	s_waitcnt vmcnt(8)
	s_waitcnt lgkmcnt(0)
	s_barrier
	s_setprio 1
	s_waitcnt lgkmcnt(0)
	v_mfma_f32_16x16x32_bf16 v[124:127], v[128:131], v[176:179], v[124:127]
	v_mfma_f32_16x16x32_bf16 v[124:127], v[132:135], v[180:183], v[124:127]
	v_mfma_f32_16x16x32_bf16 v[120:123], v[140:143], v[180:183], v[120:123]
	v_mfma_f32_16x16x32_bf16 v[120:123], v[136:139], v[176:179], v[120:123]
	v_mfma_f32_16x16x32_bf16 v[104:107], v[136:139], v[184:187], v[104:107]
	v_mfma_f32_16x16x32_bf16 v[104:107], v[140:143], v[188:191], v[104:107]
	v_mfma_f32_16x16x32_bf16 v[108:111], v[132:135], v[188:191], v[108:111]
	v_mfma_f32_16x16x32_bf16 v[108:111], v[128:131], v[184:187], v[108:111]
	v_mfma_f32_16x16x32_bf16 v[92:95], v[128:131], v[200:203], v[92:95]
	v_mfma_f32_16x16x32_bf16 v[92:95], v[132:135], v[204:207], v[92:95]
	v_mfma_f32_16x16x32_bf16 v[88:91], v[140:143], v[204:207], v[88:91]
	v_mfma_f32_16x16x32_bf16 v[88:91], v[136:139], v[200:203], v[88:91]
	v_mfma_f32_16x16x32_bf16 v[72:75], v[136:139], v[208:211], v[72:75]
	v_mfma_f32_16x16x32_bf16 v[72:75], v[140:143], v[212:215], v[72:75]
	v_mfma_f32_16x16x32_bf16 v[76:79], v[132:135], v[212:215], v[76:79]
	v_mfma_f32_16x16x32_bf16 v[76:79], v[128:131], v[208:211], v[76:79]
	s_setprio 0
	s_setprio 1
	v_mfma_f32_16x16x32_bf16 v[116:119], v[144:147], v[176:179], v[116:119]
	v_mfma_f32_16x16x32_bf16 v[116:119], v[148:151], v[180:183], v[116:119]
	v_mfma_f32_16x16x32_bf16 v[112:115], v[156:159], v[180:183], v[112:115]
	v_mfma_f32_16x16x32_bf16 v[112:115], v[152:155], v[176:179], v[112:115]
	v_mfma_f32_16x16x32_bf16 v[96:99], v[152:155], v[184:187], v[96:99]
	v_mfma_f32_16x16x32_bf16 v[96:99], v[156:159], v[188:191], v[96:99]
	v_mfma_f32_16x16x32_bf16 v[100:103], v[148:151], v[188:191], v[100:103]
	v_mfma_f32_16x16x32_bf16 v[100:103], v[144:147], v[184:187], v[100:103]
	v_mfma_f32_16x16x32_bf16 v[84:87], v[144:147], v[200:203], v[84:87]
	v_mfma_f32_16x16x32_bf16 v[84:87], v[148:151], v[204:207], v[84:87]
	v_mfma_f32_16x16x32_bf16 v[80:83], v[156:159], v[204:207], v[80:83]
	v_mfma_f32_16x16x32_bf16 v[80:83], v[152:155], v[200:203], v[80:83]
	v_mfma_f32_16x16x32_bf16 v[64:67], v[152:155], v[208:211], v[64:67]
	v_mfma_f32_16x16x32_bf16 v[64:67], v[156:159], v[212:215], v[64:67]
	v_mfma_f32_16x16x32_bf16 v[68:71], v[148:151], v[212:215], v[68:71]
	v_mfma_f32_16x16x32_bf16 v[68:71], v[144:147], v[208:211], v[68:71]
	s_setprio 0
	s_barrier
	s_add_i32 s37, s60, s49
	v_lshl_add_u64 v[216:217], s[42:43], 0, v[162:163]
	s_mov_b32 m0, s37
	ds_read_b128 v[176:179], v198 offset:16384
	ds_read_b128 v[180:183], v198 offset:17408
	ds_read_b128 v[184:187], v198 offset:18432
	ds_read_b128 v[188:191], v198 offset:19456
	ds_read_b128 v[200:203], v198 offset:20480
	ds_read_b128 v[204:207], v198 offset:21504
	ds_read_b128 v[208:211], v198 offset:22528
	ds_read_b128 v[212:215], v198 offset:23552
	global_load_lds_dwordx4 v[216:217], off
	s_add_i32 m0, s37, 0x2000
	s_add_u32 s38, s42, 0x80000
	v_lshl_add_u64 v[218:219], s[42:43], 0, v[166:167]
	s_addc_u32 s39, s43, 0
	s_add_i32 s37, s61, s49
	global_load_lds_dwordx4 v[218:219], off
	v_lshl_add_u64 v[220:221], s[38:39], 0, v[162:163]
	s_mov_b32 m0, s37
	v_lshl_add_u64 v[222:223], s[44:45], 0, v[164:165]
	global_load_lds_dwordx4 v[220:221], off
	v_lshl_add_u64 v[220:221], s[38:39], 0, v[166:167]
	s_add_i32 m0, s37, 0x2000
	s_nop 0
	global_load_lds_dwordx4 v[220:221], off
	v_lshl_add_u64 v[220:221], s[44:45], 0, v[160:161]
	s_mov_b32 m0, s50
	s_nop 0
	global_load_lds_dwordx4 v[220:221], off
	s_mov_b32 m0, s51
	s_nop 0
	global_load_lds_dwordx4 v[222:223], off
	s_waitcnt vmcnt(8)
	s_waitcnt lgkmcnt(0)
	s_barrier
; #define PG8_STAGE(bufoff, gbase, voff) do { _Pragma("unroll") for (int _i = 0; _i < 2; ++_i) \
;         __builtin_amdgcn_global_load_lds((const unsigned*)((const char*)(gbase) + (voff)[_i]), (LAS unsigned*)(lds + (bufoff) + ldsw + _i * 8192), 16, 0, 0); } while (0)
; #define PG8_LDA(dst, b, h) do { _Pragma("unroll") for (int m = 0; m < 4; ++m) _Pragma("unroll") for (int k = 0; k < 2; ++k) dst[m][k] = *(const LAS bf16x8*)(lds + PG8_SA(b, h) + aoff + m * 2048 + k * 1024); } while (0)
; #define PG8_LDB(dst, b, h) do { _Pragma("unroll") for (int n = 0; n < 2; ++n) _Pragma("unroll") for (int k = 0; k < 2; ++k) dst[n][k] = *(const LAS bf16x8*)(lds + PG8_SB(b, h) + boff + n * 2048 + k * 1024); } while (0)
; #define PG8_MMA(ai, bj, At, Bt) do { __builtin_amdgcn_s_setprio(1); _Pragma("unroll") for (int m = 0; m < 4; ++m) _Pragma("unroll") for (int n = 0; n < 2; ++n) _Pragma("unroll") for (int k = 0; k < 2; ++k) \
;         acc[ai][bj][m][n] = __builtin_amdgcn_mfma_f32_16x16x32_bf16(Bt[n][k], At[m][k], acc[ai][bj][m][n], 0, 0, 0); __builtin_amdgcn_s_setprio(0); } while (0)
; #define PG8_WAIT_V(n) asm volatile("s_waitcnt vmcnt(" #n ")" ::: "memory")
; #define PG8_WAIT_L(n) asm volatile("s_waitcnt lgkmcnt(" #n ")" ::: "memory")
; #define PG8_BAR __builtin_amdgcn_s_barrier()
; #define PG8_SCHED __builtin_amdgcn_sched_barrier(0)
; template <class Epi, bool ALIGN_EPI>
; __device__ __forceinline__ void gemm_phase(LAS unsigned char* lds, const Gemm g, const StaticOrder& S, const Epi& E) {
;     ...
;             PG8_WAIT_V(8); PG8_WAIT_L(0); PG8_BAR; PG8_MMA(1, 0, At, B0); PG8_MMA(1, 1, At, B1); PG8_BAR; PG8_SCHED;
;             PG8_LDB(B0, 1, 0); PG8_LDB(B1, 1, 1); PG8_SCHED; PG8_LDA(At, 1, 0); PG8_STAGE(PG8_SA(0, 1), a2 + hA, voffA);
;             PG8_WAIT_V(8); PG8_WAIT_L(0); PG8_BAR; PG8_MMA(0, 0, At, B0); PG8_MMA(0, 1, At, B1); PG8_BAR; PG8_SCHED;
	s_setprio 1
	s_waitcnt lgkmcnt(0)
	v_mfma_f32_16x16x32_bf16 v[60:63], v[128:131], v[176:179], v[60:63]
	v_mfma_f32_16x16x32_bf16 v[60:63], v[132:135], v[180:183], v[60:63]
	v_mfma_f32_16x16x32_bf16 v[56:59], v[140:143], v[180:183], v[56:59]
	v_mfma_f32_16x16x32_bf16 v[56:59], v[136:139], v[176:179], v[56:59]
	v_mfma_f32_16x16x32_bf16 v[40:43], v[136:139], v[184:187], v[40:43]
	v_mfma_f32_16x16x32_bf16 v[40:43], v[140:143], v[188:191], v[40:43]
	v_mfma_f32_16x16x32_bf16 v[44:47], v[132:135], v[188:191], v[44:47]
	v_mfma_f32_16x16x32_bf16 v[44:47], v[128:131], v[184:187], v[44:47]
	v_mfma_f32_16x16x32_bf16 v[28:31], v[128:131], v[200:203], v[28:31]
	v_mfma_f32_16x16x32_bf16 v[28:31], v[132:135], v[204:207], v[28:31]
	v_mfma_f32_16x16x32_bf16 v[24:27], v[140:143], v[204:207], v[24:27]
	v_mfma_f32_16x16x32_bf16 v[24:27], v[136:139], v[200:203], v[24:27]
	v_mfma_f32_16x16x32_bf16 v[8:11], v[136:139], v[208:211], v[8:11]
	v_mfma_f32_16x16x32_bf16 v[8:11], v[140:143], v[212:215], v[8:11]
	v_mfma_f32_16x16x32_bf16 v[16:19], v[132:135], v[212:215], v[16:19]
	v_mfma_f32_16x16x32_bf16 v[16:19], v[128:131], v[208:211], v[16:19]
	s_setprio 0
	s_setprio 1
	v_mfma_f32_16x16x32_bf16 v[52:55], v[144:147], v[176:179], v[52:55]
	v_mfma_f32_16x16x32_bf16 v[52:55], v[148:151], v[180:183], v[52:55]
	v_mfma_f32_16x16x32_bf16 v[48:51], v[156:159], v[180:183], v[48:51]
	v_mfma_f32_16x16x32_bf16 v[48:51], v[152:155], v[176:179], v[48:51]
	v_mfma_f32_16x16x32_bf16 v[32:35], v[152:155], v[184:187], v[32:35]
	v_mfma_f32_16x16x32_bf16 v[32:35], v[156:159], v[188:191], v[32:35]
	v_mfma_f32_16x16x32_bf16 v[36:39], v[148:151], v[188:191], v[36:39]
	v_mfma_f32_16x16x32_bf16 v[36:39], v[144:147], v[184:187], v[36:39]
	v_mfma_f32_16x16x32_bf16 v[20:23], v[144:147], v[200:203], v[20:23]
	v_mfma_f32_16x16x32_bf16 v[20:23], v[148:151], v[204:207], v[20:23]
	v_mfma_f32_16x16x32_bf16 v[12:15], v[156:159], v[204:207], v[12:15]
	v_mfma_f32_16x16x32_bf16 v[12:15], v[152:155], v[200:203], v[12:15]
	v_mfma_f32_16x16x32_bf16 v[0:3], v[152:155], v[208:211], v[0:3]
	v_mfma_f32_16x16x32_bf16 v[0:3], v[156:159], v[212:215], v[0:3]
	v_mfma_f32_16x16x32_bf16 v[4:7], v[148:151], v[212:215], v[4:7]
	v_mfma_f32_16x16x32_bf16 v[4:7], v[144:147], v[208:211], v[4:7]
	s_setprio 0
	s_barrier
	s_add_i32 s37, 0, 0x18000
	s_add_i32 s63, 0, 0x1c000
	v_add_u32_e32 v140, s37, v194
	v_add_u32_e32 v156, s63, v194
	ds_read_b128 v[128:131], v140
	ds_read_b128 v[132:135], v140 offset:1024
	ds_read_b128 v[136:139], v140 offset:2048
	ds_read_b128 v[140:143], v140 offset:3072
	ds_read_b128 v[144:147], v156
	ds_read_b128 v[148:151], v156 offset:1024
	ds_read_b128 v[152:155], v156 offset:2048
	ds_read_b128 v[156:159], v156 offset:3072
	s_add_u32 s38, s44, 0x80000
	s_addc_u32 s39, s45, 0
	s_mov_b32 m0, s52
	v_lshl_add_u64 v[224:225], s[38:39], 0, v[160:161]
	ds_read_b128 v[176:179], v198 offset:32768
	ds_read_b128 v[180:183], v198 offset:33792
	ds_read_b128 v[184:187], v198 offset:34816
	ds_read_b128 v[188:191], v198 offset:35840
	ds_read_b128 v[200:203], v198 offset:36864
	ds_read_b128 v[204:207], v198 offset:37888
	ds_read_b128 v[208:211], v198 offset:38912
	ds_read_b128 v[212:215], v198 offset:39936
	global_load_lds_dwordx4 v[224:225], off
	v_lshl_add_u64 v[224:225], s[38:39], 0, v[164:165]
	s_mov_b32 m0, s53
	s_nop 0
	global_load_lds_dwordx4 v[224:225], off
	s_waitcnt vmcnt(8)
	s_waitcnt lgkmcnt(0)
	s_barrier
	s_setprio 1
	s_waitcnt lgkmcnt(0)
	v_mfma_f32_16x16x32_bf16 v[124:127], v[128:131], v[176:179], v[124:127]
	v_mfma_f32_16x16x32_bf16 v[124:127], v[132:135], v[180:183], v[124:127]
	v_mfma_f32_16x16x32_bf16 v[120:123], v[140:143], v[180:183], v[120:123]
	v_mfma_f32_16x16x32_bf16 v[120:123], v[136:139], v[176:179], v[120:123]
	v_mfma_f32_16x16x32_bf16 v[104:107], v[136:139], v[184:187], v[104:107]
	v_mfma_f32_16x16x32_bf16 v[104:107], v[140:143], v[188:191], v[104:107]
	v_mfma_f32_16x16x32_bf16 v[108:111], v[132:135], v[188:191], v[108:111]
	v_mfma_f32_16x16x32_bf16 v[108:111], v[128:131], v[184:187], v[108:111]
	v_mfma_f32_16x16x32_bf16 v[92:95], v[128:131], v[200:203], v[92:95]
	v_mfma_f32_16x16x32_bf16 v[92:95], v[132:135], v[204:207], v[92:95]
	v_mfma_f32_16x16x32_bf16 v[88:91], v[140:143], v[204:207], v[88:91]
	v_mfma_f32_16x16x32_bf16 v[88:91], v[136:139], v[200:203], v[88:91]
	v_mfma_f32_16x16x32_bf16 v[72:75], v[136:139], v[208:211], v[72:75]
	v_mfma_f32_16x16x32_bf16 v[72:75], v[140:143], v[212:215], v[72:75]
	v_mfma_f32_16x16x32_bf16 v[76:79], v[132:135], v[212:215], v[76:79]
	v_mfma_f32_16x16x32_bf16 v[76:79], v[128:131], v[208:211], v[76:79]
	s_setprio 0
	s_setprio 1
	v_mfma_f32_16x16x32_bf16 v[116:119], v[144:147], v[176:179], v[116:119]
	v_mfma_f32_16x16x32_bf16 v[116:119], v[148:151], v[180:183], v[116:119]
	v_mfma_f32_16x16x32_bf16 v[112:115], v[156:159], v[180:183], v[112:115]
	v_mfma_f32_16x16x32_bf16 v[112:115], v[152:155], v[176:179], v[112:115]
	v_mfma_f32_16x16x32_bf16 v[96:99], v[152:155], v[184:187], v[96:99]
	v_mfma_f32_16x16x32_bf16 v[96:99], v[156:159], v[188:191], v[96:99]
	v_mfma_f32_16x16x32_bf16 v[100:103], v[148:151], v[188:191], v[100:103]
	v_mfma_f32_16x16x32_bf16 v[100:103], v[144:147], v[184:187], v[100:103]
	v_mfma_f32_16x16x32_bf16 v[84:87], v[144:147], v[200:203], v[84:87]
	v_mfma_f32_16x16x32_bf16 v[84:87], v[148:151], v[204:207], v[84:87]
	v_mfma_f32_16x16x32_bf16 v[80:83], v[156:159], v[204:207], v[80:83]
	v_mfma_f32_16x16x32_bf16 v[80:83], v[152:155], v[200:203], v[80:83]
	v_mfma_f32_16x16x32_bf16 v[64:67], v[152:155], v[208:211], v[64:67]
	v_mfma_f32_16x16x32_bf16 v[64:67], v[156:159], v[212:215], v[64:67]
	v_mfma_f32_16x16x32_bf16 v[68:71], v[148:151], v[212:215], v[68:71]
	v_mfma_f32_16x16x32_bf16 v[68:71], v[144:147], v[208:211], v[68:71]
	s_setprio 0
	s_barrier
; #define PG8_STAGE(bufoff, gbase, voff) do { _Pragma("unroll") for (int _i = 0; _i < 2; ++_i) \
;         __builtin_amdgcn_global_load_lds((const unsigned*)((const char*)(gbase) + (voff)[_i]), (LAS unsigned*)(lds + (bufoff) + ldsw + _i * 8192), 16, 0, 0); } while (0)
; #define PG8_LDA(dst, b, h) do { _Pragma("unroll") for (int m = 0; m < 4; ++m) _Pragma("unroll") for (int k = 0; k < 2; ++k) dst[m][k] = *(const LAS bf16x8*)(lds + PG8_SA(b, h) + aoff + m * 2048 + k * 1024); } while (0)
; #define PG8_MMA(ai, bj, At, Bt) do { __builtin_amdgcn_s_setprio(1); _Pragma("unroll") for (int m = 0; m < 4; ++m) _Pragma("unroll") for (int n = 0; n < 2; ++n) _Pragma("unroll") for (int k = 0; k < 2; ++k) \
;         acc[ai][bj][m][n] = __builtin_amdgcn_mfma_f32_16x16x32_bf16(Bt[n][k], At[m][k], acc[ai][bj][m][n], 0, 0, 0); __builtin_amdgcn_s_setprio(0); } while (0)
; #define PG8_WAIT_V(n) asm volatile("s_waitcnt vmcnt(" #n ")" ::: "memory")
; #define PG8_WAIT_L(n) asm volatile("s_waitcnt lgkmcnt(" #n ")" ::: "memory")
; #define PG8_BAR __builtin_amdgcn_s_barrier()
; #define PG8_SCHED __builtin_amdgcn_sched_barrier(0)
; template <class Epi, bool ALIGN_EPI>
; __device__ __forceinline__ void gemm_phase(LAS unsigned char* lds, const Gemm g, const StaticOrder& S, const Epi& E) {
;     ...
;             PG8_LDA(At, 1, 1); PG8_STAGE(PG8_SB(1, 0), b3, voffB); PG8_STAGE(PG8_SB(1, 1), b3 + hB, voffB); PG8_STAGE(PG8_SA(1, 0), a3, voffA);
;             PG8_WAIT_V(8); PG8_WAIT_L(0); PG8_BAR; PG8_MMA(1, 0, At, B0); PG8_MMA(1, 1, At, B1); PG8_BAR; PG8_SCHED;
;         }
;         if constexpr (ALIGN_EPI) { if (wr == 0) PG8_BAR; }
	s_add_i32 s37, s37, s49
	v_lshl_add_u64 v[216:217], v[216:217], 0, s[20:21]
	s_mov_b32 m0, s37
	ds_read_b128 v[176:179], v198 offset:49152
	ds_read_b128 v[180:183], v198 offset:50176
	ds_read_b128 v[184:187], v198 offset:51200
	ds_read_b128 v[188:191], v198 offset:52224
	ds_read_b128 v[200:203], v198 offset:53248
	ds_read_b128 v[204:207], v198 offset:54272
	ds_read_b128 v[208:211], v198 offset:55296
	ds_read_b128 v[212:215], v198 offset:56320
	global_load_lds_dwordx4 v[216:217], off
	s_add_i32 m0, s37, 0x2000
	s_add_u32 s38, s42, 0x80080
	v_lshl_add_u64 v[216:217], v[218:219], 0, s[20:21]
	s_addc_u32 s39, s43, 0
	s_add_i32 s37, s63, s49
	global_load_lds_dwordx4 v[216:217], off
	v_lshl_add_u64 v[216:217], s[38:39], 0, v[162:163]
	s_mov_b32 m0, s37
	s_nop 0
	global_load_lds_dwordx4 v[216:217], off
	v_lshl_add_u64 v[216:217], s[38:39], 0, v[166:167]
	s_add_i32 m0, s37, 0x2000
	s_nop 0
	global_load_lds_dwordx4 v[216:217], off
	v_lshl_add_u64 v[216:217], v[220:221], 0, s[20:21]
	s_mov_b32 m0, s57
	s_nop 0
	global_load_lds_dwordx4 v[216:217], off
	v_lshl_add_u64 v[216:217], v[222:223], 0, s[20:21]
	s_mov_b32 m0, s58
	s_nop 0
	global_load_lds_dwordx4 v[216:217], off
	s_waitcnt vmcnt(8)
	s_waitcnt lgkmcnt(0)
	s_barrier
	s_setprio 1
	s_waitcnt lgkmcnt(0)
	v_mfma_f32_16x16x32_bf16 v[60:63], v[128:131], v[176:179], v[60:63]
	v_mfma_f32_16x16x32_bf16 v[60:63], v[132:135], v[180:183], v[60:63]
	v_mfma_f32_16x16x32_bf16 v[56:59], v[140:143], v[180:183], v[56:59]
	v_mfma_f32_16x16x32_bf16 v[56:59], v[136:139], v[176:179], v[56:59]
	v_mfma_f32_16x16x32_bf16 v[40:43], v[136:139], v[184:187], v[40:43]
	v_mfma_f32_16x16x32_bf16 v[40:43], v[140:143], v[188:191], v[40:43]
	v_mfma_f32_16x16x32_bf16 v[44:47], v[132:135], v[188:191], v[44:47]
	v_mfma_f32_16x16x32_bf16 v[44:47], v[128:131], v[184:187], v[44:47]
	v_mfma_f32_16x16x32_bf16 v[28:31], v[128:131], v[200:203], v[28:31]
	v_mfma_f32_16x16x32_bf16 v[28:31], v[132:135], v[204:207], v[28:31]
	v_mfma_f32_16x16x32_bf16 v[24:27], v[140:143], v[204:207], v[24:27]
	v_mfma_f32_16x16x32_bf16 v[24:27], v[136:139], v[200:203], v[24:27]
	v_mfma_f32_16x16x32_bf16 v[8:11], v[136:139], v[208:211], v[8:11]
	v_mfma_f32_16x16x32_bf16 v[8:11], v[140:143], v[212:215], v[8:11]
	v_mfma_f32_16x16x32_bf16 v[16:19], v[132:135], v[212:215], v[16:19]
	v_mfma_f32_16x16x32_bf16 v[16:19], v[128:131], v[208:211], v[16:19]
	s_setprio 0
	s_setprio 1
	v_mfma_f32_16x16x32_bf16 v[52:55], v[144:147], v[176:179], v[52:55]
	v_mfma_f32_16x16x32_bf16 v[52:55], v[148:151], v[180:183], v[52:55]
	v_mfma_f32_16x16x32_bf16 v[48:51], v[156:159], v[180:183], v[48:51]
	v_mfma_f32_16x16x32_bf16 v[48:51], v[152:155], v[176:179], v[48:51]
	v_mfma_f32_16x16x32_bf16 v[32:35], v[152:155], v[184:187], v[32:35]
	v_mfma_f32_16x16x32_bf16 v[32:35], v[156:159], v[188:191], v[32:35]
	v_mfma_f32_16x16x32_bf16 v[36:39], v[148:151], v[188:191], v[36:39]
	v_mfma_f32_16x16x32_bf16 v[36:39], v[144:147], v[184:187], v[36:39]
	v_mfma_f32_16x16x32_bf16 v[20:23], v[144:147], v[200:203], v[20:23]
	v_mfma_f32_16x16x32_bf16 v[20:23], v[148:151], v[204:207], v[20:23]
	v_mfma_f32_16x16x32_bf16 v[12:15], v[156:159], v[204:207], v[12:15]
	v_mfma_f32_16x16x32_bf16 v[12:15], v[152:155], v[200:203], v[12:15]
	v_mfma_f32_16x16x32_bf16 v[0:3], v[152:155], v[208:211], v[0:3]
	v_mfma_f32_16x16x32_bf16 v[0:3], v[156:159], v[212:215], v[0:3]
	v_mfma_f32_16x16x32_bf16 v[4:7], v[148:151], v[212:215], v[4:7]
	v_mfma_f32_16x16x32_bf16 v[4:7], v[144:147], v[208:211], v[4:7]
	s_setprio 0
	s_barrier
	s_add_i32 s29, s29, 2
	s_add_u32 s40, s40, 0x100
	s_addc_u32 s41, s41, 0
	s_add_u32 s9, s9, 0x100
	s_addc_u32 s27, s27, 0
	s_cmp_gt_u32 s29, 29
	s_cbranch_scc0 .LBB0_775
	s_and_b64 vcc, exec, s[22:23]
	s_cbranch_vccz .LBB0_778
	s_barrier

; #define PG8_STAGE(bufoff, gbase, voff) do { _Pragma("unroll") for (int _i = 0; _i < 2; ++_i) \
;         __builtin_amdgcn_global_load_lds((const unsigned*)((const char*)(gbase) + (voff)[_i]), (LAS unsigned*)(lds + (bufoff) + ldsw + _i * 8192), 16, 0, 0); } while (0)
; #define PG8_LDA(dst, b, h) do { _Pragma("unroll") for (int m = 0; m < 4; ++m) _Pragma("unroll") for (int k = 0; k < 2; ++k) dst[m][k] = *(const LAS bf16x8*)(lds + PG8_SA(b, h) + aoff + m * 2048 + k * 1024); } while (0)
; #define PG8_LDB(dst, b, h) do { _Pragma("unroll") for (int n = 0; n < 2; ++n) _Pragma("unroll") for (int k = 0; k < 2; ++k) dst[n][k] = *(const LAS bf16x8*)(lds + PG8_SB(b, h) + boff + n * 2048 + k * 1024); } while (0)
; #define PG8_MMA(ai, bj, At, Bt) do { __builtin_amdgcn_s_setprio(1); _Pragma("unroll") for (int m = 0; m < 4; ++m) _Pragma("unroll") for (int n = 0; n < 2; ++n) _Pragma("unroll") for (int k = 0; k < 2; ++k) \
;         acc[ai][bj][m][n] = __builtin_amdgcn_mfma_f32_16x16x32_bf16(Bt[n][k], At[m][k], acc[ai][bj][m][n], 0, 0, 0); __builtin_amdgcn_s_setprio(0); } while (0)
; #define PG8_WAIT_V(n) asm volatile("s_waitcnt vmcnt(" #n ")" ::: "memory")
; #define PG8_WAIT_L(n) asm volatile("s_waitcnt lgkmcnt(" #n ")" ::: "memory")
; #define PG8_BAR __builtin_amdgcn_s_barrier()
; #define PG8_SCHED __builtin_amdgcn_sched_barrier(0)
; template <class Epi, bool ALIGN_EPI>
; __device__ __forceinline__ void gemm_phase(LAS unsigned char* lds, const Gemm g, const StaticOrder& S, const Epi& E) {
;     ...
;             const char* a1 = cA + (size_t)(t + 1) * kstep;
;             const char* a2 = last ? nA : cA + (size_t)(t + 2) * kstep; const char* b2 = last ? nB : cB + (size_t)(t + 2) * kstep;
;             const char* a3 = a2 + kstep; const char* b3 = b2 + kstep;
;             PG8_LDB(B0, 0, 0); PG8_LDB(B1, 0, 1); PG8_SCHED; PG8_LDA(At, 0, 0); PG8_STAGE(PG8_SA(1, 1), a1 + hA, voffA);
;             PG8_WAIT_V(8); PG8_WAIT_L(0); PG8_BAR; PG8_MMA(0, 0, At, B0); PG8_MMA(0, 1, At, B1); PG8_BAR; PG8_SCHED;
;             PG8_LDA(At, 0, 1); PG8_STAGE(PG8_SB(0, 0), b2, voffB); PG8_STAGE(PG8_SB(0, 1), b2 + hB, voffB); PG8_STAGE(PG8_SA(0, 0), a2, voffA);
;             PG8_WAIT_V(8); PG8_WAIT_L(0); PG8_BAR; PG8_MMA(1, 0, At, B0); PG8_MMA(1, 1, At, B1); PG8_BAR; PG8_SCHED;
.LBB0_926:
	ds_read_b128 v[168:171], v153
	ds_read_b128 v[172:175], v153 offset:1024
	ds_read_b128 v[176:179], v153 offset:2048
	ds_read_b128 v[180:183], v153 offset:3072
	ds_read_b128 v[184:187], v155
	ds_read_b128 v[188:191], v155 offset:1024
	ds_read_b128 v[194:197], v155 offset:2048
	ds_read_b128 v[198:201], v155 offset:3072
	s_add_u32 s8, s6, 0xfff80080
	s_addc_u32 s9, s7, -1
	s_cmp_eq_u32 s71, 28
	s_cselect_b32 s55, s47, s9
	s_cselect_b32 s54, s67, s8
	s_cselect_b32 s9, s45, s70
	s_cselect_b32 s8, s68, s69
	v_lshl_add_u64 v[234:235], s[6:7], 0, v[136:137]
	s_add_i32 m0, s39, 0xc000
	ds_read_b128 v[202:205], v156
	ds_read_b128 v[206:209], v156 offset:1024
	ds_read_b128 v[210:213], v156 offset:2048
	ds_read_b128 v[214:217], v156 offset:3072
	ds_read_b128 v[218:221], v156 offset:4096
	ds_read_b128 v[222:225], v156 offset:5120
	ds_read_b128 v[226:229], v156 offset:6144
	ds_read_b128 v[230:233], v156 offset:7168
	global_load_lds_dwordx4 v[234:235], off
	v_lshl_add_u64 v[234:235], s[6:7], 0, v[138:139]
	s_add_i32 m0, s39, 0xe000
	s_nop 0
	global_load_lds_dwordx4 v[234:235], off
	s_waitcnt vmcnt(8)
	s_waitcnt lgkmcnt(0)
	s_barrier
	s_setprio 1
	s_waitcnt lgkmcnt(0)
	v_mfma_f32_16x16x32_bf16 v[124:127], v[168:171], v[202:205], v[124:127]
	v_mfma_f32_16x16x32_bf16 v[124:127], v[172:175], v[206:209], v[124:127]
	v_mfma_f32_16x16x32_bf16 v[120:123], v[180:183], v[206:209], v[120:123]
	v_mfma_f32_16x16x32_bf16 v[120:123], v[176:179], v[202:205], v[120:123]
	v_mfma_f32_16x16x32_bf16 v[104:107], v[176:179], v[210:213], v[104:107]
	v_mfma_f32_16x16x32_bf16 v[104:107], v[180:183], v[214:217], v[104:107]
	v_mfma_f32_16x16x32_bf16 v[108:111], v[172:175], v[214:217], v[108:111]
	v_mfma_f32_16x16x32_bf16 v[108:111], v[168:171], v[210:213], v[108:111]
	v_mfma_f32_16x16x32_bf16 v[92:95], v[168:171], v[218:221], v[92:95]
	v_mfma_f32_16x16x32_bf16 v[92:95], v[172:175], v[222:225], v[92:95]
	v_mfma_f32_16x16x32_bf16 v[88:91], v[180:183], v[222:225], v[88:91]
	v_mfma_f32_16x16x32_bf16 v[88:91], v[176:179], v[218:221], v[88:91]
	v_mfma_f32_16x16x32_bf16 v[72:75], v[176:179], v[226:229], v[72:75]
	v_mfma_f32_16x16x32_bf16 v[72:75], v[180:183], v[230:233], v[72:75]
	v_mfma_f32_16x16x32_bf16 v[76:79], v[172:175], v[230:233], v[76:79]
	v_mfma_f32_16x16x32_bf16 v[76:79], v[168:171], v[226:229], v[76:79]
	s_setprio 0
	s_setprio 1
	v_mfma_f32_16x16x32_bf16 v[116:119], v[184:187], v[202:205], v[116:119]
	v_mfma_f32_16x16x32_bf16 v[116:119], v[188:191], v[206:209], v[116:119]
	v_mfma_f32_16x16x32_bf16 v[112:115], v[198:201], v[206:209], v[112:115]
	v_mfma_f32_16x16x32_bf16 v[112:115], v[194:197], v[202:205], v[112:115]
	v_mfma_f32_16x16x32_bf16 v[96:99], v[194:197], v[210:213], v[96:99]
	v_mfma_f32_16x16x32_bf16 v[96:99], v[198:201], v[214:217], v[96:99]
	v_mfma_f32_16x16x32_bf16 v[100:103], v[188:191], v[214:217], v[100:103]
	v_mfma_f32_16x16x32_bf16 v[100:103], v[184:187], v[210:213], v[100:103]
	v_mfma_f32_16x16x32_bf16 v[84:87], v[184:187], v[218:221], v[84:87]
	v_mfma_f32_16x16x32_bf16 v[84:87], v[188:191], v[222:225], v[84:87]
	v_mfma_f32_16x16x32_bf16 v[80:83], v[198:201], v[222:225], v[80:83]
	v_mfma_f32_16x16x32_bf16 v[80:83], v[194:197], v[218:221], v[80:83]
	v_mfma_f32_16x16x32_bf16 v[64:67], v[194:197], v[226:229], v[64:67]
	v_mfma_f32_16x16x32_bf16 v[64:67], v[198:201], v[230:233], v[64:67]
	v_mfma_f32_16x16x32_bf16 v[68:71], v[188:191], v[230:233], v[68:71]
	v_mfma_f32_16x16x32_bf16 v[68:71], v[184:187], v[226:229], v[68:71]
	s_setprio 0
	s_barrier
	s_add_i32 s72, s63, s33
	v_lshl_add_u64 v[234:235], s[8:9], 0, v[132:133]
	s_mov_b32 m0, s72
	ds_read_b128 v[202:205], v156 offset:16384
	ds_read_b128 v[206:209], v156 offset:17408
	ds_read_b128 v[210:213], v156 offset:18432
	ds_read_b128 v[214:217], v156 offset:19456
	ds_read_b128 v[218:221], v156 offset:20480
	ds_read_b128 v[222:225], v156 offset:21504
	ds_read_b128 v[226:229], v156 offset:22528
	ds_read_b128 v[230:233], v156 offset:23552
	global_load_lds_dwordx4 v[234:235], off
	s_add_i32 m0, s72, 0x2000
	s_add_u32 s72, s8, 0x80000
	v_lshl_add_u64 v[236:237], s[8:9], 0, v[128:129]
	s_addc_u32 s73, s9, 0
	s_add_i32 s74, s64, s33
	global_load_lds_dwordx4 v[236:237], off
	v_lshl_add_u64 v[238:239], s[72:73], 0, v[132:133]
	s_mov_b32 m0, s74
	v_lshl_add_u64 v[240:241], s[54:55], 0, v[130:131]
	global_load_lds_dwordx4 v[238:239], off
	v_lshl_add_u64 v[238:239], s[72:73], 0, v[128:129]
	s_add_i32 m0, s74, 0x2000
	s_nop 0
	global_load_lds_dwordx4 v[238:239], off
	v_lshl_add_u64 v[238:239], s[54:55], 0, v[134:135]
	s_mov_b32 m0, s39
	s_nop 0
	global_load_lds_dwordx4 v[238:239], off
	s_mov_b32 m0, s53
	s_nop 0
	global_load_lds_dwordx4 v[240:241], off
	s_waitcnt vmcnt(8)
	s_waitcnt lgkmcnt(0)
	s_barrier
; #define PG8_STAGE(bufoff, gbase, voff) do { _Pragma("unroll") for (int _i = 0; _i < 2; ++_i) \
;         __builtin_amdgcn_global_load_lds((const unsigned*)((const char*)(gbase) + (voff)[_i]), (LAS unsigned*)(lds + (bufoff) + ldsw + _i * 8192), 16, 0, 0); } while (0)
; #define PG8_LDA(dst, b, h) do { _Pragma("unroll") for (int m = 0; m < 4; ++m) _Pragma("unroll") for (int k = 0; k < 2; ++k) dst[m][k] = *(const LAS bf16x8*)(lds + PG8_SA(b, h) + aoff + m * 2048 + k * 1024); } while (0)
; #define PG8_LDB(dst, b, h) do { _Pragma("unroll") for (int n = 0; n < 2; ++n) _Pragma("unroll") for (int k = 0; k < 2; ++k) dst[n][k] = *(const LAS bf16x8*)(lds + PG8_SB(b, h) + boff + n * 2048 + k * 1024); } while (0)
; #define PG8_MMA(ai, bj, At, Bt) do { __builtin_amdgcn_s_setprio(1); _Pragma("unroll") for (int m = 0; m < 4; ++m) _Pragma("unroll") for (int n = 0; n < 2; ++n) _Pragma("unroll") for (int k = 0; k < 2; ++k) \
;         acc[ai][bj][m][n] = __builtin_amdgcn_mfma_f32_16x16x32_bf16(Bt[n][k], At[m][k], acc[ai][bj][m][n], 0, 0, 0); __builtin_amdgcn_s_setprio(0); } while (0)
; #define PG8_WAIT_V(n) asm volatile("s_waitcnt vmcnt(" #n ")" ::: "memory")
; #define PG8_WAIT_L(n) asm volatile("s_waitcnt lgkmcnt(" #n ")" ::: "memory")
; #define PG8_BAR __builtin_amdgcn_s_barrier()
; #define PG8_SCHED __builtin_amdgcn_sched_barrier(0)
; template <class Epi, bool ALIGN_EPI>
; __device__ __forceinline__ void gemm_phase(LAS unsigned char* lds, const Gemm g, const StaticOrder& S, const Epi& E) {
;     ...
;             PG8_WAIT_V(8); PG8_WAIT_L(0); PG8_BAR; PG8_MMA(1, 0, At, B0); PG8_MMA(1, 1, At, B1); PG8_BAR; PG8_SCHED;
;             PG8_LDB(B0, 1, 0); PG8_LDB(B1, 1, 1); PG8_SCHED; PG8_LDA(At, 1, 0); PG8_STAGE(PG8_SA(0, 1), a2 + hA, voffA);
;             PG8_WAIT_V(8); PG8_WAIT_L(0); PG8_BAR; PG8_MMA(0, 0, At, B0); PG8_MMA(0, 1, At, B1); PG8_BAR; PG8_SCHED;
	s_setprio 1
	s_waitcnt lgkmcnt(0)
	v_mfma_f32_16x16x32_bf16 v[60:63], v[168:171], v[202:205], v[60:63]
	v_mfma_f32_16x16x32_bf16 v[60:63], v[172:175], v[206:209], v[60:63]
	v_mfma_f32_16x16x32_bf16 v[56:59], v[180:183], v[206:209], v[56:59]
	v_mfma_f32_16x16x32_bf16 v[56:59], v[176:179], v[202:205], v[56:59]
	v_mfma_f32_16x16x32_bf16 v[40:43], v[176:179], v[210:213], v[40:43]
	v_mfma_f32_16x16x32_bf16 v[40:43], v[180:183], v[214:217], v[40:43]
	v_mfma_f32_16x16x32_bf16 v[44:47], v[172:175], v[214:217], v[44:47]
	v_mfma_f32_16x16x32_bf16 v[44:47], v[168:171], v[210:213], v[44:47]
	v_mfma_f32_16x16x32_bf16 v[28:31], v[168:171], v[218:221], v[28:31]
	v_mfma_f32_16x16x32_bf16 v[28:31], v[172:175], v[222:225], v[28:31]
	v_mfma_f32_16x16x32_bf16 v[24:27], v[180:183], v[222:225], v[24:27]
	v_mfma_f32_16x16x32_bf16 v[24:27], v[176:179], v[218:221], v[24:27]
	v_mfma_f32_16x16x32_bf16 v[8:11], v[176:179], v[226:229], v[8:11]
	v_mfma_f32_16x16x32_bf16 v[8:11], v[180:183], v[230:233], v[8:11]
	v_mfma_f32_16x16x32_bf16 v[12:15], v[172:175], v[230:233], v[12:15]
	v_mfma_f32_16x16x32_bf16 v[12:15], v[168:171], v[226:229], v[12:15]
	s_setprio 0
	s_setprio 1
	v_mfma_f32_16x16x32_bf16 v[52:55], v[184:187], v[202:205], v[52:55]
	v_mfma_f32_16x16x32_bf16 v[52:55], v[188:191], v[206:209], v[52:55]
	v_mfma_f32_16x16x32_bf16 v[48:51], v[198:201], v[206:209], v[48:51]
	v_mfma_f32_16x16x32_bf16 v[48:51], v[194:197], v[202:205], v[48:51]
	v_mfma_f32_16x16x32_bf16 v[32:35], v[194:197], v[210:213], v[32:35]
	v_mfma_f32_16x16x32_bf16 v[32:35], v[198:201], v[214:217], v[32:35]
	v_mfma_f32_16x16x32_bf16 v[36:39], v[188:191], v[214:217], v[36:39]
	v_mfma_f32_16x16x32_bf16 v[36:39], v[184:187], v[210:213], v[36:39]
	v_mfma_f32_16x16x32_bf16 v[20:23], v[184:187], v[218:221], v[20:23]
	v_mfma_f32_16x16x32_bf16 v[20:23], v[188:191], v[222:225], v[20:23]
	v_mfma_f32_16x16x32_bf16 v[16:19], v[198:201], v[222:225], v[16:19]
	v_mfma_f32_16x16x32_bf16 v[16:19], v[194:197], v[218:221], v[16:19]
	v_mfma_f32_16x16x32_bf16 v[0:3], v[194:197], v[226:229], v[0:3]
	v_mfma_f32_16x16x32_bf16 v[0:3], v[198:201], v[230:233], v[0:3]
	v_mfma_f32_16x16x32_bf16 v[4:7], v[188:191], v[230:233], v[4:7]
	v_mfma_f32_16x16x32_bf16 v[4:7], v[184:187], v[226:229], v[4:7]
	s_setprio 0
	s_barrier
	s_add_i32 s72, 0, 0x18000
	v_add_u32_e32 v167, s72, v149
	s_add_i32 s73, 0, 0x1c000
	ds_read_b128 v[168:171], v167
	ds_read_b128 v[172:175], v167 offset:1024
	ds_read_b128 v[176:179], v167 offset:2048
	ds_read_b128 v[180:183], v167 offset:3072
	v_add_u32_e32 v167, s73, v149
	ds_read_b128 v[184:187], v167
	ds_read_b128 v[188:191], v167 offset:1024
	ds_read_b128 v[194:197], v167 offset:2048
	ds_read_b128 v[198:201], v167 offset:3072
	s_add_u32 s54, s54, 0x80000
	s_addc_u32 s55, s55, 0
	s_mov_b32 m0, s56
	v_lshl_add_u64 v[242:243], s[54:55], 0, v[134:135]
	ds_read_b128 v[202:205], v156 offset:32768
	ds_read_b128 v[206:209], v156 offset:33792
	ds_read_b128 v[210:213], v156 offset:34816
	ds_read_b128 v[214:217], v156 offset:35840
	ds_read_b128 v[218:221], v156 offset:36864
	ds_read_b128 v[222:225], v156 offset:37888
	ds_read_b128 v[226:229], v156 offset:38912
	ds_read_b128 v[230:233], v156 offset:39936
	global_load_lds_dwordx4 v[242:243], off
	v_lshl_add_u64 v[242:243], s[54:55], 0, v[130:131]
	s_mov_b32 m0, s57
	s_nop 0
	global_load_lds_dwordx4 v[242:243], off
	s_waitcnt vmcnt(8)
	s_waitcnt lgkmcnt(0)
	s_barrier
	s_setprio 1
	s_waitcnt lgkmcnt(0)
	v_mfma_f32_16x16x32_bf16 v[124:127], v[168:171], v[202:205], v[124:127]
	v_mfma_f32_16x16x32_bf16 v[124:127], v[172:175], v[206:209], v[124:127]
	v_mfma_f32_16x16x32_bf16 v[120:123], v[180:183], v[206:209], v[120:123]
	v_mfma_f32_16x16x32_bf16 v[120:123], v[176:179], v[202:205], v[120:123]
	v_mfma_f32_16x16x32_bf16 v[104:107], v[176:179], v[210:213], v[104:107]
	v_mfma_f32_16x16x32_bf16 v[104:107], v[180:183], v[214:217], v[104:107]
	v_mfma_f32_16x16x32_bf16 v[108:111], v[172:175], v[214:217], v[108:111]
	v_mfma_f32_16x16x32_bf16 v[108:111], v[168:171], v[210:213], v[108:111]
	v_mfma_f32_16x16x32_bf16 v[92:95], v[168:171], v[218:221], v[92:95]
	v_mfma_f32_16x16x32_bf16 v[92:95], v[172:175], v[222:225], v[92:95]
	v_mfma_f32_16x16x32_bf16 v[88:91], v[180:183], v[222:225], v[88:91]
	v_mfma_f32_16x16x32_bf16 v[88:91], v[176:179], v[218:221], v[88:91]
	v_mfma_f32_16x16x32_bf16 v[72:75], v[176:179], v[226:229], v[72:75]
	v_mfma_f32_16x16x32_bf16 v[72:75], v[180:183], v[230:233], v[72:75]
	v_mfma_f32_16x16x32_bf16 v[76:79], v[172:175], v[230:233], v[76:79]
	v_mfma_f32_16x16x32_bf16 v[76:79], v[168:171], v[226:229], v[76:79]
	s_setprio 0
	s_setprio 1
	v_mfma_f32_16x16x32_bf16 v[116:119], v[184:187], v[202:205], v[116:119]
	v_mfma_f32_16x16x32_bf16 v[116:119], v[188:191], v[206:209], v[116:119]
	v_mfma_f32_16x16x32_bf16 v[112:115], v[198:201], v[206:209], v[112:115]
	v_mfma_f32_16x16x32_bf16 v[112:115], v[194:197], v[202:205], v[112:115]
	v_mfma_f32_16x16x32_bf16 v[96:99], v[194:197], v[210:213], v[96:99]
	v_mfma_f32_16x16x32_bf16 v[96:99], v[198:201], v[214:217], v[96:99]
	v_mfma_f32_16x16x32_bf16 v[100:103], v[188:191], v[214:217], v[100:103]
	v_mfma_f32_16x16x32_bf16 v[100:103], v[184:187], v[210:213], v[100:103]
	v_mfma_f32_16x16x32_bf16 v[84:87], v[184:187], v[218:221], v[84:87]
	v_mfma_f32_16x16x32_bf16 v[84:87], v[188:191], v[222:225], v[84:87]
	v_mfma_f32_16x16x32_bf16 v[80:83], v[198:201], v[222:225], v[80:83]
	v_mfma_f32_16x16x32_bf16 v[80:83], v[194:197], v[218:221], v[80:83]
	v_mfma_f32_16x16x32_bf16 v[64:67], v[194:197], v[226:229], v[64:67]
	v_mfma_f32_16x16x32_bf16 v[64:67], v[198:201], v[230:233], v[64:67]
	v_mfma_f32_16x16x32_bf16 v[68:71], v[188:191], v[230:233], v[68:71]
	v_mfma_f32_16x16x32_bf16 v[68:71], v[184:187], v[226:229], v[68:71]
	s_setprio 0
	s_barrier
; #define PG8_STAGE(bufoff, gbase, voff) do { _Pragma("unroll") for (int _i = 0; _i < 2; ++_i) \
;         __builtin_amdgcn_global_load_lds((const unsigned*)((const char*)(gbase) + (voff)[_i]), (LAS unsigned*)(lds + (bufoff) + ldsw + _i * 8192), 16, 0, 0); } while (0)
; #define PG8_LDA(dst, b, h) do { _Pragma("unroll") for (int m = 0; m < 4; ++m) _Pragma("unroll") for (int k = 0; k < 2; ++k) dst[m][k] = *(const LAS bf16x8*)(lds + PG8_SA(b, h) + aoff + m * 2048 + k * 1024); } while (0)
; #define PG8_MMA(ai, bj, At, Bt) do { __builtin_amdgcn_s_setprio(1); _Pragma("unroll") for (int m = 0; m < 4; ++m) _Pragma("unroll") for (int n = 0; n < 2; ++n) _Pragma("unroll") for (int k = 0; k < 2; ++k) \
;         acc[ai][bj][m][n] = __builtin_amdgcn_mfma_f32_16x16x32_bf16(Bt[n][k], At[m][k], acc[ai][bj][m][n], 0, 0, 0); __builtin_amdgcn_s_setprio(0); } while (0)
; #define PG8_WAIT_V(n) asm volatile("s_waitcnt vmcnt(" #n ")" ::: "memory")
; #define PG8_WAIT_L(n) asm volatile("s_waitcnt lgkmcnt(" #n ")" ::: "memory")
; #define PG8_BAR __builtin_amdgcn_s_barrier()
; #define PG8_SCHED __builtin_amdgcn_sched_barrier(0)
; template <class Epi, bool ALIGN_EPI>
; __device__ __forceinline__ void gemm_phase(LAS unsigned char* lds, const Gemm g, const StaticOrder& S, const Epi& E) {
;     ...
;             PG8_LDA(At, 1, 1); PG8_STAGE(PG8_SB(1, 0), b3, voffB); PG8_STAGE(PG8_SB(1, 1), b3 + hB, voffB); PG8_STAGE(PG8_SA(1, 0), a3, voffA);
;             PG8_WAIT_V(8); PG8_WAIT_L(0); PG8_BAR; PG8_MMA(1, 0, At, B0); PG8_MMA(1, 1, At, B1); PG8_BAR; PG8_SCHED;
;         }
;         if constexpr (ALIGN_EPI) { if (wr == 0) PG8_BAR; }
	s_add_i32 s54, s72, s33
	v_lshl_add_u64 v[234:235], v[234:235], 0, s[18:19]
	s_mov_b32 m0, s54
	ds_read_b128 v[202:205], v156 offset:49152
	ds_read_b128 v[206:209], v156 offset:50176
	ds_read_b128 v[210:213], v156 offset:51200
	ds_read_b128 v[214:217], v156 offset:52224
	ds_read_b128 v[218:221], v156 offset:53248
	ds_read_b128 v[222:225], v156 offset:54272
	ds_read_b128 v[226:229], v156 offset:55296
	ds_read_b128 v[230:233], v156 offset:56320
	global_load_lds_dwordx4 v[234:235], off
	s_add_i32 m0, s54, 0x2000
	s_add_u32 s8, s8, 0x80080
	v_lshl_add_u64 v[234:235], v[236:237], 0, s[18:19]
	s_addc_u32 s9, s9, 0
	s_add_i32 s54, s73, s33
	global_load_lds_dwordx4 v[234:235], off
	v_lshl_add_u64 v[234:235], s[8:9], 0, v[132:133]
	s_mov_b32 m0, s54
	s_nop 0
	global_load_lds_dwordx4 v[234:235], off
	v_lshl_add_u64 v[234:235], s[8:9], 0, v[128:129]
	s_add_i32 m0, s54, 0x2000
	s_nop 0
	global_load_lds_dwordx4 v[234:235], off
	v_lshl_add_u64 v[234:235], v[238:239], 0, s[18:19]
	s_mov_b32 m0, s60
	s_nop 0
	global_load_lds_dwordx4 v[234:235], off
	v_lshl_add_u64 v[234:235], v[240:241], 0, s[18:19]
	s_mov_b32 m0, s61
	s_nop 0
	global_load_lds_dwordx4 v[234:235], off
	s_waitcnt vmcnt(8)
	s_waitcnt lgkmcnt(0)
	s_barrier
	s_setprio 1
	s_waitcnt lgkmcnt(0)
	v_mfma_f32_16x16x32_bf16 v[60:63], v[168:171], v[202:205], v[60:63]
	v_mfma_f32_16x16x32_bf16 v[60:63], v[172:175], v[206:209], v[60:63]
	v_mfma_f32_16x16x32_bf16 v[56:59], v[180:183], v[206:209], v[56:59]
	v_mfma_f32_16x16x32_bf16 v[56:59], v[176:179], v[202:205], v[56:59]
	v_mfma_f32_16x16x32_bf16 v[40:43], v[176:179], v[210:213], v[40:43]
	v_mfma_f32_16x16x32_bf16 v[40:43], v[180:183], v[214:217], v[40:43]
	v_mfma_f32_16x16x32_bf16 v[44:47], v[172:175], v[214:217], v[44:47]
	v_mfma_f32_16x16x32_bf16 v[44:47], v[168:171], v[210:213], v[44:47]
	v_mfma_f32_16x16x32_bf16 v[28:31], v[168:171], v[218:221], v[28:31]
	v_mfma_f32_16x16x32_bf16 v[28:31], v[172:175], v[222:225], v[28:31]
	v_mfma_f32_16x16x32_bf16 v[24:27], v[180:183], v[222:225], v[24:27]
	v_mfma_f32_16x16x32_bf16 v[24:27], v[176:179], v[218:221], v[24:27]
	v_mfma_f32_16x16x32_bf16 v[8:11], v[176:179], v[226:229], v[8:11]
	v_mfma_f32_16x16x32_bf16 v[8:11], v[180:183], v[230:233], v[8:11]
	v_mfma_f32_16x16x32_bf16 v[12:15], v[172:175], v[230:233], v[12:15]
	v_mfma_f32_16x16x32_bf16 v[12:15], v[168:171], v[226:229], v[12:15]
	s_setprio 0
	s_setprio 1
	v_mfma_f32_16x16x32_bf16 v[52:55], v[184:187], v[202:205], v[52:55]
	v_mfma_f32_16x16x32_bf16 v[52:55], v[188:191], v[206:209], v[52:55]
	v_mfma_f32_16x16x32_bf16 v[48:51], v[198:201], v[206:209], v[48:51]
	v_mfma_f32_16x16x32_bf16 v[48:51], v[194:197], v[202:205], v[48:51]
	v_mfma_f32_16x16x32_bf16 v[32:35], v[194:197], v[210:213], v[32:35]
	v_mfma_f32_16x16x32_bf16 v[32:35], v[198:201], v[214:217], v[32:35]
	v_mfma_f32_16x16x32_bf16 v[36:39], v[188:191], v[214:217], v[36:39]
	v_mfma_f32_16x16x32_bf16 v[36:39], v[184:187], v[210:213], v[36:39]
	v_mfma_f32_16x16x32_bf16 v[20:23], v[184:187], v[218:221], v[20:23]
	v_mfma_f32_16x16x32_bf16 v[20:23], v[188:191], v[222:225], v[20:23]
	v_mfma_f32_16x16x32_bf16 v[16:19], v[198:201], v[222:225], v[16:19]
	v_mfma_f32_16x16x32_bf16 v[16:19], v[194:197], v[218:221], v[16:19]
	v_mfma_f32_16x16x32_bf16 v[0:3], v[194:197], v[226:229], v[0:3]
	v_mfma_f32_16x16x32_bf16 v[0:3], v[198:201], v[230:233], v[0:3]
	v_mfma_f32_16x16x32_bf16 v[4:7], v[188:191], v[230:233], v[4:7]
	v_mfma_f32_16x16x32_bf16 v[4:7], v[184:187], v[226:229], v[4:7]
	s_setprio 0
	s_barrier
	s_add_i32 s71, s71, 2
	s_add_u32 s6, s6, 0x100
	s_addc_u32 s7, s7, 0
	s_add_u32 s69, s69, 0x100
	s_addc_u32 s70, s70, 0
	s_cmp_gt_u32 s71, 29
	s_cbranch_scc0 .LBB0_926
	s_and_b64 vcc, exec, s[20:21]
	s_cbranch_vccz .LBB0_929
	s_barrier

; #define PG8_STAGE(bufoff, gbase, voff) do { _Pragma("unroll") for (int _i = 0; _i < 2; ++_i) \
;         __builtin_amdgcn_global_load_lds((const unsigned*)((const char*)(gbase) + (voff)[_i]), (LAS unsigned*)(lds + (bufoff) + ldsw + _i * 8192), 16, 0, 0); } while (0)
; #define PG8_LDA(dst, b, h) do { _Pragma("unroll") for (int m = 0; m < 4; ++m) _Pragma("unroll") for (int k = 0; k < 2; ++k) dst[m][k] = *(const LAS bf16x8*)(lds + PG8_SA(b, h) + aoff + m * 2048 + k * 1024); } while (0)
; #define PG8_LDB(dst, b, h) do { _Pragma("unroll") for (int n = 0; n < 2; ++n) _Pragma("unroll") for (int k = 0; k < 2; ++k) dst[n][k] = *(const LAS bf16x8*)(lds + PG8_SB(b, h) + boff + n * 2048 + k * 1024); } while (0)
; #define PG8_MMA(ai, bj, At, Bt) do { __builtin_amdgcn_s_setprio(1); _Pragma("unroll") for (int m = 0; m < 4; ++m) _Pragma("unroll") for (int n = 0; n < 2; ++n) _Pragma("unroll") for (int k = 0; k < 2; ++k) \
;         acc[ai][bj][m][n] = __builtin_amdgcn_mfma_f32_16x16x32_bf16(Bt[n][k], At[m][k], acc[ai][bj][m][n], 0, 0, 0); __builtin_amdgcn_s_setprio(0); } while (0)
; #define PG8_WAIT_V(n) asm volatile("s_waitcnt vmcnt(" #n ")" ::: "memory")
; #define PG8_WAIT_L(n) asm volatile("s_waitcnt lgkmcnt(" #n ")" ::: "memory")
; #define PG8_BAR __builtin_amdgcn_s_barrier()
; #define PG8_SCHED __builtin_amdgcn_sched_barrier(0)
; template <class Epi, bool ALIGN_EPI>
; __device__ __forceinline__ void gemm_phase(LAS unsigned char* lds, const Gemm g, const StaticOrder& S, const Epi& E) {
;     ...
;             const char* a1 = cA + (size_t)(t + 1) * kstep;
;             const char* a2 = last ? nA : cA + (size_t)(t + 2) * kstep; const char* b2 = last ? nB : cB + (size_t)(t + 2) * kstep;
;             const char* a3 = a2 + kstep; const char* b3 = b2 + kstep;
;             PG8_LDB(B0, 0, 0); PG8_LDB(B1, 0, 1); PG8_SCHED; PG8_LDA(At, 0, 0); PG8_STAGE(PG8_SA(1, 1), a1 + hA, voffA);
;             PG8_WAIT_V(8); PG8_WAIT_L(0); PG8_BAR; PG8_MMA(0, 0, At, B0); PG8_MMA(0, 1, At, B1); PG8_BAR; PG8_SCHED;
;             PG8_LDA(At, 0, 1); PG8_STAGE(PG8_SB(0, 0), b2, voffB); PG8_STAGE(PG8_SB(0, 1), b2 + hB, voffB); PG8_STAGE(PG8_SA(0, 0), a2, voffA);
;             PG8_WAIT_V(8); PG8_WAIT_L(0); PG8_BAR; PG8_MMA(1, 0, At, B0); PG8_MMA(1, 1, At, B1); PG8_BAR; PG8_SCHED;
.LBB0_1005:
	ds_read_b128 v[128:131], v175
	ds_read_b128 v[132:135], v175 offset:1024
	ds_read_b128 v[136:139], v175 offset:2048
	ds_read_b128 v[140:143], v175 offset:3072
	ds_read_b128 v[160:163], v176
	ds_read_b128 v[164:167], v176 offset:1024
	ds_read_b128 v[168:171], v176 offset:2048
	ds_read_b128 v[180:183], v176 offset:3072
	s_add_u32 s40, s36, 0xffe00080
	s_addc_u32 s41, s37, -1
	s_cmpk_eq_i32 s57, 0x7c
	s_cselect_b32 s43, s25, s41
	s_cselect_b32 s42, s31, s40
	s_cselect_b32 s41, s23, s56
	s_cselect_b32 s40, s54, s55
	v_lshl_add_u64 v[218:219], s[36:37], 0, v[152:153]
	s_add_i32 m0, s35, 0xc000
	ds_read_b128 v[184:187], v177
	ds_read_b128 v[188:191], v177 offset:1024
	ds_read_b128 v[194:197], v177 offset:2048
	ds_read_b128 v[198:201], v177 offset:3072
	ds_read_b128 v[202:205], v177 offset:4096
	ds_read_b128 v[206:209], v177 offset:5120
	ds_read_b128 v[210:213], v177 offset:6144
	ds_read_b128 v[214:217], v177 offset:7168
	global_load_lds_dwordx4 v[218:219], off
	v_lshl_add_u64 v[218:219], s[36:37], 0, v[154:155]
	s_add_i32 m0, s35, 0xe000
	s_nop 0
	global_load_lds_dwordx4 v[218:219], off
	s_waitcnt vmcnt(8)
	s_waitcnt lgkmcnt(0)
	s_barrier
	s_setprio 1
	s_waitcnt lgkmcnt(0)
	v_mfma_f32_16x16x32_bf16 v[124:127], v[128:131], v[184:187], v[124:127]
	v_mfma_f32_16x16x32_bf16 v[124:127], v[132:135], v[188:191], v[124:127]
	v_mfma_f32_16x16x32_bf16 v[120:123], v[140:143], v[188:191], v[120:123]
	v_mfma_f32_16x16x32_bf16 v[120:123], v[136:139], v[184:187], v[120:123]
	v_mfma_f32_16x16x32_bf16 v[104:107], v[136:139], v[194:197], v[104:107]
	v_mfma_f32_16x16x32_bf16 v[104:107], v[140:143], v[198:201], v[104:107]
	v_mfma_f32_16x16x32_bf16 v[112:115], v[132:135], v[198:201], v[112:115]
	v_mfma_f32_16x16x32_bf16 v[112:115], v[128:131], v[194:197], v[112:115]
	v_mfma_f32_16x16x32_bf16 v[92:95], v[128:131], v[202:205], v[92:95]
	v_mfma_f32_16x16x32_bf16 v[92:95], v[132:135], v[206:209], v[92:95]
	v_mfma_f32_16x16x32_bf16 v[88:91], v[140:143], v[206:209], v[88:91]
	v_mfma_f32_16x16x32_bf16 v[88:91], v[136:139], v[202:205], v[88:91]
	v_mfma_f32_16x16x32_bf16 v[72:75], v[136:139], v[210:213], v[72:75]
	v_mfma_f32_16x16x32_bf16 v[72:75], v[140:143], v[214:217], v[72:75]
	v_mfma_f32_16x16x32_bf16 v[76:79], v[132:135], v[214:217], v[76:79]
	v_mfma_f32_16x16x32_bf16 v[76:79], v[128:131], v[210:213], v[76:79]
	s_setprio 0
	s_setprio 1
	v_mfma_f32_16x16x32_bf16 v[116:119], v[160:163], v[184:187], v[116:119]
	v_mfma_f32_16x16x32_bf16 v[116:119], v[164:167], v[188:191], v[116:119]
	v_mfma_f32_16x16x32_bf16 v[108:111], v[180:183], v[188:191], v[108:111]
	v_mfma_f32_16x16x32_bf16 v[108:111], v[168:171], v[184:187], v[108:111]
	v_mfma_f32_16x16x32_bf16 v[96:99], v[168:171], v[194:197], v[96:99]
	v_mfma_f32_16x16x32_bf16 v[96:99], v[180:183], v[198:201], v[96:99]
	v_mfma_f32_16x16x32_bf16 v[100:103], v[164:167], v[198:201], v[100:103]
	v_mfma_f32_16x16x32_bf16 v[100:103], v[160:163], v[194:197], v[100:103]
	v_mfma_f32_16x16x32_bf16 v[84:87], v[160:163], v[202:205], v[84:87]
	v_mfma_f32_16x16x32_bf16 v[84:87], v[164:167], v[206:209], v[84:87]
	v_mfma_f32_16x16x32_bf16 v[80:83], v[180:183], v[206:209], v[80:83]
	v_mfma_f32_16x16x32_bf16 v[80:83], v[168:171], v[202:205], v[80:83]
	v_mfma_f32_16x16x32_bf16 v[64:67], v[168:171], v[210:213], v[64:67]
	v_mfma_f32_16x16x32_bf16 v[64:67], v[180:183], v[214:217], v[64:67]
	v_mfma_f32_16x16x32_bf16 v[68:71], v[164:167], v[214:217], v[68:71]
	v_mfma_f32_16x16x32_bf16 v[68:71], v[160:163], v[210:213], v[68:71]
	s_setprio 0
	s_barrier
	s_add_i32 s58, s51, s33
	v_lshl_add_u64 v[218:219], s[40:41], 0, v[146:147]
	s_mov_b32 m0, s58
	ds_read_b128 v[184:187], v177 offset:16384
	ds_read_b128 v[188:191], v177 offset:17408
	ds_read_b128 v[194:197], v177 offset:18432
	ds_read_b128 v[198:201], v177 offset:19456
	ds_read_b128 v[202:205], v177 offset:20480
	ds_read_b128 v[206:209], v177 offset:21504
	ds_read_b128 v[210:213], v177 offset:22528
	ds_read_b128 v[214:217], v177 offset:23552
	global_load_lds_dwordx4 v[218:219], off
	s_add_i32 m0, s58, 0x2000
	s_add_u32 s58, s40, 0x200000
	v_lshl_add_u64 v[220:221], s[40:41], 0, v[150:151]
	s_addc_u32 s59, s41, 0
	s_add_i32 s60, s52, s33
	global_load_lds_dwordx4 v[220:221], off
	v_lshl_add_u64 v[222:223], s[58:59], 0, v[146:147]
	s_mov_b32 m0, s60
	v_lshl_add_u64 v[224:225], s[42:43], 0, v[148:149]
	global_load_lds_dwordx4 v[222:223], off
	v_lshl_add_u64 v[222:223], s[58:59], 0, v[150:151]
	s_add_i32 m0, s60, 0x2000
	s_nop 0
	global_load_lds_dwordx4 v[222:223], off
	v_lshl_add_u64 v[222:223], s[42:43], 0, v[144:145]
	s_mov_b32 m0, s35
	s_nop 0
	global_load_lds_dwordx4 v[222:223], off
	s_mov_b32 m0, s38
	s_nop 0
	global_load_lds_dwordx4 v[224:225], off
	s_waitcnt vmcnt(8)
	s_waitcnt lgkmcnt(0)
	s_barrier
; #define PG8_STAGE(bufoff, gbase, voff) do { _Pragma("unroll") for (int _i = 0; _i < 2; ++_i) \
;         __builtin_amdgcn_global_load_lds((const unsigned*)((const char*)(gbase) + (voff)[_i]), (LAS unsigned*)(lds + (bufoff) + ldsw + _i * 8192), 16, 0, 0); } while (0)
; #define PG8_LDA(dst, b, h) do { _Pragma("unroll") for (int m = 0; m < 4; ++m) _Pragma("unroll") for (int k = 0; k < 2; ++k) dst[m][k] = *(const LAS bf16x8*)(lds + PG8_SA(b, h) + aoff + m * 2048 + k * 1024); } while (0)
; #define PG8_LDB(dst, b, h) do { _Pragma("unroll") for (int n = 0; n < 2; ++n) _Pragma("unroll") for (int k = 0; k < 2; ++k) dst[n][k] = *(const LAS bf16x8*)(lds + PG8_SB(b, h) + boff + n * 2048 + k * 1024); } while (0)
; #define PG8_MMA(ai, bj, At, Bt) do { __builtin_amdgcn_s_setprio(1); _Pragma("unroll") for (int m = 0; m < 4; ++m) _Pragma("unroll") for (int n = 0; n < 2; ++n) _Pragma("unroll") for (int k = 0; k < 2; ++k) \
;         acc[ai][bj][m][n] = __builtin_amdgcn_mfma_f32_16x16x32_bf16(Bt[n][k], At[m][k], acc[ai][bj][m][n], 0, 0, 0); __builtin_amdgcn_s_setprio(0); } while (0)
; #define PG8_WAIT_V(n) asm volatile("s_waitcnt vmcnt(" #n ")" ::: "memory")
; #define PG8_WAIT_L(n) asm volatile("s_waitcnt lgkmcnt(" #n ")" ::: "memory")
; #define PG8_BAR __builtin_amdgcn_s_barrier()
; #define PG8_SCHED __builtin_amdgcn_sched_barrier(0)
; template <class Epi, bool ALIGN_EPI>
; __device__ __forceinline__ void gemm_phase(LAS unsigned char* lds, const Gemm g, const StaticOrder& S, const Epi& E) {
;     ...
;             PG8_WAIT_V(8); PG8_WAIT_L(0); PG8_BAR; PG8_MMA(1, 0, At, B0); PG8_MMA(1, 1, At, B1); PG8_BAR; PG8_SCHED;
;             PG8_LDB(B0, 1, 0); PG8_LDB(B1, 1, 1); PG8_SCHED; PG8_LDA(At, 1, 0); PG8_STAGE(PG8_SA(0, 1), a2 + hA, voffA);
;             PG8_WAIT_V(8); PG8_WAIT_L(0); PG8_BAR; PG8_MMA(0, 0, At, B0); PG8_MMA(0, 1, At, B1); PG8_BAR; PG8_SCHED;
	s_setprio 1
	s_waitcnt lgkmcnt(0)
	v_mfma_f32_16x16x32_bf16 v[60:63], v[128:131], v[184:187], v[60:63]
	v_mfma_f32_16x16x32_bf16 v[60:63], v[132:135], v[188:191], v[60:63]
	v_mfma_f32_16x16x32_bf16 v[56:59], v[140:143], v[188:191], v[56:59]
	v_mfma_f32_16x16x32_bf16 v[56:59], v[136:139], v[184:187], v[56:59]
	v_mfma_f32_16x16x32_bf16 v[40:43], v[136:139], v[194:197], v[40:43]
	v_mfma_f32_16x16x32_bf16 v[40:43], v[140:143], v[198:201], v[40:43]
	v_mfma_f32_16x16x32_bf16 v[44:47], v[132:135], v[198:201], v[44:47]
	v_mfma_f32_16x16x32_bf16 v[44:47], v[128:131], v[194:197], v[44:47]
	v_mfma_f32_16x16x32_bf16 v[28:31], v[128:131], v[202:205], v[28:31]
	v_mfma_f32_16x16x32_bf16 v[28:31], v[132:135], v[206:209], v[28:31]
	v_mfma_f32_16x16x32_bf16 v[24:27], v[140:143], v[206:209], v[24:27]
	v_mfma_f32_16x16x32_bf16 v[24:27], v[136:139], v[202:205], v[24:27]
	v_mfma_f32_16x16x32_bf16 v[8:11], v[136:139], v[210:213], v[8:11]
	v_mfma_f32_16x16x32_bf16 v[8:11], v[140:143], v[214:217], v[8:11]
	v_mfma_f32_16x16x32_bf16 v[12:15], v[132:135], v[214:217], v[12:15]
	v_mfma_f32_16x16x32_bf16 v[12:15], v[128:131], v[210:213], v[12:15]
	s_setprio 0
	s_setprio 1
	v_mfma_f32_16x16x32_bf16 v[52:55], v[160:163], v[184:187], v[52:55]
	v_mfma_f32_16x16x32_bf16 v[52:55], v[164:167], v[188:191], v[52:55]
	v_mfma_f32_16x16x32_bf16 v[48:51], v[180:183], v[188:191], v[48:51]
	v_mfma_f32_16x16x32_bf16 v[48:51], v[168:171], v[184:187], v[48:51]
	v_mfma_f32_16x16x32_bf16 v[32:35], v[168:171], v[194:197], v[32:35]
	v_mfma_f32_16x16x32_bf16 v[32:35], v[180:183], v[198:201], v[32:35]
	v_mfma_f32_16x16x32_bf16 v[36:39], v[164:167], v[198:201], v[36:39]
	v_mfma_f32_16x16x32_bf16 v[36:39], v[160:163], v[194:197], v[36:39]
	v_mfma_f32_16x16x32_bf16 v[20:23], v[160:163], v[202:205], v[20:23]
	v_mfma_f32_16x16x32_bf16 v[20:23], v[164:167], v[206:209], v[20:23]
	v_mfma_f32_16x16x32_bf16 v[16:19], v[180:183], v[206:209], v[16:19]
	v_mfma_f32_16x16x32_bf16 v[16:19], v[168:171], v[202:205], v[16:19]
	v_mfma_f32_16x16x32_bf16 v[0:3], v[168:171], v[210:213], v[0:3]
	v_mfma_f32_16x16x32_bf16 v[0:3], v[180:183], v[214:217], v[0:3]
	v_mfma_f32_16x16x32_bf16 v[4:7], v[164:167], v[214:217], v[4:7]
	v_mfma_f32_16x16x32_bf16 v[4:7], v[160:163], v[210:213], v[4:7]
	s_setprio 0
	s_barrier
	s_add_i32 s58, 0, 0x18000
	s_add_i32 s59, 0, 0x1c000
	v_add_u32_e32 v140, s58, v173
	v_add_u32_e32 v179, s59, v173
	ds_read_b128 v[128:131], v140
	ds_read_b128 v[132:135], v140 offset:1024
	ds_read_b128 v[136:139], v140 offset:2048
	ds_read_b128 v[140:143], v140 offset:3072
	ds_read_b128 v[160:163], v179
	ds_read_b128 v[164:167], v179 offset:1024
	ds_read_b128 v[168:171], v179 offset:2048
	ds_read_b128 v[180:183], v179 offset:3072
	s_add_u32 s42, s42, 0x200000
	s_addc_u32 s43, s43, 0
	s_mov_b32 m0, s39
	v_lshl_add_u64 v[226:227], s[42:43], 0, v[144:145]
	ds_read_b128 v[184:187], v177 offset:32768
	ds_read_b128 v[188:191], v177 offset:33792
	ds_read_b128 v[194:197], v177 offset:34816
	ds_read_b128 v[198:201], v177 offset:35840
	ds_read_b128 v[202:205], v177 offset:36864
	ds_read_b128 v[206:209], v177 offset:37888
	ds_read_b128 v[210:213], v177 offset:38912
	ds_read_b128 v[214:217], v177 offset:39936
	global_load_lds_dwordx4 v[226:227], off
	v_lshl_add_u64 v[226:227], s[42:43], 0, v[148:149]
	s_mov_b32 m0, s44
	s_nop 0
	global_load_lds_dwordx4 v[226:227], off
	s_waitcnt vmcnt(8)
	s_waitcnt lgkmcnt(0)
	s_barrier
	s_setprio 1
	s_waitcnt lgkmcnt(0)
	v_mfma_f32_16x16x32_bf16 v[124:127], v[128:131], v[184:187], v[124:127]
	v_mfma_f32_16x16x32_bf16 v[124:127], v[132:135], v[188:191], v[124:127]
	v_mfma_f32_16x16x32_bf16 v[120:123], v[140:143], v[188:191], v[120:123]
	v_mfma_f32_16x16x32_bf16 v[120:123], v[136:139], v[184:187], v[120:123]
	v_mfma_f32_16x16x32_bf16 v[104:107], v[136:139], v[194:197], v[104:107]
	v_mfma_f32_16x16x32_bf16 v[104:107], v[140:143], v[198:201], v[104:107]
	v_mfma_f32_16x16x32_bf16 v[112:115], v[132:135], v[198:201], v[112:115]
	v_mfma_f32_16x16x32_bf16 v[112:115], v[128:131], v[194:197], v[112:115]
	v_mfma_f32_16x16x32_bf16 v[92:95], v[128:131], v[202:205], v[92:95]
	v_mfma_f32_16x16x32_bf16 v[92:95], v[132:135], v[206:209], v[92:95]
	v_mfma_f32_16x16x32_bf16 v[88:91], v[140:143], v[206:209], v[88:91]
	v_mfma_f32_16x16x32_bf16 v[88:91], v[136:139], v[202:205], v[88:91]
	v_mfma_f32_16x16x32_bf16 v[72:75], v[136:139], v[210:213], v[72:75]
	v_mfma_f32_16x16x32_bf16 v[72:75], v[140:143], v[214:217], v[72:75]
	v_mfma_f32_16x16x32_bf16 v[76:79], v[132:135], v[214:217], v[76:79]
	v_mfma_f32_16x16x32_bf16 v[76:79], v[128:131], v[210:213], v[76:79]
	s_setprio 0
	s_setprio 1
	v_mfma_f32_16x16x32_bf16 v[116:119], v[160:163], v[184:187], v[116:119]
	v_mfma_f32_16x16x32_bf16 v[116:119], v[164:167], v[188:191], v[116:119]
	v_mfma_f32_16x16x32_bf16 v[108:111], v[180:183], v[188:191], v[108:111]
	v_mfma_f32_16x16x32_bf16 v[108:111], v[168:171], v[184:187], v[108:111]
	v_mfma_f32_16x16x32_bf16 v[96:99], v[168:171], v[194:197], v[96:99]
	v_mfma_f32_16x16x32_bf16 v[96:99], v[180:183], v[198:201], v[96:99]
	v_mfma_f32_16x16x32_bf16 v[100:103], v[164:167], v[198:201], v[100:103]
	v_mfma_f32_16x16x32_bf16 v[100:103], v[160:163], v[194:197], v[100:103]
	v_mfma_f32_16x16x32_bf16 v[84:87], v[160:163], v[202:205], v[84:87]
	v_mfma_f32_16x16x32_bf16 v[84:87], v[164:167], v[206:209], v[84:87]
	v_mfma_f32_16x16x32_bf16 v[80:83], v[180:183], v[206:209], v[80:83]
	v_mfma_f32_16x16x32_bf16 v[80:83], v[168:171], v[202:205], v[80:83]
	v_mfma_f32_16x16x32_bf16 v[64:67], v[168:171], v[210:213], v[64:67]
	v_mfma_f32_16x16x32_bf16 v[64:67], v[180:183], v[214:217], v[64:67]
	v_mfma_f32_16x16x32_bf16 v[68:71], v[164:167], v[214:217], v[68:71]
	v_mfma_f32_16x16x32_bf16 v[68:71], v[160:163], v[210:213], v[68:71]
	s_setprio 0
	s_barrier
; #define PG8_STAGE(bufoff, gbase, voff) do { _Pragma("unroll") for (int _i = 0; _i < 2; ++_i) \
;         __builtin_amdgcn_global_load_lds((const unsigned*)((const char*)(gbase) + (voff)[_i]), (LAS unsigned*)(lds + (bufoff) + ldsw + _i * 8192), 16, 0, 0); } while (0)
; #define PG8_LDA(dst, b, h) do { _Pragma("unroll") for (int m = 0; m < 4; ++m) _Pragma("unroll") for (int k = 0; k < 2; ++k) dst[m][k] = *(const LAS bf16x8*)(lds + PG8_SA(b, h) + aoff + m * 2048 + k * 1024); } while (0)
; #define PG8_MMA(ai, bj, At, Bt) do { __builtin_amdgcn_s_setprio(1); _Pragma("unroll") for (int m = 0; m < 4; ++m) _Pragma("unroll") for (int n = 0; n < 2; ++n) _Pragma("unroll") for (int k = 0; k < 2; ++k) \
;         acc[ai][bj][m][n] = __builtin_amdgcn_mfma_f32_16x16x32_bf16(Bt[n][k], At[m][k], acc[ai][bj][m][n], 0, 0, 0); __builtin_amdgcn_s_setprio(0); } while (0)
; #define PG8_WAIT_V(n) asm volatile("s_waitcnt vmcnt(" #n ")" ::: "memory")
; #define PG8_WAIT_L(n) asm volatile("s_waitcnt lgkmcnt(" #n ")" ::: "memory")
; #define PG8_BAR __builtin_amdgcn_s_barrier()
; #define PG8_SCHED __builtin_amdgcn_sched_barrier(0)
; template <class Epi, bool ALIGN_EPI>
; __device__ __forceinline__ void gemm_phase(LAS unsigned char* lds, const Gemm g, const StaticOrder& S, const Epi& E) {
;     ...
;             PG8_LDA(At, 1, 1); PG8_STAGE(PG8_SB(1, 0), b3, voffB); PG8_STAGE(PG8_SB(1, 1), b3 + hB, voffB); PG8_STAGE(PG8_SA(1, 0), a3, voffA);
;             PG8_WAIT_V(8); PG8_WAIT_L(0); PG8_BAR; PG8_MMA(1, 0, At, B0); PG8_MMA(1, 1, At, B1); PG8_BAR; PG8_SCHED;
;         }
;         if constexpr (ALIGN_EPI) { if (wr == 0) PG8_BAR; }
	s_add_i32 s42, s58, s33
	v_lshl_add_u64 v[218:219], v[218:219], 0, s[16:17]
	s_mov_b32 m0, s42
	ds_read_b128 v[184:187], v177 offset:49152
	ds_read_b128 v[188:191], v177 offset:50176
	ds_read_b128 v[194:197], v177 offset:51200
	ds_read_b128 v[198:201], v177 offset:52224
	ds_read_b128 v[202:205], v177 offset:53248
	ds_read_b128 v[206:209], v177 offset:54272
	ds_read_b128 v[210:213], v177 offset:55296
	ds_read_b128 v[214:217], v177 offset:56320
	global_load_lds_dwordx4 v[218:219], off
	s_add_i32 m0, s42, 0x2000
	s_add_u32 s40, s40, 0x200080
	v_lshl_add_u64 v[218:219], v[220:221], 0, s[16:17]
	s_addc_u32 s41, s41, 0
	s_add_i32 s42, s59, s33
	global_load_lds_dwordx4 v[218:219], off
	v_lshl_add_u64 v[218:219], s[40:41], 0, v[146:147]
	s_mov_b32 m0, s42
	s_nop 0
	global_load_lds_dwordx4 v[218:219], off
	v_lshl_add_u64 v[218:219], s[40:41], 0, v[150:151]
	s_add_i32 m0, s42, 0x2000
	s_nop 0
	global_load_lds_dwordx4 v[218:219], off
	v_lshl_add_u64 v[218:219], v[222:223], 0, s[16:17]
	s_mov_b32 m0, s48
	s_nop 0
	global_load_lds_dwordx4 v[218:219], off
	v_lshl_add_u64 v[218:219], v[224:225], 0, s[16:17]
	s_mov_b32 m0, s49
	s_nop 0
	global_load_lds_dwordx4 v[218:219], off
	s_waitcnt vmcnt(8)
	s_waitcnt lgkmcnt(0)
	s_barrier
	s_setprio 1
	s_waitcnt lgkmcnt(0)
	v_mfma_f32_16x16x32_bf16 v[60:63], v[128:131], v[184:187], v[60:63]
	v_mfma_f32_16x16x32_bf16 v[60:63], v[132:135], v[188:191], v[60:63]
	v_mfma_f32_16x16x32_bf16 v[56:59], v[140:143], v[188:191], v[56:59]
	v_mfma_f32_16x16x32_bf16 v[56:59], v[136:139], v[184:187], v[56:59]
	v_mfma_f32_16x16x32_bf16 v[40:43], v[136:139], v[194:197], v[40:43]
	v_mfma_f32_16x16x32_bf16 v[40:43], v[140:143], v[198:201], v[40:43]
	v_mfma_f32_16x16x32_bf16 v[44:47], v[132:135], v[198:201], v[44:47]
	v_mfma_f32_16x16x32_bf16 v[44:47], v[128:131], v[194:197], v[44:47]
	v_mfma_f32_16x16x32_bf16 v[28:31], v[128:131], v[202:205], v[28:31]
	v_mfma_f32_16x16x32_bf16 v[28:31], v[132:135], v[206:209], v[28:31]
	v_mfma_f32_16x16x32_bf16 v[24:27], v[140:143], v[206:209], v[24:27]
	v_mfma_f32_16x16x32_bf16 v[24:27], v[136:139], v[202:205], v[24:27]
	v_mfma_f32_16x16x32_bf16 v[8:11], v[136:139], v[210:213], v[8:11]
	v_mfma_f32_16x16x32_bf16 v[8:11], v[140:143], v[214:217], v[8:11]
	v_mfma_f32_16x16x32_bf16 v[12:15], v[132:135], v[214:217], v[12:15]
	v_mfma_f32_16x16x32_bf16 v[12:15], v[128:131], v[210:213], v[12:15]
	s_setprio 0
	s_setprio 1
	v_mfma_f32_16x16x32_bf16 v[52:55], v[160:163], v[184:187], v[52:55]
	v_mfma_f32_16x16x32_bf16 v[52:55], v[164:167], v[188:191], v[52:55]
	v_mfma_f32_16x16x32_bf16 v[48:51], v[180:183], v[188:191], v[48:51]
	v_mfma_f32_16x16x32_bf16 v[48:51], v[168:171], v[184:187], v[48:51]
	v_mfma_f32_16x16x32_bf16 v[32:35], v[168:171], v[194:197], v[32:35]
	v_mfma_f32_16x16x32_bf16 v[32:35], v[180:183], v[198:201], v[32:35]
	v_mfma_f32_16x16x32_bf16 v[36:39], v[164:167], v[198:201], v[36:39]
	v_mfma_f32_16x16x32_bf16 v[36:39], v[160:163], v[194:197], v[36:39]
	v_mfma_f32_16x16x32_bf16 v[20:23], v[160:163], v[202:205], v[20:23]
	v_mfma_f32_16x16x32_bf16 v[20:23], v[164:167], v[206:209], v[20:23]
	v_mfma_f32_16x16x32_bf16 v[16:19], v[180:183], v[206:209], v[16:19]
	v_mfma_f32_16x16x32_bf16 v[16:19], v[168:171], v[202:205], v[16:19]
	v_mfma_f32_16x16x32_bf16 v[0:3], v[168:171], v[210:213], v[0:3]
	v_mfma_f32_16x16x32_bf16 v[0:3], v[180:183], v[214:217], v[0:3]
	v_mfma_f32_16x16x32_bf16 v[4:7], v[164:167], v[214:217], v[4:7]
	v_mfma_f32_16x16x32_bf16 v[4:7], v[160:163], v[210:213], v[4:7]
	s_setprio 0
	s_barrier
	s_add_i32 s57, s57, 2
	s_add_u32 s36, s36, 0x100
	s_addc_u32 s37, s37, 0
	s_add_u32 s55, s55, 0x100
	s_addc_u32 s56, s56, 0
	s_cmpk_gt_u32 s57, 0x7d
	s_cbranch_scc0 .LBB0_1005
	s_and_b64 vcc, exec, s[18:19]
	s_cbranch_vccz .LBB0_1008
	s_barrier

; #define PG8_STAGE(bufoff, gbase, voff) do { _Pragma("unroll") for (int _i = 0; _i < 2; ++_i) \
;         __builtin_amdgcn_global_load_lds((const unsigned*)((const char*)(gbase) + (voff)[_i]), (LAS unsigned*)(lds + (bufoff) + ldsw + _i * 8192), 16, 0, 0); } while (0)
; #define PG8_LDA(dst, b, h) do { _Pragma("unroll") for (int m = 0; m < 4; ++m) _Pragma("unroll") for (int k = 0; k < 2; ++k) dst[m][k] = *(const LAS bf16x8*)(lds + PG8_SA(b, h) + aoff + m * 2048 + k * 1024); } while (0)
; #define PG8_LDB(dst, b, h) do { _Pragma("unroll") for (int n = 0; n < 2; ++n) _Pragma("unroll") for (int k = 0; k < 2; ++k) dst[n][k] = *(const LAS bf16x8*)(lds + PG8_SB(b, h) + boff + n * 2048 + k * 1024); } while (0)
; #define PG8_MMA(ai, bj, At, Bt) do { __builtin_amdgcn_s_setprio(1); _Pragma("unroll") for (int m = 0; m < 4; ++m) _Pragma("unroll") for (int n = 0; n < 2; ++n) _Pragma("unroll") for (int k = 0; k < 2; ++k) \
;         acc[ai][bj][m][n] = __builtin_amdgcn_mfma_f32_16x16x32_bf16(Bt[n][k], At[m][k], acc[ai][bj][m][n], 0, 0, 0); __builtin_amdgcn_s_setprio(0); } while (0)
; #define PG8_WAIT_V(n) asm volatile("s_waitcnt vmcnt(" #n ")" ::: "memory")
; #define PG8_WAIT_L(n) asm volatile("s_waitcnt lgkmcnt(" #n ")" ::: "memory")
; #define PG8_BAR __builtin_amdgcn_s_barrier()
; #define PG8_SCHED __builtin_amdgcn_sched_barrier(0)
; template <class Epi, bool ALIGN_EPI>
; __device__ __forceinline__ void gemm_phase(LAS unsigned char* lds, const Gemm g, const StaticOrder& S, const Epi& E) {
;     ...
;             const char* a1 = cA + (size_t)(t + 1) * kstep;
;             const char* a2 = last ? nA : cA + (size_t)(t + 2) * kstep; const char* b2 = last ? nB : cB + (size_t)(t + 2) * kstep;
;             const char* a3 = a2 + kstep; const char* b3 = b2 + kstep;
;             PG8_LDB(B0, 0, 0); PG8_LDB(B1, 0, 1); PG8_SCHED; PG8_LDA(At, 0, 0); PG8_STAGE(PG8_SA(1, 1), a1 + hA, voffA);
;             PG8_WAIT_V(8); PG8_WAIT_L(0); PG8_BAR; PG8_MMA(0, 0, At, B0); PG8_MMA(0, 1, At, B1); PG8_BAR; PG8_SCHED;
;             PG8_LDA(At, 0, 1); PG8_STAGE(PG8_SB(0, 0), b2, voffB); PG8_STAGE(PG8_SB(0, 1), b2 + hB, voffB); PG8_STAGE(PG8_SA(0, 0), a2, voffA);
;             PG8_WAIT_V(8); PG8_WAIT_L(0); PG8_BAR; PG8_MMA(1, 0, At, B0); PG8_MMA(1, 1, At, B1); PG8_BAR; PG8_SCHED;
.LBB0_1094:
	ds_read_b128 v[146:149], v153
	ds_read_b128 v[174:177], v153 offset:1024
	ds_read_b128 v[178:181], v153 offset:2048
	ds_read_b128 v[182:185], v153 offset:3072
	ds_read_b128 v[186:189], v154
	ds_read_b128 v[194:197], v154 offset:1024
	ds_read_b128 v[198:201], v154 offset:2048
	ds_read_b128 v[202:205], v154 offset:3072
	s_add_u32 s36, s4, 0xfff80080
	s_addc_u32 s37, s5, -1
	s_cmp_eq_u32 s38, 28
	s_cselect_b32 s45, s0, s37
	s_cselect_b32 s44, s1, s36
	s_cselect_b32 s37, s2, s29
	s_cselect_b32 s36, s3, s27
	v_lshl_add_u64 v[190:191], s[4:5], 0, v[136:137]
	s_add_i32 m0, s41, 0xc000
	ds_read_b128 v[206:209], v155
	ds_read_b128 v[210:213], v155 offset:1024
	ds_read_b128 v[214:217], v155 offset:2048
	ds_read_b128 v[218:221], v155 offset:3072
	ds_read_b128 v[222:225], v155 offset:4096
	ds_read_b128 v[226:229], v155 offset:5120
	ds_read_b128 v[230:233], v155 offset:6144
	ds_read_b128 v[234:237], v155 offset:7168
	global_load_lds_dwordx4 v[190:191], off
	v_lshl_add_u64 v[190:191], s[4:5], 0, v[138:139]
	s_add_i32 m0, s41, 0xe000
	s_nop 0
	global_load_lds_dwordx4 v[190:191], off
	s_waitcnt vmcnt(8)
	s_waitcnt lgkmcnt(0)
	s_barrier
	s_setprio 1
	s_waitcnt lgkmcnt(0)
	v_mfma_f32_16x16x32_bf16 v[124:127], v[146:149], v[206:209], v[124:127]
	v_mfma_f32_16x16x32_bf16 v[124:127], v[174:177], v[210:213], v[124:127]
	v_mfma_f32_16x16x32_bf16 v[120:123], v[182:185], v[210:213], v[120:123]
	v_mfma_f32_16x16x32_bf16 v[120:123], v[178:181], v[206:209], v[120:123]
	v_mfma_f32_16x16x32_bf16 v[104:107], v[178:181], v[214:217], v[104:107]
	v_mfma_f32_16x16x32_bf16 v[104:107], v[182:185], v[218:221], v[104:107]
	v_mfma_f32_16x16x32_bf16 v[108:111], v[174:177], v[218:221], v[108:111]
	v_mfma_f32_16x16x32_bf16 v[108:111], v[146:149], v[214:217], v[108:111]
	v_mfma_f32_16x16x32_bf16 v[92:95], v[146:149], v[222:225], v[92:95]
	v_mfma_f32_16x16x32_bf16 v[92:95], v[174:177], v[226:229], v[92:95]
	v_mfma_f32_16x16x32_bf16 v[88:91], v[182:185], v[226:229], v[88:91]
	v_mfma_f32_16x16x32_bf16 v[88:91], v[178:181], v[222:225], v[88:91]
	v_mfma_f32_16x16x32_bf16 v[72:75], v[178:181], v[230:233], v[72:75]
	v_mfma_f32_16x16x32_bf16 v[72:75], v[182:185], v[234:237], v[72:75]
	v_mfma_f32_16x16x32_bf16 v[76:79], v[174:177], v[234:237], v[76:79]
	v_mfma_f32_16x16x32_bf16 v[76:79], v[146:149], v[230:233], v[76:79]
	s_setprio 0
	s_setprio 1
	v_mfma_f32_16x16x32_bf16 v[116:119], v[186:189], v[206:209], v[116:119]
	v_mfma_f32_16x16x32_bf16 v[116:119], v[194:197], v[210:213], v[116:119]
	v_mfma_f32_16x16x32_bf16 v[112:115], v[202:205], v[210:213], v[112:115]
	v_mfma_f32_16x16x32_bf16 v[112:115], v[198:201], v[206:209], v[112:115]
	v_mfma_f32_16x16x32_bf16 v[96:99], v[198:201], v[214:217], v[96:99]
	v_mfma_f32_16x16x32_bf16 v[96:99], v[202:205], v[218:221], v[96:99]
	v_mfma_f32_16x16x32_bf16 v[100:103], v[194:197], v[218:221], v[100:103]
	v_mfma_f32_16x16x32_bf16 v[100:103], v[186:189], v[214:217], v[100:103]
	v_mfma_f32_16x16x32_bf16 v[84:87], v[186:189], v[222:225], v[84:87]
	v_mfma_f32_16x16x32_bf16 v[84:87], v[194:197], v[226:229], v[84:87]
	v_mfma_f32_16x16x32_bf16 v[80:83], v[202:205], v[226:229], v[80:83]
	v_mfma_f32_16x16x32_bf16 v[80:83], v[198:201], v[222:225], v[80:83]
	v_mfma_f32_16x16x32_bf16 v[64:67], v[198:201], v[230:233], v[64:67]
	v_mfma_f32_16x16x32_bf16 v[64:67], v[202:205], v[234:237], v[64:67]
	v_mfma_f32_16x16x32_bf16 v[68:71], v[194:197], v[234:237], v[68:71]
	v_mfma_f32_16x16x32_bf16 v[68:71], v[186:189], v[230:233], v[68:71]
	s_setprio 0
	s_barrier
	s_add_i32 s39, s61, s51
	v_lshl_add_u64 v[190:191], s[36:37], 0, v[130:131]
	s_mov_b32 m0, s39
	ds_read_b128 v[206:209], v155 offset:16384
	ds_read_b128 v[210:213], v155 offset:17408
	ds_read_b128 v[214:217], v155 offset:18432
	ds_read_b128 v[218:221], v155 offset:19456
	ds_read_b128 v[222:225], v155 offset:20480
	ds_read_b128 v[226:229], v155 offset:21504
	ds_read_b128 v[230:233], v155 offset:22528
	ds_read_b128 v[234:237], v155 offset:23552
	global_load_lds_dwordx4 v[190:191], off
	s_add_i32 m0, s39, 0x2000
	s_add_u32 s46, s36, 0x80000
	v_lshl_add_u64 v[238:239], s[36:37], 0, v[134:135]
	s_addc_u32 s47, s37, 0
	s_add_i32 s39, s62, s51
	global_load_lds_dwordx4 v[238:239], off
	v_lshl_add_u64 v[240:241], s[46:47], 0, v[130:131]
	s_mov_b32 m0, s39
	v_lshl_add_u64 v[242:243], s[44:45], 0, v[132:133]
	global_load_lds_dwordx4 v[240:241], off
	v_lshl_add_u64 v[240:241], s[46:47], 0, v[134:135]
	s_add_i32 m0, s39, 0x2000
	s_nop 0
	global_load_lds_dwordx4 v[240:241], off
	v_lshl_add_u64 v[240:241], s[44:45], 0, v[128:129]
	s_mov_b32 m0, s41
	s_nop 0
	global_load_lds_dwordx4 v[240:241], off
	s_mov_b32 m0, s43
	s_nop 0
	global_load_lds_dwordx4 v[242:243], off
	s_waitcnt vmcnt(8)
	s_waitcnt lgkmcnt(0)
	s_barrier
; #define PG8_STAGE(bufoff, gbase, voff) do { _Pragma("unroll") for (int _i = 0; _i < 2; ++_i) \
;         __builtin_amdgcn_global_load_lds((const unsigned*)((const char*)(gbase) + (voff)[_i]), (LAS unsigned*)(lds + (bufoff) + ldsw + _i * 8192), 16, 0, 0); } while (0)
; #define PG8_LDA(dst, b, h) do { _Pragma("unroll") for (int m = 0; m < 4; ++m) _Pragma("unroll") for (int k = 0; k < 2; ++k) dst[m][k] = *(const LAS bf16x8*)(lds + PG8_SA(b, h) + aoff + m * 2048 + k * 1024); } while (0)
; #define PG8_LDB(dst, b, h) do { _Pragma("unroll") for (int n = 0; n < 2; ++n) _Pragma("unroll") for (int k = 0; k < 2; ++k) dst[n][k] = *(const LAS bf16x8*)(lds + PG8_SB(b, h) + boff + n * 2048 + k * 1024); } while (0)
; #define PG8_MMA(ai, bj, At, Bt) do { __builtin_amdgcn_s_setprio(1); _Pragma("unroll") for (int m = 0; m < 4; ++m) _Pragma("unroll") for (int n = 0; n < 2; ++n) _Pragma("unroll") for (int k = 0; k < 2; ++k) \
;         acc[ai][bj][m][n] = __builtin_amdgcn_mfma_f32_16x16x32_bf16(Bt[n][k], At[m][k], acc[ai][bj][m][n], 0, 0, 0); __builtin_amdgcn_s_setprio(0); } while (0)
; #define PG8_WAIT_V(n) asm volatile("s_waitcnt vmcnt(" #n ")" ::: "memory")
; #define PG8_WAIT_L(n) asm volatile("s_waitcnt lgkmcnt(" #n ")" ::: "memory")
; #define PG8_BAR __builtin_amdgcn_s_barrier()
; #define PG8_SCHED __builtin_amdgcn_sched_barrier(0)
; template <class Epi, bool ALIGN_EPI>
; __device__ __forceinline__ void gemm_phase(LAS unsigned char* lds, const Gemm g, const StaticOrder& S, const Epi& E) {
;     ...
;             PG8_WAIT_V(8); PG8_WAIT_L(0); PG8_BAR; PG8_MMA(1, 0, At, B0); PG8_MMA(1, 1, At, B1); PG8_BAR; PG8_SCHED;
;             PG8_LDB(B0, 1, 0); PG8_LDB(B1, 1, 1); PG8_SCHED; PG8_LDA(At, 1, 0); PG8_STAGE(PG8_SA(0, 1), a2 + hA, voffA);
;             PG8_WAIT_V(8); PG8_WAIT_L(0); PG8_BAR; PG8_MMA(0, 0, At, B0); PG8_MMA(0, 1, At, B1); PG8_BAR; PG8_SCHED;
	s_setprio 1
	s_waitcnt lgkmcnt(0)
	v_mfma_f32_16x16x32_bf16 v[60:63], v[146:149], v[206:209], v[60:63]
	v_mfma_f32_16x16x32_bf16 v[60:63], v[174:177], v[210:213], v[60:63]
	v_mfma_f32_16x16x32_bf16 v[56:59], v[182:185], v[210:213], v[56:59]
	v_mfma_f32_16x16x32_bf16 v[56:59], v[178:181], v[206:209], v[56:59]
	v_mfma_f32_16x16x32_bf16 v[40:43], v[178:181], v[214:217], v[40:43]
	v_mfma_f32_16x16x32_bf16 v[40:43], v[182:185], v[218:221], v[40:43]
	v_mfma_f32_16x16x32_bf16 v[44:47], v[174:177], v[218:221], v[44:47]
	v_mfma_f32_16x16x32_bf16 v[44:47], v[146:149], v[214:217], v[44:47]
	v_mfma_f32_16x16x32_bf16 v[28:31], v[146:149], v[222:225], v[28:31]
	v_mfma_f32_16x16x32_bf16 v[28:31], v[174:177], v[226:229], v[28:31]
	v_mfma_f32_16x16x32_bf16 v[24:27], v[182:185], v[226:229], v[24:27]
	v_mfma_f32_16x16x32_bf16 v[24:27], v[178:181], v[222:225], v[24:27]
	v_mfma_f32_16x16x32_bf16 v[8:11], v[178:181], v[230:233], v[8:11]
	v_mfma_f32_16x16x32_bf16 v[8:11], v[182:185], v[234:237], v[8:11]
	v_mfma_f32_16x16x32_bf16 v[12:15], v[174:177], v[234:237], v[12:15]
	v_mfma_f32_16x16x32_bf16 v[12:15], v[146:149], v[230:233], v[12:15]
	s_setprio 0
	s_setprio 1
	v_mfma_f32_16x16x32_bf16 v[52:55], v[186:189], v[206:209], v[52:55]
	v_mfma_f32_16x16x32_bf16 v[52:55], v[194:197], v[210:213], v[52:55]
	v_mfma_f32_16x16x32_bf16 v[48:51], v[202:205], v[210:213], v[48:51]
	v_mfma_f32_16x16x32_bf16 v[48:51], v[198:201], v[206:209], v[48:51]
	v_mfma_f32_16x16x32_bf16 v[32:35], v[198:201], v[214:217], v[32:35]
	v_mfma_f32_16x16x32_bf16 v[32:35], v[202:205], v[218:221], v[32:35]
	v_mfma_f32_16x16x32_bf16 v[36:39], v[194:197], v[218:221], v[36:39]
	v_mfma_f32_16x16x32_bf16 v[36:39], v[186:189], v[214:217], v[36:39]
	v_mfma_f32_16x16x32_bf16 v[20:23], v[186:189], v[222:225], v[20:23]
	v_mfma_f32_16x16x32_bf16 v[20:23], v[194:197], v[226:229], v[20:23]
	v_mfma_f32_16x16x32_bf16 v[16:19], v[202:205], v[226:229], v[16:19]
	v_mfma_f32_16x16x32_bf16 v[16:19], v[198:201], v[222:225], v[16:19]
	v_mfma_f32_16x16x32_bf16 v[0:3], v[198:201], v[230:233], v[0:3]
	v_mfma_f32_16x16x32_bf16 v[0:3], v[202:205], v[234:237], v[0:3]
	v_mfma_f32_16x16x32_bf16 v[4:7], v[194:197], v[234:237], v[4:7]
	v_mfma_f32_16x16x32_bf16 v[4:7], v[186:189], v[230:233], v[4:7]
	s_setprio 0
	s_barrier
	s_add_i32 s39, 0, 0x18000
	v_add_u32_e32 v145, s39, v151
	s_add_i32 s46, 0, 0x1c000
	ds_read_b128 v[146:149], v145
	ds_read_b128 v[174:177], v145 offset:1024
	ds_read_b128 v[178:181], v145 offset:2048
	ds_read_b128 v[182:185], v145 offset:3072
	v_add_u32_e32 v145, s46, v151
	ds_read_b128 v[186:189], v145
	ds_read_b128 v[194:197], v145 offset:1024
	ds_read_b128 v[198:201], v145 offset:2048
	ds_read_b128 v[202:205], v145 offset:3072
	s_add_u32 s44, s44, 0x80000
	s_addc_u32 s45, s45, 0
	s_mov_b32 m0, s52
	v_lshl_add_u64 v[244:245], s[44:45], 0, v[128:129]
	ds_read_b128 v[206:209], v155 offset:32768
	ds_read_b128 v[210:213], v155 offset:33792
	ds_read_b128 v[214:217], v155 offset:34816
	ds_read_b128 v[218:221], v155 offset:35840
	ds_read_b128 v[222:225], v155 offset:36864
	ds_read_b128 v[226:229], v155 offset:37888
	ds_read_b128 v[230:233], v155 offset:38912
	ds_read_b128 v[234:237], v155 offset:39936
	global_load_lds_dwordx4 v[244:245], off
	v_lshl_add_u64 v[244:245], s[44:45], 0, v[132:133]
	s_mov_b32 m0, s53
	s_nop 0
	global_load_lds_dwordx4 v[244:245], off
	s_waitcnt vmcnt(8)
	s_waitcnt lgkmcnt(0)
	s_barrier
	s_setprio 1
	s_waitcnt lgkmcnt(0)
	v_mfma_f32_16x16x32_bf16 v[124:127], v[146:149], v[206:209], v[124:127]
	v_mfma_f32_16x16x32_bf16 v[124:127], v[174:177], v[210:213], v[124:127]
	v_mfma_f32_16x16x32_bf16 v[120:123], v[182:185], v[210:213], v[120:123]
	v_mfma_f32_16x16x32_bf16 v[120:123], v[178:181], v[206:209], v[120:123]
	v_mfma_f32_16x16x32_bf16 v[104:107], v[178:181], v[214:217], v[104:107]
	v_mfma_f32_16x16x32_bf16 v[104:107], v[182:185], v[218:221], v[104:107]
	v_mfma_f32_16x16x32_bf16 v[108:111], v[174:177], v[218:221], v[108:111]
	v_mfma_f32_16x16x32_bf16 v[108:111], v[146:149], v[214:217], v[108:111]
	v_mfma_f32_16x16x32_bf16 v[92:95], v[146:149], v[222:225], v[92:95]
	v_mfma_f32_16x16x32_bf16 v[92:95], v[174:177], v[226:229], v[92:95]
	v_mfma_f32_16x16x32_bf16 v[88:91], v[182:185], v[226:229], v[88:91]
	v_mfma_f32_16x16x32_bf16 v[88:91], v[178:181], v[222:225], v[88:91]
	v_mfma_f32_16x16x32_bf16 v[72:75], v[178:181], v[230:233], v[72:75]
	v_mfma_f32_16x16x32_bf16 v[72:75], v[182:185], v[234:237], v[72:75]
	v_mfma_f32_16x16x32_bf16 v[76:79], v[174:177], v[234:237], v[76:79]
	v_mfma_f32_16x16x32_bf16 v[76:79], v[146:149], v[230:233], v[76:79]
	s_setprio 0
	s_setprio 1
	v_mfma_f32_16x16x32_bf16 v[116:119], v[186:189], v[206:209], v[116:119]
	v_mfma_f32_16x16x32_bf16 v[116:119], v[194:197], v[210:213], v[116:119]
	v_mfma_f32_16x16x32_bf16 v[112:115], v[202:205], v[210:213], v[112:115]
	v_mfma_f32_16x16x32_bf16 v[112:115], v[198:201], v[206:209], v[112:115]
	v_mfma_f32_16x16x32_bf16 v[96:99], v[198:201], v[214:217], v[96:99]
	v_mfma_f32_16x16x32_bf16 v[96:99], v[202:205], v[218:221], v[96:99]
	v_mfma_f32_16x16x32_bf16 v[100:103], v[194:197], v[218:221], v[100:103]
	v_mfma_f32_16x16x32_bf16 v[100:103], v[186:189], v[214:217], v[100:103]
	v_mfma_f32_16x16x32_bf16 v[84:87], v[186:189], v[222:225], v[84:87]
	v_mfma_f32_16x16x32_bf16 v[84:87], v[194:197], v[226:229], v[84:87]
	v_mfma_f32_16x16x32_bf16 v[80:83], v[202:205], v[226:229], v[80:83]
	v_mfma_f32_16x16x32_bf16 v[80:83], v[198:201], v[222:225], v[80:83]
	v_mfma_f32_16x16x32_bf16 v[64:67], v[198:201], v[230:233], v[64:67]
	v_mfma_f32_16x16x32_bf16 v[64:67], v[202:205], v[234:237], v[64:67]
	v_mfma_f32_16x16x32_bf16 v[68:71], v[194:197], v[234:237], v[68:71]
	v_mfma_f32_16x16x32_bf16 v[68:71], v[186:189], v[230:233], v[68:71]
	s_setprio 0
	s_barrier
; #define PG8_STAGE(bufoff, gbase, voff) do { _Pragma("unroll") for (int _i = 0; _i < 2; ++_i) \
;         __builtin_amdgcn_global_load_lds((const unsigned*)((const char*)(gbase) + (voff)[_i]), (LAS unsigned*)(lds + (bufoff) + ldsw + _i * 8192), 16, 0, 0); } while (0)
; #define PG8_LDA(dst, b, h) do { _Pragma("unroll") for (int m = 0; m < 4; ++m) _Pragma("unroll") for (int k = 0; k < 2; ++k) dst[m][k] = *(const LAS bf16x8*)(lds + PG8_SA(b, h) + aoff + m * 2048 + k * 1024); } while (0)
; #define PG8_MMA(ai, bj, At, Bt) do { __builtin_amdgcn_s_setprio(1); _Pragma("unroll") for (int m = 0; m < 4; ++m) _Pragma("unroll") for (int n = 0; n < 2; ++n) _Pragma("unroll") for (int k = 0; k < 2; ++k) \
;         acc[ai][bj][m][n] = __builtin_amdgcn_mfma_f32_16x16x32_bf16(Bt[n][k], At[m][k], acc[ai][bj][m][n], 0, 0, 0); __builtin_amdgcn_s_setprio(0); } while (0)
; #define PG8_WAIT_V(n) asm volatile("s_waitcnt vmcnt(" #n ")" ::: "memory")
; #define PG8_WAIT_L(n) asm volatile("s_waitcnt lgkmcnt(" #n ")" ::: "memory")
; #define PG8_BAR __builtin_amdgcn_s_barrier()
; #define PG8_SCHED __builtin_amdgcn_sched_barrier(0)
; template <class Epi, bool ALIGN_EPI>
; __device__ __forceinline__ void gemm_phase(LAS unsigned char* lds, const Gemm g, const StaticOrder& S, const Epi& E) {
;     ...
;             PG8_LDA(At, 1, 1); PG8_STAGE(PG8_SB(1, 0), b3, voffB); PG8_STAGE(PG8_SB(1, 1), b3 + hB, voffB); PG8_STAGE(PG8_SA(1, 0), a3, voffA);
;             PG8_WAIT_V(8); PG8_WAIT_L(0); PG8_BAR; PG8_MMA(1, 0, At, B0); PG8_MMA(1, 1, At, B1); PG8_BAR; PG8_SCHED;
;         }
;         if constexpr (ALIGN_EPI) { if (wr == 0) PG8_BAR; }
	s_add_i32 s39, s39, s51
	v_lshl_add_u64 v[190:191], v[190:191], 0, s[20:21]
	s_mov_b32 m0, s39
	ds_read_b128 v[206:209], v155 offset:49152
	ds_read_b128 v[210:213], v155 offset:50176
	ds_read_b128 v[214:217], v155 offset:51200
	ds_read_b128 v[218:221], v155 offset:52224
	ds_read_b128 v[222:225], v155 offset:53248
	ds_read_b128 v[226:229], v155 offset:54272
	ds_read_b128 v[230:233], v155 offset:55296
	ds_read_b128 v[234:237], v155 offset:56320
	global_load_lds_dwordx4 v[190:191], off
	s_add_i32 m0, s39, 0x2000
	s_add_u32 s36, s36, 0x80080
	v_lshl_add_u64 v[190:191], v[238:239], 0, s[20:21]
	s_addc_u32 s37, s37, 0
	s_add_i32 s39, s46, s51
	global_load_lds_dwordx4 v[190:191], off
	v_lshl_add_u64 v[190:191], s[36:37], 0, v[130:131]
	s_mov_b32 m0, s39
	s_nop 0
	global_load_lds_dwordx4 v[190:191], off
	v_lshl_add_u64 v[190:191], s[36:37], 0, v[134:135]
	s_add_i32 m0, s39, 0x2000
	s_nop 0
	global_load_lds_dwordx4 v[190:191], off
	v_lshl_add_u64 v[190:191], v[240:241], 0, s[20:21]
	s_mov_b32 m0, s57
	s_nop 0
	global_load_lds_dwordx4 v[190:191], off
	v_lshl_add_u64 v[190:191], v[242:243], 0, s[20:21]
	s_mov_b32 m0, s58
	s_nop 0
	global_load_lds_dwordx4 v[190:191], off
	s_waitcnt vmcnt(8)
	s_waitcnt lgkmcnt(0)
	s_barrier
	s_setprio 1
	s_waitcnt lgkmcnt(0)
	v_mfma_f32_16x16x32_bf16 v[60:63], v[146:149], v[206:209], v[60:63]
	v_mfma_f32_16x16x32_bf16 v[60:63], v[174:177], v[210:213], v[60:63]
	v_mfma_f32_16x16x32_bf16 v[56:59], v[182:185], v[210:213], v[56:59]
	v_mfma_f32_16x16x32_bf16 v[56:59], v[178:181], v[206:209], v[56:59]
	v_mfma_f32_16x16x32_bf16 v[40:43], v[178:181], v[214:217], v[40:43]
	v_mfma_f32_16x16x32_bf16 v[40:43], v[182:185], v[218:221], v[40:43]
	v_mfma_f32_16x16x32_bf16 v[44:47], v[174:177], v[218:221], v[44:47]
	v_mfma_f32_16x16x32_bf16 v[44:47], v[146:149], v[214:217], v[44:47]
	v_mfma_f32_16x16x32_bf16 v[28:31], v[146:149], v[222:225], v[28:31]
	v_mfma_f32_16x16x32_bf16 v[28:31], v[174:177], v[226:229], v[28:31]
	v_mfma_f32_16x16x32_bf16 v[24:27], v[182:185], v[226:229], v[24:27]
	v_mfma_f32_16x16x32_bf16 v[24:27], v[178:181], v[222:225], v[24:27]
	v_mfma_f32_16x16x32_bf16 v[8:11], v[178:181], v[230:233], v[8:11]
	v_mfma_f32_16x16x32_bf16 v[8:11], v[182:185], v[234:237], v[8:11]
	v_mfma_f32_16x16x32_bf16 v[12:15], v[174:177], v[234:237], v[12:15]
	v_mfma_f32_16x16x32_bf16 v[12:15], v[146:149], v[230:233], v[12:15]
	s_setprio 0
	s_setprio 1
	v_mfma_f32_16x16x32_bf16 v[52:55], v[186:189], v[206:209], v[52:55]
	v_mfma_f32_16x16x32_bf16 v[52:55], v[194:197], v[210:213], v[52:55]
	v_mfma_f32_16x16x32_bf16 v[48:51], v[202:205], v[210:213], v[48:51]
	v_mfma_f32_16x16x32_bf16 v[48:51], v[198:201], v[206:209], v[48:51]
	v_mfma_f32_16x16x32_bf16 v[32:35], v[198:201], v[214:217], v[32:35]
	v_mfma_f32_16x16x32_bf16 v[32:35], v[202:205], v[218:221], v[32:35]
	v_mfma_f32_16x16x32_bf16 v[36:39], v[194:197], v[218:221], v[36:39]
	v_mfma_f32_16x16x32_bf16 v[36:39], v[186:189], v[214:217], v[36:39]
	v_mfma_f32_16x16x32_bf16 v[20:23], v[186:189], v[222:225], v[20:23]
	v_mfma_f32_16x16x32_bf16 v[20:23], v[194:197], v[226:229], v[20:23]
	v_mfma_f32_16x16x32_bf16 v[16:19], v[202:205], v[226:229], v[16:19]
	v_mfma_f32_16x16x32_bf16 v[16:19], v[198:201], v[222:225], v[16:19]
	v_mfma_f32_16x16x32_bf16 v[0:3], v[198:201], v[230:233], v[0:3]
	v_mfma_f32_16x16x32_bf16 v[0:3], v[202:205], v[234:237], v[0:3]
	v_mfma_f32_16x16x32_bf16 v[4:7], v[194:197], v[234:237], v[4:7]
	v_mfma_f32_16x16x32_bf16 v[4:7], v[186:189], v[230:233], v[4:7]
	s_setprio 0
	s_barrier
	s_add_i32 s38, s38, 2
	s_add_u32 s4, s4, 0x100
	s_addc_u32 s5, s5, 0
	s_add_u32 s27, s27, 0x100
	s_addc_u32 s29, s29, 0
	s_cmp_gt_u32 s38, 29
	s_cbranch_scc0 .LBB0_1094
	s_and_b64 vcc, exec, s[22:23]
	s_cbranch_vccz .LBB0_1097
	s_barrier

; #define PG8_STAGE(bufoff, gbase, voff) do { _Pragma("unroll") for (int _i = 0; _i < 2; ++_i) \
;         __builtin_amdgcn_global_load_lds((const unsigned*)((const char*)(gbase) + (voff)[_i]), (LAS unsigned*)(lds + (bufoff) + ldsw + _i * 8192), 16, 0, 0); } while (0)
; #define PG8_LDA(dst, b, h) do { _Pragma("unroll") for (int m = 0; m < 4; ++m) _Pragma("unroll") for (int k = 0; k < 2; ++k) dst[m][k] = *(const LAS bf16x8*)(lds + PG8_SA(b, h) + aoff + m * 2048 + k * 1024); } while (0)
; #define PG8_LDB(dst, b, h) do { _Pragma("unroll") for (int n = 0; n < 2; ++n) _Pragma("unroll") for (int k = 0; k < 2; ++k) dst[n][k] = *(const LAS bf16x8*)(lds + PG8_SB(b, h) + boff + n * 2048 + k * 1024); } while (0)
; #define PG8_MMA(ai, bj, At, Bt) do { __builtin_amdgcn_s_setprio(1); _Pragma("unroll") for (int m = 0; m < 4; ++m) _Pragma("unroll") for (int n = 0; n < 2; ++n) _Pragma("unroll") for (int k = 0; k < 2; ++k) \
;         acc[ai][bj][m][n] = __builtin_amdgcn_mfma_f32_16x16x32_bf16(Bt[n][k], At[m][k], acc[ai][bj][m][n], 0, 0, 0); __builtin_amdgcn_s_setprio(0); } while (0)
; #define PG8_WAIT_V(n) asm volatile("s_waitcnt vmcnt(" #n ")" ::: "memory")
; #define PG8_WAIT_L(n) asm volatile("s_waitcnt lgkmcnt(" #n ")" ::: "memory")
; #define PG8_BAR __builtin_amdgcn_s_barrier()
; #define PG8_SCHED __builtin_amdgcn_sched_barrier(0)
; template <class Epi, bool ALIGN_EPI>
; __device__ __forceinline__ void gemm_phase(LAS unsigned char* lds, const Gemm g, const StaticOrder& S, const Epi& E) {
;     ...
;             const char* a1 = cA + (size_t)(t + 1) * kstep;
;             const char* a2 = last ? nA : cA + (size_t)(t + 2) * kstep; const char* b2 = last ? nB : cB + (size_t)(t + 2) * kstep;
;             const char* a3 = a2 + kstep; const char* b3 = b2 + kstep;
;             PG8_LDB(B0, 0, 0); PG8_LDB(B1, 0, 1); PG8_SCHED; PG8_LDA(At, 0, 0); PG8_STAGE(PG8_SA(1, 1), a1 + hA, voffA);
;             PG8_WAIT_V(8); PG8_WAIT_L(0); PG8_BAR; PG8_MMA(0, 0, At, B0); PG8_MMA(0, 1, At, B1); PG8_BAR; PG8_SCHED;
;             PG8_LDA(At, 0, 1); PG8_STAGE(PG8_SB(0, 0), b2, voffB); PG8_STAGE(PG8_SB(0, 1), b2 + hB, voffB); PG8_STAGE(PG8_SA(0, 0), a2, voffA);
;             PG8_WAIT_V(8); PG8_WAIT_L(0); PG8_BAR; PG8_MMA(1, 0, At, B0); PG8_MMA(1, 1, At, B1); PG8_BAR; PG8_SCHED;
.LBB0_1585:
	ds_read_b128 v[128:131], v175
	ds_read_b128 v[132:135], v175 offset:1024
	ds_read_b128 v[136:139], v175 offset:2048
	ds_read_b128 v[140:143], v175 offset:3072
	ds_read_b128 v[160:163], v176
	ds_read_b128 v[164:167], v176 offset:1024
	ds_read_b128 v[168:171], v176 offset:2048
	ds_read_b128 v[180:183], v176 offset:3072
	s_add_u32 s40, s36, 0xfff80080
	s_addc_u32 s41, s37, -1
	s_cmp_eq_u32 s57, 28
	s_cselect_b32 s43, s25, s41
	s_cselect_b32 s42, s31, s40
	s_cselect_b32 s41, s23, s56
	s_cselect_b32 s40, s54, s55
	v_lshl_add_u64 v[218:219], s[36:37], 0, v[152:153]
	s_add_i32 m0, s35, 0xc000
	ds_read_b128 v[184:187], v177
	ds_read_b128 v[188:191], v177 offset:1024
	ds_read_b128 v[194:197], v177 offset:2048
	ds_read_b128 v[198:201], v177 offset:3072
	ds_read_b128 v[202:205], v177 offset:4096
	ds_read_b128 v[206:209], v177 offset:5120
	ds_read_b128 v[210:213], v177 offset:6144
	ds_read_b128 v[214:217], v177 offset:7168
	global_load_lds_dwordx4 v[218:219], off
	v_lshl_add_u64 v[218:219], s[36:37], 0, v[154:155]
	s_add_i32 m0, s35, 0xe000
	s_nop 0
	global_load_lds_dwordx4 v[218:219], off
	s_waitcnt vmcnt(8)
	s_waitcnt lgkmcnt(0)
	s_barrier
	s_setprio 1
	s_waitcnt lgkmcnt(0)
	v_mfma_f32_16x16x32_bf16 v[124:127], v[128:131], v[184:187], v[124:127]
	v_mfma_f32_16x16x32_bf16 v[124:127], v[132:135], v[188:191], v[124:127]
	v_mfma_f32_16x16x32_bf16 v[120:123], v[140:143], v[188:191], v[120:123]
	v_mfma_f32_16x16x32_bf16 v[120:123], v[136:139], v[184:187], v[120:123]
	v_mfma_f32_16x16x32_bf16 v[104:107], v[136:139], v[194:197], v[104:107]
	v_mfma_f32_16x16x32_bf16 v[104:107], v[140:143], v[198:201], v[104:107]
	v_mfma_f32_16x16x32_bf16 v[112:115], v[132:135], v[198:201], v[112:115]
	v_mfma_f32_16x16x32_bf16 v[112:115], v[128:131], v[194:197], v[112:115]
	v_mfma_f32_16x16x32_bf16 v[92:95], v[128:131], v[202:205], v[92:95]
	v_mfma_f32_16x16x32_bf16 v[92:95], v[132:135], v[206:209], v[92:95]
	v_mfma_f32_16x16x32_bf16 v[88:91], v[140:143], v[206:209], v[88:91]
	v_mfma_f32_16x16x32_bf16 v[88:91], v[136:139], v[202:205], v[88:91]
	v_mfma_f32_16x16x32_bf16 v[72:75], v[136:139], v[210:213], v[72:75]
	v_mfma_f32_16x16x32_bf16 v[72:75], v[140:143], v[214:217], v[72:75]
	v_mfma_f32_16x16x32_bf16 v[76:79], v[132:135], v[214:217], v[76:79]
	v_mfma_f32_16x16x32_bf16 v[76:79], v[128:131], v[210:213], v[76:79]
	s_setprio 0
	s_setprio 1
	v_mfma_f32_16x16x32_bf16 v[116:119], v[160:163], v[184:187], v[116:119]
	v_mfma_f32_16x16x32_bf16 v[116:119], v[164:167], v[188:191], v[116:119]
	v_mfma_f32_16x16x32_bf16 v[108:111], v[180:183], v[188:191], v[108:111]
	v_mfma_f32_16x16x32_bf16 v[108:111], v[168:171], v[184:187], v[108:111]
	v_mfma_f32_16x16x32_bf16 v[96:99], v[168:171], v[194:197], v[96:99]
	v_mfma_f32_16x16x32_bf16 v[96:99], v[180:183], v[198:201], v[96:99]
	v_mfma_f32_16x16x32_bf16 v[100:103], v[164:167], v[198:201], v[100:103]
	v_mfma_f32_16x16x32_bf16 v[100:103], v[160:163], v[194:197], v[100:103]
	v_mfma_f32_16x16x32_bf16 v[84:87], v[160:163], v[202:205], v[84:87]
	v_mfma_f32_16x16x32_bf16 v[84:87], v[164:167], v[206:209], v[84:87]
	v_mfma_f32_16x16x32_bf16 v[80:83], v[180:183], v[206:209], v[80:83]
	v_mfma_f32_16x16x32_bf16 v[80:83], v[168:171], v[202:205], v[80:83]
	v_mfma_f32_16x16x32_bf16 v[64:67], v[168:171], v[210:213], v[64:67]
	v_mfma_f32_16x16x32_bf16 v[64:67], v[180:183], v[214:217], v[64:67]
	v_mfma_f32_16x16x32_bf16 v[68:71], v[164:167], v[214:217], v[68:71]
	v_mfma_f32_16x16x32_bf16 v[68:71], v[160:163], v[210:213], v[68:71]
	s_setprio 0
	s_barrier
	s_add_i32 s58, s51, s33
	v_lshl_add_u64 v[218:219], s[40:41], 0, v[146:147]
	s_mov_b32 m0, s58
	ds_read_b128 v[184:187], v177 offset:16384
	ds_read_b128 v[188:191], v177 offset:17408
	ds_read_b128 v[194:197], v177 offset:18432
	ds_read_b128 v[198:201], v177 offset:19456
	ds_read_b128 v[202:205], v177 offset:20480
	ds_read_b128 v[206:209], v177 offset:21504
	ds_read_b128 v[210:213], v177 offset:22528
	ds_read_b128 v[214:217], v177 offset:23552
	global_load_lds_dwordx4 v[218:219], off
	s_add_i32 m0, s58, 0x2000
	s_add_u32 s58, s40, 0x80000
	v_lshl_add_u64 v[220:221], s[40:41], 0, v[150:151]
	s_addc_u32 s59, s41, 0
	s_add_i32 s60, s52, s33
	global_load_lds_dwordx4 v[220:221], off
	v_lshl_add_u64 v[222:223], s[58:59], 0, v[146:147]
	s_mov_b32 m0, s60
	v_lshl_add_u64 v[224:225], s[42:43], 0, v[148:149]
	global_load_lds_dwordx4 v[222:223], off
	v_lshl_add_u64 v[222:223], s[58:59], 0, v[150:151]
	s_add_i32 m0, s60, 0x2000
	s_nop 0
	global_load_lds_dwordx4 v[222:223], off
	v_lshl_add_u64 v[222:223], s[42:43], 0, v[144:145]
	s_mov_b32 m0, s35
	s_nop 0
	global_load_lds_dwordx4 v[222:223], off
	s_mov_b32 m0, s38
	s_nop 0
	global_load_lds_dwordx4 v[224:225], off
	s_waitcnt vmcnt(8)
	s_waitcnt lgkmcnt(0)
	s_barrier
; #define PG8_STAGE(bufoff, gbase, voff) do { _Pragma("unroll") for (int _i = 0; _i < 2; ++_i) \
;         __builtin_amdgcn_global_load_lds((const unsigned*)((const char*)(gbase) + (voff)[_i]), (LAS unsigned*)(lds + (bufoff) + ldsw + _i * 8192), 16, 0, 0); } while (0)
; #define PG8_LDA(dst, b, h) do { _Pragma("unroll") for (int m = 0; m < 4; ++m) _Pragma("unroll") for (int k = 0; k < 2; ++k) dst[m][k] = *(const LAS bf16x8*)(lds + PG8_SA(b, h) + aoff + m * 2048 + k * 1024); } while (0)
; #define PG8_LDB(dst, b, h) do { _Pragma("unroll") for (int n = 0; n < 2; ++n) _Pragma("unroll") for (int k = 0; k < 2; ++k) dst[n][k] = *(const LAS bf16x8*)(lds + PG8_SB(b, h) + boff + n * 2048 + k * 1024); } while (0)
; #define PG8_MMA(ai, bj, At, Bt) do { __builtin_amdgcn_s_setprio(1); _Pragma("unroll") for (int m = 0; m < 4; ++m) _Pragma("unroll") for (int n = 0; n < 2; ++n) _Pragma("unroll") for (int k = 0; k < 2; ++k) \
;         acc[ai][bj][m][n] = __builtin_amdgcn_mfma_f32_16x16x32_bf16(Bt[n][k], At[m][k], acc[ai][bj][m][n], 0, 0, 0); __builtin_amdgcn_s_setprio(0); } while (0)
; #define PG8_WAIT_V(n) asm volatile("s_waitcnt vmcnt(" #n ")" ::: "memory")
; #define PG8_WAIT_L(n) asm volatile("s_waitcnt lgkmcnt(" #n ")" ::: "memory")
; #define PG8_BAR __builtin_amdgcn_s_barrier()
; #define PG8_SCHED __builtin_amdgcn_sched_barrier(0)
; template <class Epi, bool ALIGN_EPI>
; __device__ __forceinline__ void gemm_phase(LAS unsigned char* lds, const Gemm g, const StaticOrder& S, const Epi& E) {
;     ...
;             PG8_WAIT_V(8); PG8_WAIT_L(0); PG8_BAR; PG8_MMA(1, 0, At, B0); PG8_MMA(1, 1, At, B1); PG8_BAR; PG8_SCHED;
;             PG8_LDB(B0, 1, 0); PG8_LDB(B1, 1, 1); PG8_SCHED; PG8_LDA(At, 1, 0); PG8_STAGE(PG8_SA(0, 1), a2 + hA, voffA);
;             PG8_WAIT_V(8); PG8_WAIT_L(0); PG8_BAR; PG8_MMA(0, 0, At, B0); PG8_MMA(0, 1, At, B1); PG8_BAR; PG8_SCHED;
	s_setprio 1
	s_waitcnt lgkmcnt(0)
	v_mfma_f32_16x16x32_bf16 v[60:63], v[128:131], v[184:187], v[60:63]
	v_mfma_f32_16x16x32_bf16 v[60:63], v[132:135], v[188:191], v[60:63]
	v_mfma_f32_16x16x32_bf16 v[56:59], v[140:143], v[188:191], v[56:59]
	v_mfma_f32_16x16x32_bf16 v[56:59], v[136:139], v[184:187], v[56:59]
	v_mfma_f32_16x16x32_bf16 v[40:43], v[136:139], v[194:197], v[40:43]
	v_mfma_f32_16x16x32_bf16 v[40:43], v[140:143], v[198:201], v[40:43]
	v_mfma_f32_16x16x32_bf16 v[44:47], v[132:135], v[198:201], v[44:47]
	v_mfma_f32_16x16x32_bf16 v[44:47], v[128:131], v[194:197], v[44:47]
	v_mfma_f32_16x16x32_bf16 v[28:31], v[128:131], v[202:205], v[28:31]
	v_mfma_f32_16x16x32_bf16 v[28:31], v[132:135], v[206:209], v[28:31]
	v_mfma_f32_16x16x32_bf16 v[24:27], v[140:143], v[206:209], v[24:27]
	v_mfma_f32_16x16x32_bf16 v[24:27], v[136:139], v[202:205], v[24:27]
	v_mfma_f32_16x16x32_bf16 v[8:11], v[136:139], v[210:213], v[8:11]
	v_mfma_f32_16x16x32_bf16 v[8:11], v[140:143], v[214:217], v[8:11]
	v_mfma_f32_16x16x32_bf16 v[12:15], v[132:135], v[214:217], v[12:15]
	v_mfma_f32_16x16x32_bf16 v[12:15], v[128:131], v[210:213], v[12:15]
	s_setprio 0
	s_setprio 1
	v_mfma_f32_16x16x32_bf16 v[52:55], v[160:163], v[184:187], v[52:55]
	v_mfma_f32_16x16x32_bf16 v[52:55], v[164:167], v[188:191], v[52:55]
	v_mfma_f32_16x16x32_bf16 v[48:51], v[180:183], v[188:191], v[48:51]
	v_mfma_f32_16x16x32_bf16 v[48:51], v[168:171], v[184:187], v[48:51]
	v_mfma_f32_16x16x32_bf16 v[32:35], v[168:171], v[194:197], v[32:35]
	v_mfma_f32_16x16x32_bf16 v[32:35], v[180:183], v[198:201], v[32:35]
	v_mfma_f32_16x16x32_bf16 v[36:39], v[164:167], v[198:201], v[36:39]
	v_mfma_f32_16x16x32_bf16 v[36:39], v[160:163], v[194:197], v[36:39]
	v_mfma_f32_16x16x32_bf16 v[20:23], v[160:163], v[202:205], v[20:23]
	v_mfma_f32_16x16x32_bf16 v[20:23], v[164:167], v[206:209], v[20:23]
	v_mfma_f32_16x16x32_bf16 v[16:19], v[180:183], v[206:209], v[16:19]
	v_mfma_f32_16x16x32_bf16 v[16:19], v[168:171], v[202:205], v[16:19]
	v_mfma_f32_16x16x32_bf16 v[0:3], v[168:171], v[210:213], v[0:3]
	v_mfma_f32_16x16x32_bf16 v[0:3], v[180:183], v[214:217], v[0:3]
	v_mfma_f32_16x16x32_bf16 v[4:7], v[164:167], v[214:217], v[4:7]
	v_mfma_f32_16x16x32_bf16 v[4:7], v[160:163], v[210:213], v[4:7]
	s_setprio 0
	s_barrier
	s_add_i32 s58, 0, 0x18000
	s_add_i32 s59, 0, 0x1c000
	v_add_u32_e32 v140, s58, v173
	v_add_u32_e32 v179, s59, v173
	ds_read_b128 v[128:131], v140
	ds_read_b128 v[132:135], v140 offset:1024
	ds_read_b128 v[136:139], v140 offset:2048
	ds_read_b128 v[140:143], v140 offset:3072
	ds_read_b128 v[160:163], v179
	ds_read_b128 v[164:167], v179 offset:1024
	ds_read_b128 v[168:171], v179 offset:2048
	ds_read_b128 v[180:183], v179 offset:3072
	s_add_u32 s42, s42, 0x80000
	s_addc_u32 s43, s43, 0
	s_mov_b32 m0, s39
	v_lshl_add_u64 v[226:227], s[42:43], 0, v[144:145]
	ds_read_b128 v[184:187], v177 offset:32768
	ds_read_b128 v[188:191], v177 offset:33792
	ds_read_b128 v[194:197], v177 offset:34816
	ds_read_b128 v[198:201], v177 offset:35840
	ds_read_b128 v[202:205], v177 offset:36864
	ds_read_b128 v[206:209], v177 offset:37888
	ds_read_b128 v[210:213], v177 offset:38912
	ds_read_b128 v[214:217], v177 offset:39936
	global_load_lds_dwordx4 v[226:227], off
	v_lshl_add_u64 v[226:227], s[42:43], 0, v[148:149]
	s_mov_b32 m0, s44
	s_nop 0
	global_load_lds_dwordx4 v[226:227], off
	s_waitcnt vmcnt(8)
	s_waitcnt lgkmcnt(0)
	s_barrier
	s_setprio 1
	s_waitcnt lgkmcnt(0)
	v_mfma_f32_16x16x32_bf16 v[124:127], v[128:131], v[184:187], v[124:127]
	v_mfma_f32_16x16x32_bf16 v[124:127], v[132:135], v[188:191], v[124:127]
	v_mfma_f32_16x16x32_bf16 v[120:123], v[140:143], v[188:191], v[120:123]
	v_mfma_f32_16x16x32_bf16 v[120:123], v[136:139], v[184:187], v[120:123]
	v_mfma_f32_16x16x32_bf16 v[104:107], v[136:139], v[194:197], v[104:107]
	v_mfma_f32_16x16x32_bf16 v[104:107], v[140:143], v[198:201], v[104:107]
	v_mfma_f32_16x16x32_bf16 v[112:115], v[132:135], v[198:201], v[112:115]
	v_mfma_f32_16x16x32_bf16 v[112:115], v[128:131], v[194:197], v[112:115]
	v_mfma_f32_16x16x32_bf16 v[92:95], v[128:131], v[202:205], v[92:95]
	v_mfma_f32_16x16x32_bf16 v[92:95], v[132:135], v[206:209], v[92:95]
	v_mfma_f32_16x16x32_bf16 v[88:91], v[140:143], v[206:209], v[88:91]
	v_mfma_f32_16x16x32_bf16 v[88:91], v[136:139], v[202:205], v[88:91]
	v_mfma_f32_16x16x32_bf16 v[72:75], v[136:139], v[210:213], v[72:75]
	v_mfma_f32_16x16x32_bf16 v[72:75], v[140:143], v[214:217], v[72:75]
	v_mfma_f32_16x16x32_bf16 v[76:79], v[132:135], v[214:217], v[76:79]
	v_mfma_f32_16x16x32_bf16 v[76:79], v[128:131], v[210:213], v[76:79]
	s_setprio 0
	s_setprio 1
	v_mfma_f32_16x16x32_bf16 v[116:119], v[160:163], v[184:187], v[116:119]
	v_mfma_f32_16x16x32_bf16 v[116:119], v[164:167], v[188:191], v[116:119]
	v_mfma_f32_16x16x32_bf16 v[108:111], v[180:183], v[188:191], v[108:111]
	v_mfma_f32_16x16x32_bf16 v[108:111], v[168:171], v[184:187], v[108:111]
	v_mfma_f32_16x16x32_bf16 v[96:99], v[168:171], v[194:197], v[96:99]
	v_mfma_f32_16x16x32_bf16 v[96:99], v[180:183], v[198:201], v[96:99]
	v_mfma_f32_16x16x32_bf16 v[100:103], v[164:167], v[198:201], v[100:103]
	v_mfma_f32_16x16x32_bf16 v[100:103], v[160:163], v[194:197], v[100:103]
	v_mfma_f32_16x16x32_bf16 v[84:87], v[160:163], v[202:205], v[84:87]
	v_mfma_f32_16x16x32_bf16 v[84:87], v[164:167], v[206:209], v[84:87]
	v_mfma_f32_16x16x32_bf16 v[80:83], v[180:183], v[206:209], v[80:83]
	v_mfma_f32_16x16x32_bf16 v[80:83], v[168:171], v[202:205], v[80:83]
	v_mfma_f32_16x16x32_bf16 v[64:67], v[168:171], v[210:213], v[64:67]
	v_mfma_f32_16x16x32_bf16 v[64:67], v[180:183], v[214:217], v[64:67]
	v_mfma_f32_16x16x32_bf16 v[68:71], v[164:167], v[214:217], v[68:71]
	v_mfma_f32_16x16x32_bf16 v[68:71], v[160:163], v[210:213], v[68:71]
	s_setprio 0
	s_barrier
; #define PG8_STAGE(bufoff, gbase, voff) do { _Pragma("unroll") for (int _i = 0; _i < 2; ++_i) \
;         __builtin_amdgcn_global_load_lds((const unsigned*)((const char*)(gbase) + (voff)[_i]), (LAS unsigned*)(lds + (bufoff) + ldsw + _i * 8192), 16, 0, 0); } while (0)
; #define PG8_LDA(dst, b, h) do { _Pragma("unroll") for (int m = 0; m < 4; ++m) _Pragma("unroll") for (int k = 0; k < 2; ++k) dst[m][k] = *(const LAS bf16x8*)(lds + PG8_SA(b, h) + aoff + m * 2048 + k * 1024); } while (0)
; #define PG8_MMA(ai, bj, At, Bt) do { __builtin_amdgcn_s_setprio(1); _Pragma("unroll") for (int m = 0; m < 4; ++m) _Pragma("unroll") for (int n = 0; n < 2; ++n) _Pragma("unroll") for (int k = 0; k < 2; ++k) \
;         acc[ai][bj][m][n] = __builtin_amdgcn_mfma_f32_16x16x32_bf16(Bt[n][k], At[m][k], acc[ai][bj][m][n], 0, 0, 0); __builtin_amdgcn_s_setprio(0); } while (0)
; #define PG8_WAIT_V(n) asm volatile("s_waitcnt vmcnt(" #n ")" ::: "memory")
; #define PG8_WAIT_L(n) asm volatile("s_waitcnt lgkmcnt(" #n ")" ::: "memory")
; #define PG8_BAR __builtin_amdgcn_s_barrier()
; #define PG8_SCHED __builtin_amdgcn_sched_barrier(0)
; template <class Epi, bool ALIGN_EPI>
; __device__ __forceinline__ void gemm_phase(LAS unsigned char* lds, const Gemm g, const StaticOrder& S, const Epi& E) {
;     ...
;             PG8_LDA(At, 1, 1); PG8_STAGE(PG8_SB(1, 0), b3, voffB); PG8_STAGE(PG8_SB(1, 1), b3 + hB, voffB); PG8_STAGE(PG8_SA(1, 0), a3, voffA);
;             PG8_WAIT_V(8); PG8_WAIT_L(0); PG8_BAR; PG8_MMA(1, 0, At, B0); PG8_MMA(1, 1, At, B1); PG8_BAR; PG8_SCHED;
;         }
;         if constexpr (ALIGN_EPI) { if (wr == 0) PG8_BAR; }
	s_add_i32 s42, s58, s33
	v_lshl_add_u64 v[218:219], v[218:219], 0, s[18:19]
	s_mov_b32 m0, s42
	ds_read_b128 v[184:187], v177 offset:49152
	ds_read_b128 v[188:191], v177 offset:50176
	ds_read_b128 v[194:197], v177 offset:51200
	ds_read_b128 v[198:201], v177 offset:52224
	ds_read_b128 v[202:205], v177 offset:53248
	ds_read_b128 v[206:209], v177 offset:54272
	ds_read_b128 v[210:213], v177 offset:55296
	ds_read_b128 v[214:217], v177 offset:56320
	global_load_lds_dwordx4 v[218:219], off
	s_add_i32 m0, s42, 0x2000
	s_add_u32 s40, s40, 0x80080
	v_lshl_add_u64 v[218:219], v[220:221], 0, s[18:19]
	s_addc_u32 s41, s41, 0
	s_add_i32 s42, s59, s33
	global_load_lds_dwordx4 v[218:219], off
	v_lshl_add_u64 v[218:219], s[40:41], 0, v[146:147]
	s_mov_b32 m0, s42
	s_nop 0
	global_load_lds_dwordx4 v[218:219], off
	v_lshl_add_u64 v[218:219], s[40:41], 0, v[150:151]
	s_add_i32 m0, s42, 0x2000
	s_nop 0
	global_load_lds_dwordx4 v[218:219], off
	v_lshl_add_u64 v[218:219], v[222:223], 0, s[18:19]
	s_mov_b32 m0, s48
	s_nop 0
	global_load_lds_dwordx4 v[218:219], off
	v_lshl_add_u64 v[218:219], v[224:225], 0, s[18:19]
	s_mov_b32 m0, s49
	s_nop 0
	global_load_lds_dwordx4 v[218:219], off
	s_waitcnt vmcnt(8)
	s_waitcnt lgkmcnt(0)
	s_barrier
	s_setprio 1
	s_waitcnt lgkmcnt(0)
	v_mfma_f32_16x16x32_bf16 v[60:63], v[128:131], v[184:187], v[60:63]
	v_mfma_f32_16x16x32_bf16 v[60:63], v[132:135], v[188:191], v[60:63]
	v_mfma_f32_16x16x32_bf16 v[56:59], v[140:143], v[188:191], v[56:59]
	v_mfma_f32_16x16x32_bf16 v[56:59], v[136:139], v[184:187], v[56:59]
	v_mfma_f32_16x16x32_bf16 v[40:43], v[136:139], v[194:197], v[40:43]
	v_mfma_f32_16x16x32_bf16 v[40:43], v[140:143], v[198:201], v[40:43]
	v_mfma_f32_16x16x32_bf16 v[44:47], v[132:135], v[198:201], v[44:47]
	v_mfma_f32_16x16x32_bf16 v[44:47], v[128:131], v[194:197], v[44:47]
	v_mfma_f32_16x16x32_bf16 v[28:31], v[128:131], v[202:205], v[28:31]
	v_mfma_f32_16x16x32_bf16 v[28:31], v[132:135], v[206:209], v[28:31]
	v_mfma_f32_16x16x32_bf16 v[24:27], v[140:143], v[206:209], v[24:27]
	v_mfma_f32_16x16x32_bf16 v[24:27], v[136:139], v[202:205], v[24:27]
	v_mfma_f32_16x16x32_bf16 v[8:11], v[136:139], v[210:213], v[8:11]
	v_mfma_f32_16x16x32_bf16 v[8:11], v[140:143], v[214:217], v[8:11]
	v_mfma_f32_16x16x32_bf16 v[12:15], v[132:135], v[214:217], v[12:15]
	v_mfma_f32_16x16x32_bf16 v[12:15], v[128:131], v[210:213], v[12:15]
	s_setprio 0
	s_setprio 1
	v_mfma_f32_16x16x32_bf16 v[52:55], v[160:163], v[184:187], v[52:55]
	v_mfma_f32_16x16x32_bf16 v[52:55], v[164:167], v[188:191], v[52:55]
	v_mfma_f32_16x16x32_bf16 v[48:51], v[180:183], v[188:191], v[48:51]
	v_mfma_f32_16x16x32_bf16 v[48:51], v[168:171], v[184:187], v[48:51]
	v_mfma_f32_16x16x32_bf16 v[32:35], v[168:171], v[194:197], v[32:35]
	v_mfma_f32_16x16x32_bf16 v[32:35], v[180:183], v[198:201], v[32:35]
	v_mfma_f32_16x16x32_bf16 v[36:39], v[164:167], v[198:201], v[36:39]
	v_mfma_f32_16x16x32_bf16 v[36:39], v[160:163], v[194:197], v[36:39]
	v_mfma_f32_16x16x32_bf16 v[20:23], v[160:163], v[202:205], v[20:23]
	v_mfma_f32_16x16x32_bf16 v[20:23], v[164:167], v[206:209], v[20:23]
	v_mfma_f32_16x16x32_bf16 v[16:19], v[180:183], v[206:209], v[16:19]
	v_mfma_f32_16x16x32_bf16 v[16:19], v[168:171], v[202:205], v[16:19]
	v_mfma_f32_16x16x32_bf16 v[0:3], v[168:171], v[210:213], v[0:3]
	v_mfma_f32_16x16x32_bf16 v[0:3], v[180:183], v[214:217], v[0:3]
	v_mfma_f32_16x16x32_bf16 v[4:7], v[164:167], v[214:217], v[4:7]
	v_mfma_f32_16x16x32_bf16 v[4:7], v[160:163], v[210:213], v[4:7]
	s_setprio 0
	s_barrier
	s_add_i32 s57, s57, 2
	s_add_u32 s36, s36, 0x100
	s_addc_u32 s37, s37, 0
	s_add_u32 s55, s55, 0x100
	s_addc_u32 s56, s56, 0
	s_cmp_gt_u32 s57, 29
	s_cbranch_scc0 .LBB0_1585
	s_and_b64 vcc, exec, s[20:21]
	s_cbranch_vccz .LBB0_1588
	s_barrier

; #define PG8_STAGE(bufoff, gbase, voff) do { _Pragma("unroll") for (int _i = 0; _i < 2; ++_i) \
;         __builtin_amdgcn_global_load_lds((const unsigned*)((const char*)(gbase) + (voff)[_i]), (LAS unsigned*)(lds + (bufoff) + ldsw + _i * 8192), 16, 0, 0); } while (0)
; #define PG8_LDA(dst, b, h) do { _Pragma("unroll") for (int m = 0; m < 4; ++m) _Pragma("unroll") for (int k = 0; k < 2; ++k) dst[m][k] = *(const LAS bf16x8*)(lds + PG8_SA(b, h) + aoff + m * 2048 + k * 1024); } while (0)
; #define PG8_LDB(dst, b, h) do { _Pragma("unroll") for (int n = 0; n < 2; ++n) _Pragma("unroll") for (int k = 0; k < 2; ++k) dst[n][k] = *(const LAS bf16x8*)(lds + PG8_SB(b, h) + boff + n * 2048 + k * 1024); } while (0)
; #define PG8_MMA(ai, bj, At, Bt) do { __builtin_amdgcn_s_setprio(1); _Pragma("unroll") for (int m = 0; m < 4; ++m) _Pragma("unroll") for (int n = 0; n < 2; ++n) _Pragma("unroll") for (int k = 0; k < 2; ++k) \
;         acc[ai][bj][m][n] = __builtin_amdgcn_mfma_f32_16x16x32_bf16(Bt[n][k], At[m][k], acc[ai][bj][m][n], 0, 0, 0); __builtin_amdgcn_s_setprio(0); } while (0)
; #define PG8_WAIT_V(n) asm volatile("s_waitcnt vmcnt(" #n ")" ::: "memory")
; #define PG8_WAIT_L(n) asm volatile("s_waitcnt lgkmcnt(" #n ")" ::: "memory")
; #define PG8_BAR __builtin_amdgcn_s_barrier()
; #define PG8_SCHED __builtin_amdgcn_sched_barrier(0)
; template <class Epi, bool ALIGN_EPI>
; __device__ __forceinline__ void gemm_phase(LAS unsigned char* lds, const Gemm g, const StaticOrder& S, const Epi& E) {
;     ...
;             const char* a1 = cA + (size_t)(t + 1) * kstep;
;             const char* a2 = last ? nA : cA + (size_t)(t + 2) * kstep; const char* b2 = last ? nB : cB + (size_t)(t + 2) * kstep;
;             const char* a3 = a2 + kstep; const char* b3 = b2 + kstep;
;             PG8_LDB(B0, 0, 0); PG8_LDB(B1, 0, 1); PG8_SCHED; PG8_LDA(At, 0, 0); PG8_STAGE(PG8_SA(1, 1), a1 + hA, voffA);
;             PG8_WAIT_V(8); PG8_WAIT_L(0); PG8_BAR; PG8_MMA(0, 0, At, B0); PG8_MMA(0, 1, At, B1); PG8_BAR; PG8_SCHED;
;             PG8_LDA(At, 0, 1); PG8_STAGE(PG8_SB(0, 0), b2, voffB); PG8_STAGE(PG8_SB(0, 1), b2 + hB, voffB); PG8_STAGE(PG8_SA(0, 0), a2, voffA);
;             PG8_WAIT_V(8); PG8_WAIT_L(0); PG8_BAR; PG8_MMA(1, 0, At, B0); PG8_MMA(1, 1, At, B1); PG8_BAR; PG8_SCHED;
.LBB0_1755:
	ds_read_b128 v[128:131], v183
	ds_read_b128 v[132:135], v183 offset:1024
	ds_read_b128 v[152:155], v183 offset:2048
	ds_read_b128 v[156:159], v183 offset:3072
	ds_read_b128 v[160:163], v184
	ds_read_b128 v[164:167], v184 offset:1024
	ds_read_b128 v[168:171], v184 offset:2048
	ds_read_b128 v[172:175], v184 offset:3072
	s_add_u32 s30, s28, 0xffe00080
	s_addc_u32 s31, s29, -1
	s_cmpk_eq_i32 s51, 0x7c
	s_cselect_b32 s35, s5, s31
	s_cselect_b32 s34, s21, s30
	s_cselect_b32 s31, s19, s50
	s_cselect_b32 s30, s48, s49
	v_lshl_add_u64 v[214:215], s[28:29], 0, v[144:145]
	s_add_i32 m0, s27, 0xc000
	ds_read_b128 v[176:179], v185
	ds_read_b128 v[186:189], v185 offset:1024
	ds_read_b128 v[190:193], v185 offset:2048
	ds_read_b128 v[194:197], v185 offset:3072
	ds_read_b128 v[198:201], v185 offset:4096
	ds_read_b128 v[202:205], v185 offset:5120
	ds_read_b128 v[206:209], v185 offset:6144
	ds_read_b128 v[210:213], v185 offset:7168
	global_load_lds_dwordx4 v[214:215], off
	v_lshl_add_u64 v[214:215], s[28:29], 0, v[146:147]
	s_add_i32 m0, s27, 0xe000
	s_nop 0
	global_load_lds_dwordx4 v[214:215], off
	s_waitcnt vmcnt(8)
	s_waitcnt lgkmcnt(0)
	s_barrier
	s_setprio 1
	s_waitcnt lgkmcnt(0)
	v_mfma_f32_16x16x32_bf16 v[120:123], v[128:131], v[176:179], v[120:123]
	v_mfma_f32_16x16x32_bf16 v[120:123], v[132:135], v[186:189], v[120:123]
	v_mfma_f32_16x16x32_bf16 v[124:127], v[156:159], v[186:189], v[124:127]
	v_mfma_f32_16x16x32_bf16 v[124:127], v[152:155], v[176:179], v[124:127]
	v_mfma_f32_16x16x32_bf16 v[108:111], v[152:155], v[190:193], v[108:111]
	v_mfma_f32_16x16x32_bf16 v[108:111], v[156:159], v[194:197], v[108:111]
	v_mfma_f32_16x16x32_bf16 v[104:107], v[132:135], v[194:197], v[104:107]
	v_mfma_f32_16x16x32_bf16 v[104:107], v[128:131], v[190:193], v[104:107]
	v_mfma_f32_16x16x32_bf16 v[88:91], v[128:131], v[198:201], v[88:91]
	v_mfma_f32_16x16x32_bf16 v[88:91], v[132:135], v[202:205], v[88:91]
	v_mfma_f32_16x16x32_bf16 v[92:95], v[156:159], v[202:205], v[92:95]
	v_mfma_f32_16x16x32_bf16 v[92:95], v[152:155], v[198:201], v[92:95]
	v_mfma_f32_16x16x32_bf16 v[76:79], v[152:155], v[206:209], v[76:79]
	v_mfma_f32_16x16x32_bf16 v[76:79], v[156:159], v[210:213], v[76:79]
	v_mfma_f32_16x16x32_bf16 v[72:75], v[132:135], v[210:213], v[72:75]
	v_mfma_f32_16x16x32_bf16 v[72:75], v[128:131], v[206:209], v[72:75]
	s_setprio 0
	s_setprio 1
	v_mfma_f32_16x16x32_bf16 v[112:115], v[160:163], v[176:179], v[112:115]
	v_mfma_f32_16x16x32_bf16 v[112:115], v[164:167], v[186:189], v[112:115]
	v_mfma_f32_16x16x32_bf16 v[116:119], v[172:175], v[186:189], v[116:119]
	v_mfma_f32_16x16x32_bf16 v[116:119], v[168:171], v[176:179], v[116:119]
	v_mfma_f32_16x16x32_bf16 v[100:103], v[168:171], v[190:193], v[100:103]
	v_mfma_f32_16x16x32_bf16 v[100:103], v[172:175], v[194:197], v[100:103]
	v_mfma_f32_16x16x32_bf16 v[96:99], v[164:167], v[194:197], v[96:99]
	v_mfma_f32_16x16x32_bf16 v[96:99], v[160:163], v[190:193], v[96:99]
	v_mfma_f32_16x16x32_bf16 v[80:83], v[160:163], v[198:201], v[80:83]
	v_mfma_f32_16x16x32_bf16 v[80:83], v[164:167], v[202:205], v[80:83]
	v_mfma_f32_16x16x32_bf16 v[84:87], v[172:175], v[202:205], v[84:87]
	v_mfma_f32_16x16x32_bf16 v[84:87], v[168:171], v[198:201], v[84:87]
	v_mfma_f32_16x16x32_bf16 v[68:71], v[168:171], v[206:209], v[68:71]
	v_mfma_f32_16x16x32_bf16 v[68:71], v[172:175], v[210:213], v[68:71]
	v_mfma_f32_16x16x32_bf16 v[64:67], v[164:167], v[210:213], v[64:67]
	v_mfma_f32_16x16x32_bf16 v[64:67], v[160:163], v[206:209], v[64:67]
	s_setprio 0
	s_barrier
	s_add_i32 s52, s46, s37
	v_lshl_add_u64 v[214:215], s[30:31], 0, v[138:139]
	s_mov_b32 m0, s52
	ds_read_b128 v[176:179], v185 offset:16384
	ds_read_b128 v[186:189], v185 offset:17408
	ds_read_b128 v[190:193], v185 offset:18432
	ds_read_b128 v[194:197], v185 offset:19456
	ds_read_b128 v[198:201], v185 offset:20480
	ds_read_b128 v[202:205], v185 offset:21504
	ds_read_b128 v[206:209], v185 offset:22528
	ds_read_b128 v[210:213], v185 offset:23552
	global_load_lds_dwordx4 v[214:215], off
	s_add_i32 m0, s52, 0x2000
	s_add_u32 s52, s30, 0x200000
	v_lshl_add_u64 v[216:217], s[30:31], 0, v[142:143]
	s_addc_u32 s53, s31, 0
	s_add_i32 s54, s47, s37
	global_load_lds_dwordx4 v[216:217], off
	v_lshl_add_u64 v[218:219], s[52:53], 0, v[138:139]
	s_mov_b32 m0, s54
	v_lshl_add_u64 v[220:221], s[34:35], 0, v[140:141]
	global_load_lds_dwordx4 v[218:219], off
	v_lshl_add_u64 v[218:219], s[52:53], 0, v[142:143]
	s_add_i32 m0, s54, 0x2000
	s_nop 0
	global_load_lds_dwordx4 v[218:219], off
	v_lshl_add_u64 v[218:219], s[34:35], 0, v[136:137]
	s_mov_b32 m0, s27
	s_nop 0
	global_load_lds_dwordx4 v[218:219], off
	s_mov_b32 m0, s38
	s_nop 0
	global_load_lds_dwordx4 v[220:221], off
	s_waitcnt vmcnt(8)
	s_waitcnt lgkmcnt(0)
	s_barrier
; #define PG8_STAGE(bufoff, gbase, voff) do { _Pragma("unroll") for (int _i = 0; _i < 2; ++_i) \
;         __builtin_amdgcn_global_load_lds((const unsigned*)((const char*)(gbase) + (voff)[_i]), (LAS unsigned*)(lds + (bufoff) + ldsw + _i * 8192), 16, 0, 0); } while (0)
; #define PG8_LDA(dst, b, h) do { _Pragma("unroll") for (int m = 0; m < 4; ++m) _Pragma("unroll") for (int k = 0; k < 2; ++k) dst[m][k] = *(const LAS bf16x8*)(lds + PG8_SA(b, h) + aoff + m * 2048 + k * 1024); } while (0)
; #define PG8_LDB(dst, b, h) do { _Pragma("unroll") for (int n = 0; n < 2; ++n) _Pragma("unroll") for (int k = 0; k < 2; ++k) dst[n][k] = *(const LAS bf16x8*)(lds + PG8_SB(b, h) + boff + n * 2048 + k * 1024); } while (0)
; #define PG8_MMA(ai, bj, At, Bt) do { __builtin_amdgcn_s_setprio(1); _Pragma("unroll") for (int m = 0; m < 4; ++m) _Pragma("unroll") for (int n = 0; n < 2; ++n) _Pragma("unroll") for (int k = 0; k < 2; ++k) \
;         acc[ai][bj][m][n] = __builtin_amdgcn_mfma_f32_16x16x32_bf16(Bt[n][k], At[m][k], acc[ai][bj][m][n], 0, 0, 0); __builtin_amdgcn_s_setprio(0); } while (0)
; #define PG8_WAIT_V(n) asm volatile("s_waitcnt vmcnt(" #n ")" ::: "memory")
; #define PG8_WAIT_L(n) asm volatile("s_waitcnt lgkmcnt(" #n ")" ::: "memory")
; #define PG8_BAR __builtin_amdgcn_s_barrier()
; #define PG8_SCHED __builtin_amdgcn_sched_barrier(0)
; template <class Epi, bool ALIGN_EPI>
; __device__ __forceinline__ void gemm_phase(LAS unsigned char* lds, const Gemm g, const StaticOrder& S, const Epi& E) {
;     ...
;             PG8_WAIT_V(8); PG8_WAIT_L(0); PG8_BAR; PG8_MMA(1, 0, At, B0); PG8_MMA(1, 1, At, B1); PG8_BAR; PG8_SCHED;
;             PG8_LDB(B0, 1, 0); PG8_LDB(B1, 1, 1); PG8_SCHED; PG8_LDA(At, 1, 0); PG8_STAGE(PG8_SA(0, 1), a2 + hA, voffA);
;             PG8_WAIT_V(8); PG8_WAIT_L(0); PG8_BAR; PG8_MMA(0, 0, At, B0); PG8_MMA(0, 1, At, B1); PG8_BAR; PG8_SCHED;
	s_setprio 1
	s_waitcnt lgkmcnt(0)
	v_mfma_f32_16x16x32_bf16 v[56:59], v[128:131], v[176:179], v[56:59]
	v_mfma_f32_16x16x32_bf16 v[56:59], v[132:135], v[186:189], v[56:59]
	v_mfma_f32_16x16x32_bf16 v[60:63], v[156:159], v[186:189], v[60:63]
	v_mfma_f32_16x16x32_bf16 v[60:63], v[152:155], v[176:179], v[60:63]
	v_mfma_f32_16x16x32_bf16 v[44:47], v[152:155], v[190:193], v[44:47]
	v_mfma_f32_16x16x32_bf16 v[44:47], v[156:159], v[194:197], v[44:47]
	v_mfma_f32_16x16x32_bf16 v[40:43], v[132:135], v[194:197], v[40:43]
	v_mfma_f32_16x16x32_bf16 v[40:43], v[128:131], v[190:193], v[40:43]
	v_mfma_f32_16x16x32_bf16 v[24:27], v[128:131], v[198:201], v[24:27]
	v_mfma_f32_16x16x32_bf16 v[24:27], v[132:135], v[202:205], v[24:27]
	v_mfma_f32_16x16x32_bf16 v[28:31], v[156:159], v[202:205], v[28:31]
	v_mfma_f32_16x16x32_bf16 v[28:31], v[152:155], v[198:201], v[28:31]
	v_mfma_f32_16x16x32_bf16 v[12:15], v[152:155], v[206:209], v[12:15]
	v_mfma_f32_16x16x32_bf16 v[12:15], v[156:159], v[210:213], v[12:15]
	v_mfma_f32_16x16x32_bf16 v[8:11], v[132:135], v[210:213], v[8:11]
	v_mfma_f32_16x16x32_bf16 v[8:11], v[128:131], v[206:209], v[8:11]
	s_setprio 0
	s_setprio 1
	v_mfma_f32_16x16x32_bf16 v[48:51], v[160:163], v[176:179], v[48:51]
	v_mfma_f32_16x16x32_bf16 v[48:51], v[164:167], v[186:189], v[48:51]
	v_mfma_f32_16x16x32_bf16 v[52:55], v[172:175], v[186:189], v[52:55]
	v_mfma_f32_16x16x32_bf16 v[52:55], v[168:171], v[176:179], v[52:55]
	v_mfma_f32_16x16x32_bf16 v[36:39], v[168:171], v[190:193], v[36:39]
	v_mfma_f32_16x16x32_bf16 v[36:39], v[172:175], v[194:197], v[36:39]
	v_mfma_f32_16x16x32_bf16 v[32:35], v[164:167], v[194:197], v[32:35]
	v_mfma_f32_16x16x32_bf16 v[32:35], v[160:163], v[190:193], v[32:35]
	v_mfma_f32_16x16x32_bf16 v[16:19], v[160:163], v[198:201], v[16:19]
	v_mfma_f32_16x16x32_bf16 v[16:19], v[164:167], v[202:205], v[16:19]
	v_mfma_f32_16x16x32_bf16 v[20:23], v[172:175], v[202:205], v[20:23]
	v_mfma_f32_16x16x32_bf16 v[20:23], v[168:171], v[198:201], v[20:23]
	v_mfma_f32_16x16x32_bf16 v[0:3], v[168:171], v[206:209], v[0:3]
	v_mfma_f32_16x16x32_bf16 v[0:3], v[172:175], v[210:213], v[0:3]
	v_mfma_f32_16x16x32_bf16 v[4:7], v[164:167], v[210:213], v[4:7]
	v_mfma_f32_16x16x32_bf16 v[4:7], v[160:163], v[206:209], v[4:7]
	s_setprio 0
	s_barrier
	s_add_i32 s52, 0, 0x18000
	s_add_i32 s53, 0, 0x1c000
	v_add_u32_e32 v156, s52, v181
	v_add_u32_e32 v172, s53, v181
	ds_read_b128 v[128:131], v156
	ds_read_b128 v[132:135], v156 offset:1024
	ds_read_b128 v[152:155], v156 offset:2048
	ds_read_b128 v[156:159], v156 offset:3072
	ds_read_b128 v[160:163], v172
	ds_read_b128 v[164:167], v172 offset:1024
	ds_read_b128 v[168:171], v172 offset:2048
	ds_read_b128 v[172:175], v172 offset:3072
	s_add_u32 s34, s34, 0x200000
	s_addc_u32 s35, s35, 0
	s_mov_b32 m0, s39
	v_lshl_add_u64 v[222:223], s[34:35], 0, v[136:137]
	ds_read_b128 v[176:179], v185 offset:32768
	ds_read_b128 v[186:189], v185 offset:33792
	ds_read_b128 v[190:193], v185 offset:34816
	ds_read_b128 v[194:197], v185 offset:35840
	ds_read_b128 v[198:201], v185 offset:36864
	ds_read_b128 v[202:205], v185 offset:37888
	ds_read_b128 v[206:209], v185 offset:38912
	ds_read_b128 v[210:213], v185 offset:39936
	global_load_lds_dwordx4 v[222:223], off
	v_lshl_add_u64 v[222:223], s[34:35], 0, v[140:141]
	s_mov_b32 m0, s40
	s_nop 0
	global_load_lds_dwordx4 v[222:223], off
	s_waitcnt vmcnt(8)
	s_waitcnt lgkmcnt(0)
	s_barrier
	s_setprio 1
	s_waitcnt lgkmcnt(0)
	v_mfma_f32_16x16x32_bf16 v[120:123], v[128:131], v[176:179], v[120:123]
	v_mfma_f32_16x16x32_bf16 v[120:123], v[132:135], v[186:189], v[120:123]
	v_mfma_f32_16x16x32_bf16 v[124:127], v[156:159], v[186:189], v[124:127]
	v_mfma_f32_16x16x32_bf16 v[124:127], v[152:155], v[176:179], v[124:127]
	v_mfma_f32_16x16x32_bf16 v[108:111], v[152:155], v[190:193], v[108:111]
	v_mfma_f32_16x16x32_bf16 v[108:111], v[156:159], v[194:197], v[108:111]
	v_mfma_f32_16x16x32_bf16 v[104:107], v[132:135], v[194:197], v[104:107]
	v_mfma_f32_16x16x32_bf16 v[104:107], v[128:131], v[190:193], v[104:107]
	v_mfma_f32_16x16x32_bf16 v[88:91], v[128:131], v[198:201], v[88:91]
	v_mfma_f32_16x16x32_bf16 v[88:91], v[132:135], v[202:205], v[88:91]
	v_mfma_f32_16x16x32_bf16 v[92:95], v[156:159], v[202:205], v[92:95]
	v_mfma_f32_16x16x32_bf16 v[92:95], v[152:155], v[198:201], v[92:95]
	v_mfma_f32_16x16x32_bf16 v[76:79], v[152:155], v[206:209], v[76:79]
	v_mfma_f32_16x16x32_bf16 v[76:79], v[156:159], v[210:213], v[76:79]
	v_mfma_f32_16x16x32_bf16 v[72:75], v[132:135], v[210:213], v[72:75]
	v_mfma_f32_16x16x32_bf16 v[72:75], v[128:131], v[206:209], v[72:75]
	s_setprio 0
	s_setprio 1
	v_mfma_f32_16x16x32_bf16 v[112:115], v[160:163], v[176:179], v[112:115]
	v_mfma_f32_16x16x32_bf16 v[112:115], v[164:167], v[186:189], v[112:115]
	v_mfma_f32_16x16x32_bf16 v[116:119], v[172:175], v[186:189], v[116:119]
	v_mfma_f32_16x16x32_bf16 v[116:119], v[168:171], v[176:179], v[116:119]
	v_mfma_f32_16x16x32_bf16 v[100:103], v[168:171], v[190:193], v[100:103]
	v_mfma_f32_16x16x32_bf16 v[100:103], v[172:175], v[194:197], v[100:103]
	v_mfma_f32_16x16x32_bf16 v[96:99], v[164:167], v[194:197], v[96:99]
	v_mfma_f32_16x16x32_bf16 v[96:99], v[160:163], v[190:193], v[96:99]
	v_mfma_f32_16x16x32_bf16 v[80:83], v[160:163], v[198:201], v[80:83]
	v_mfma_f32_16x16x32_bf16 v[80:83], v[164:167], v[202:205], v[80:83]
	v_mfma_f32_16x16x32_bf16 v[84:87], v[172:175], v[202:205], v[84:87]
	v_mfma_f32_16x16x32_bf16 v[84:87], v[168:171], v[198:201], v[84:87]
	v_mfma_f32_16x16x32_bf16 v[68:71], v[168:171], v[206:209], v[68:71]
	v_mfma_f32_16x16x32_bf16 v[68:71], v[172:175], v[210:213], v[68:71]
	v_mfma_f32_16x16x32_bf16 v[64:67], v[164:167], v[210:213], v[64:67]
	v_mfma_f32_16x16x32_bf16 v[64:67], v[160:163], v[206:209], v[64:67]
	s_setprio 0
	s_barrier
; #define PG8_STAGE(bufoff, gbase, voff) do { _Pragma("unroll") for (int _i = 0; _i < 2; ++_i) \
;         __builtin_amdgcn_global_load_lds((const unsigned*)((const char*)(gbase) + (voff)[_i]), (LAS unsigned*)(lds + (bufoff) + ldsw + _i * 8192), 16, 0, 0); } while (0)
; #define PG8_LDA(dst, b, h) do { _Pragma("unroll") for (int m = 0; m < 4; ++m) _Pragma("unroll") for (int k = 0; k < 2; ++k) dst[m][k] = *(const LAS bf16x8*)(lds + PG8_SA(b, h) + aoff + m * 2048 + k * 1024); } while (0)
; #define PG8_MMA(ai, bj, At, Bt) do { __builtin_amdgcn_s_setprio(1); _Pragma("unroll") for (int m = 0; m < 4; ++m) _Pragma("unroll") for (int n = 0; n < 2; ++n) _Pragma("unroll") for (int k = 0; k < 2; ++k) \
;         acc[ai][bj][m][n] = __builtin_amdgcn_mfma_f32_16x16x32_bf16(Bt[n][k], At[m][k], acc[ai][bj][m][n], 0, 0, 0); __builtin_amdgcn_s_setprio(0); } while (0)
; #define PG8_WAIT_V(n) asm volatile("s_waitcnt vmcnt(" #n ")" ::: "memory")
; #define PG8_WAIT_L(n) asm volatile("s_waitcnt lgkmcnt(" #n ")" ::: "memory")
; #define PG8_BAR __builtin_amdgcn_s_barrier()
; #define PG8_SCHED __builtin_amdgcn_sched_barrier(0)
; template <class Epi, bool ALIGN_EPI>
; __device__ __forceinline__ void gemm_phase(LAS unsigned char* lds, const Gemm g, const StaticOrder& S, const Epi& E) {
;     ...
;             PG8_LDA(At, 1, 1); PG8_STAGE(PG8_SB(1, 0), b3, voffB); PG8_STAGE(PG8_SB(1, 1), b3 + hB, voffB); PG8_STAGE(PG8_SA(1, 0), a3, voffA);
;             PG8_WAIT_V(8); PG8_WAIT_L(0); PG8_BAR; PG8_MMA(1, 0, At, B0); PG8_MMA(1, 1, At, B1); PG8_BAR; PG8_SCHED;
	s_add_i32 s34, s52, s37
	v_lshl_add_u64 v[214:215], v[214:215], 0, s[12:13]
	s_mov_b32 m0, s34
	ds_read_b128 v[176:179], v185 offset:49152
	ds_read_b128 v[186:189], v185 offset:50176
	ds_read_b128 v[190:193], v185 offset:51200
	ds_read_b128 v[194:197], v185 offset:52224
	ds_read_b128 v[198:201], v185 offset:53248
	ds_read_b128 v[202:205], v185 offset:54272
	ds_read_b128 v[206:209], v185 offset:55296
	ds_read_b128 v[210:213], v185 offset:56320
	global_load_lds_dwordx4 v[214:215], off
	s_add_i32 m0, s34, 0x2000
	s_add_u32 s30, s30, 0x200080
	v_lshl_add_u64 v[214:215], v[216:217], 0, s[12:13]
	s_addc_u32 s31, s31, 0
	s_add_i32 s34, s53, s37
	global_load_lds_dwordx4 v[214:215], off
	v_lshl_add_u64 v[214:215], s[30:31], 0, v[138:139]
	s_mov_b32 m0, s34
	s_nop 0
	global_load_lds_dwordx4 v[214:215], off
	v_lshl_add_u64 v[214:215], s[30:31], 0, v[142:143]
	s_add_i32 m0, s34, 0x2000
	s_nop 0
	global_load_lds_dwordx4 v[214:215], off
	v_lshl_add_u64 v[214:215], v[218:219], 0, s[12:13]
	s_mov_b32 m0, s44
	s_nop 0
	global_load_lds_dwordx4 v[214:215], off
	v_lshl_add_u64 v[214:215], v[220:221], 0, s[12:13]
	s_mov_b32 m0, s45
	s_nop 0
	global_load_lds_dwordx4 v[214:215], off
	s_waitcnt vmcnt(8)
	s_waitcnt lgkmcnt(0)
	s_barrier
	s_setprio 1
	s_waitcnt lgkmcnt(0)
	v_mfma_f32_16x16x32_bf16 v[56:59], v[128:131], v[176:179], v[56:59]
	v_mfma_f32_16x16x32_bf16 v[56:59], v[132:135], v[186:189], v[56:59]
	v_mfma_f32_16x16x32_bf16 v[60:63], v[156:159], v[186:189], v[60:63]
	v_mfma_f32_16x16x32_bf16 v[60:63], v[152:155], v[176:179], v[60:63]
	v_mfma_f32_16x16x32_bf16 v[44:47], v[152:155], v[190:193], v[44:47]
	v_mfma_f32_16x16x32_bf16 v[44:47], v[156:159], v[194:197], v[44:47]
	v_mfma_f32_16x16x32_bf16 v[40:43], v[132:135], v[194:197], v[40:43]
	v_mfma_f32_16x16x32_bf16 v[40:43], v[128:131], v[190:193], v[40:43]
	v_mfma_f32_16x16x32_bf16 v[24:27], v[128:131], v[198:201], v[24:27]
	v_mfma_f32_16x16x32_bf16 v[24:27], v[132:135], v[202:205], v[24:27]
	v_mfma_f32_16x16x32_bf16 v[28:31], v[156:159], v[202:205], v[28:31]
	v_mfma_f32_16x16x32_bf16 v[28:31], v[152:155], v[198:201], v[28:31]
	v_mfma_f32_16x16x32_bf16 v[12:15], v[152:155], v[206:209], v[12:15]
	v_mfma_f32_16x16x32_bf16 v[12:15], v[156:159], v[210:213], v[12:15]
	v_mfma_f32_16x16x32_bf16 v[8:11], v[132:135], v[210:213], v[8:11]
	v_mfma_f32_16x16x32_bf16 v[8:11], v[128:131], v[206:209], v[8:11]
	s_setprio 0
	s_setprio 1
	v_mfma_f32_16x16x32_bf16 v[48:51], v[160:163], v[176:179], v[48:51]
	v_mfma_f32_16x16x32_bf16 v[48:51], v[164:167], v[186:189], v[48:51]
	v_mfma_f32_16x16x32_bf16 v[52:55], v[172:175], v[186:189], v[52:55]
	v_mfma_f32_16x16x32_bf16 v[52:55], v[168:171], v[176:179], v[52:55]
	v_mfma_f32_16x16x32_bf16 v[36:39], v[168:171], v[190:193], v[36:39]
	v_mfma_f32_16x16x32_bf16 v[36:39], v[172:175], v[194:197], v[36:39]
	v_mfma_f32_16x16x32_bf16 v[32:35], v[164:167], v[194:197], v[32:35]
	v_mfma_f32_16x16x32_bf16 v[32:35], v[160:163], v[190:193], v[32:35]
	v_mfma_f32_16x16x32_bf16 v[16:19], v[160:163], v[198:201], v[16:19]
	v_mfma_f32_16x16x32_bf16 v[16:19], v[164:167], v[202:205], v[16:19]
	v_mfma_f32_16x16x32_bf16 v[20:23], v[172:175], v[202:205], v[20:23]
	v_mfma_f32_16x16x32_bf16 v[20:23], v[168:171], v[198:201], v[20:23]
	v_mfma_f32_16x16x32_bf16 v[0:3], v[168:171], v[206:209], v[0:3]
	v_mfma_f32_16x16x32_bf16 v[0:3], v[172:175], v[210:213], v[0:3]
	v_mfma_f32_16x16x32_bf16 v[4:7], v[164:167], v[210:213], v[4:7]
	v_mfma_f32_16x16x32_bf16 v[4:7], v[160:163], v[206:209], v[4:7]
	s_setprio 0
	s_barrier
	s_add_i32 s51, s51, 2
	s_add_u32 s28, s28, 0x100
	s_addc_u32 s29, s29, 0
	s_add_u32 s49, s49, 0x100
	s_addc_u32 s50, s50, 0
	s_cmpk_gt_u32 s51, 0x7d
	s_cbranch_scc0 .LBB0_1755
	s_and_b64 vcc, exec, s[14:15]
	s_cbranch_vccz .LBB0_1758
	s_barrier
